# E38: E36 + one static s_setprio 1 for the leading wave half (threads 0..255) at every GEMM K-loop entry
# baseline (speedup 1.0000x reference)
.LBB0_301:
	s_load_dwordx16 s[80:95], s[78:79], 0x1e0
	s_ashr_i32 s23, s22, 31
	v_cmp_lt_i64_e64 s[36:37], s[24:25], 56
	s_lshl_b64 s[24:25], s[22:23], 19
	v_mov_b32_e32 v2, 0
	s_waitcnt lgkmcnt(0)
	s_add_u32 s24, s90, s24
	s_addc_u32 s25, s91, s25
	s_load_dwordx16 s[80:95], s[78:79], 0x140
	s_and_b64 s[26:27], s[36:37], exec
	s_cselect_b32 s23, s25, s31
	s_cselect_b32 s29, s24, s30
	s_ashr_i32 s21, s20, 31
	s_lshl_b64 s[26:27], s[20:21], 19
	s_waitcnt lgkmcnt(0)
	s_add_u32 s26, s94, s26
	s_addc_u32 s27, s95, s27
	s_and_b64 s[36:37], s[36:37], exec
	s_cselect_b32 s21, s27, s35
	s_cselect_b32 s54, s26, s34
	s_add_u32 s30, s30, 0x40080
	s_addc_u32 s31, s31, 0
	s_add_u32 s55, s34, 0x100
	s_addc_u32 s70, s35, 0
	s_mov_b32 s71, -2
	v_mov_b32_e32 v3, v2
	v_mov_b32_e32 v4, v2
	v_mov_b32_e32 v5, v2
	v_mov_b32_e32 v6, v2
	v_mov_b32_e32 v7, v2
	v_mov_b32_e32 v8, v2
	v_mov_b32_e32 v9, v2
	v_mov_b32_e32 v18, v2
	v_mov_b32_e32 v19, v2
	v_mov_b32_e32 v20, v2
	v_mov_b32_e32 v21, v2
	s_waitcnt vmcnt(0)
	v_mov_b32_e32 v22, v2
	v_mov_b32_e32 v23, v2
	v_mov_b32_e32 v24, v2
	v_mov_b32_e32 v25, v2
	v_mov_b32_e32 v34, v2
	v_mov_b32_e32 v35, v2
	v_mov_b32_e32 v36, v2
	v_mov_b32_e32 v37, v2
	v_mov_b32_e32 v38, v2
	v_mov_b32_e32 v39, v2
	v_mov_b32_e32 v40, v2
	v_mov_b32_e32 v41, v2
	v_mov_b32_e32 v50, v2
	v_mov_b32_e32 v51, v2
	v_mov_b32_e32 v52, v2
	v_mov_b32_e32 v53, v2
	v_mov_b32_e32 v54, v2
	v_mov_b32_e32 v55, v2
	v_mov_b32_e32 v56, v2
	v_mov_b32_e32 v57, v2
	v_mov_b32_e32 v10, v2
	v_mov_b32_e32 v11, v2
	v_mov_b32_e32 v12, v2
	v_mov_b32_e32 v13, v2
	v_mov_b32_e32 v14, v2
	v_mov_b32_e32 v15, v2
	v_mov_b32_e32 v16, v2
	v_mov_b32_e32 v17, v2
	v_mov_b32_e32 v26, v2
	v_mov_b32_e32 v27, v2
	v_mov_b32_e32 v28, v2
	v_mov_b32_e32 v29, v2
	v_mov_b32_e32 v30, v2
	v_mov_b32_e32 v31, v2
	v_mov_b32_e32 v32, v2
	v_mov_b32_e32 v33, v2
	v_mov_b32_e32 v42, v2
	v_mov_b32_e32 v43, v2
	v_mov_b32_e32 v44, v2
	v_mov_b32_e32 v45, v2
	v_mov_b32_e32 v46, v2
	v_mov_b32_e32 v47, v2
	v_mov_b32_e32 v48, v2
	v_mov_b32_e32 v49, v2
	v_mov_b32_e32 v58, v2
	v_mov_b32_e32 v59, v2
	v_mov_b32_e32 v60, v2
	v_mov_b32_e32 v61, v2
	v_mov_b32_e32 v62, v2
	v_mov_b32_e32 v63, v2
	v_mov_b32_e32 v64, v2
	v_mov_b32_e32 v65, v2
	v_mov_b32_e32 v66, v2
	v_mov_b32_e32 v67, v2
	v_mov_b32_e32 v68, v2
	v_mov_b32_e32 v69, v2
	v_mov_b32_e32 v70, v2
	v_mov_b32_e32 v71, v2
	v_mov_b32_e32 v72, v2
	v_mov_b32_e32 v73, v2
	v_mov_b32_e32 v82, v2
	v_mov_b32_e32 v83, v2
	v_mov_b32_e32 v84, v2
	v_mov_b32_e32 v85, v2
	v_mov_b32_e32 v86, v2
	v_mov_b32_e32 v87, v2
	v_mov_b32_e32 v88, v2
	v_mov_b32_e32 v89, v2
	v_mov_b32_e32 v98, v2
	v_mov_b32_e32 v99, v2
	v_mov_b32_e32 v100, v2
	v_mov_b32_e32 v101, v2
	v_mov_b32_e32 v102, v2
	v_mov_b32_e32 v103, v2
	v_mov_b32_e32 v104, v2
	v_mov_b32_e32 v105, v2
	v_mov_b32_e32 v114, v2
	v_mov_b32_e32 v115, v2
	v_mov_b32_e32 v116, v2
	v_mov_b32_e32 v117, v2
	v_mov_b32_e32 v118, v2
	v_mov_b32_e32 v119, v2
	v_mov_b32_e32 v120, v2
	v_mov_b32_e32 v121, v2
	v_mov_b32_e32 v74, v2
	v_mov_b32_e32 v75, v2
	v_mov_b32_e32 v76, v2
	v_mov_b32_e32 v77, v2
	v_mov_b32_e32 v78, v2
	v_mov_b32_e32 v79, v2
	v_mov_b32_e32 v80, v2
	v_mov_b32_e32 v81, v2
	v_mov_b32_e32 v90, v2
	v_mov_b32_e32 v91, v2
	v_mov_b32_e32 v92, v2
	v_mov_b32_e32 v93, v2
	v_mov_b32_e32 v94, v2
	v_mov_b32_e32 v95, v2
	v_mov_b32_e32 v96, v2
	v_mov_b32_e32 v97, v2
	v_mov_b32_e32 v106, v2
	v_mov_b32_e32 v107, v2
	v_mov_b32_e32 v108, v2
	v_mov_b32_e32 v109, v2
	v_mov_b32_e32 v110, v2
	v_mov_b32_e32 v111, v2
	v_mov_b32_e32 v112, v2
	v_mov_b32_e32 v113, v2
	v_mov_b32_e32 v122, v2
	v_mov_b32_e32 v123, v2
	v_mov_b32_e32 v124, v2
	v_mov_b32_e32 v125, v2
	v_mov_b32_e32 v126, v2
	v_mov_b32_e32 v127, v2
	v_mov_b32_e32 v128, v2
	v_mov_b32_e32 v129, v2
	v_readfirstlane_b32 s98, v248
	s_cmpk_lt_u32 s98, 0x100
	s_cbranch_scc0 .Lmy_lprio0
	s_setprio 1
.Lmy_lprio0:
.LBB0_302:
	ds_read_b128 v[150:153], v146
	ds_read_b128 v[154:157], v146 offset:1024
	ds_read_b128 v[158:161], v146 offset:2048
	ds_read_b128 v[162:165], v146 offset:3072
	s_add_u32 s34, s30, 0xfffc0080
	s_addc_u32 s35, s31, -1
	s_cmp_eq_u32 s71, 12
	s_cselect_b32 s37, s23, s35
	s_cselect_b32 s36, s29, s34
	s_cselect_b32 s35, s21, s70
	s_cselect_b32 s34, s54, s55
	v_lshl_add_u64 v[198:199], s[30:31], 0, v[138:139]
	s_add_i32 m0, s5, 0xc000
	ds_read_b128 v[166:169], v147
	ds_read_b128 v[170:173], v147 offset:1024
	ds_read_b128 v[174:177], v147 offset:2048
	ds_read_b128 v[178:181], v147 offset:3072
	ds_read_b128 v[182:185], v147 offset:4096
	ds_read_b128 v[186:189], v147 offset:5120
	ds_read_b128 v[190:193], v147 offset:6144
	ds_read_b128 v[194:197], v147 offset:7168
	global_load_lds_dwordx4 v[198:199], off
	v_lshl_add_u64 v[198:199], s[30:31], 0, v[140:141]
	s_add_i32 m0, s5, 0xe000
	s_nop 0
	global_load_lds_dwordx4 v[198:199], off
	s_waitcnt lgkmcnt(8)
	s_barrier
	s_waitcnt lgkmcnt(0)
	s_waitcnt lgkmcnt(0)
	v_mfma_f32_16x16x32_bf16 v[126:129], v[150:153], v[166:169], v[126:129]
	v_mfma_f32_16x16x32_bf16 v[122:125], v[158:161], v[166:169], v[122:125]
	v_mfma_f32_16x16x32_bf16 v[110:113], v[150:153], v[174:177], v[110:113]
	v_mfma_f32_16x16x32_bf16 v[106:109], v[158:161], v[174:177], v[106:109]
	v_mfma_f32_16x16x32_bf16 v[94:97], v[150:153], v[182:185], v[94:97]
	v_mfma_f32_16x16x32_bf16 v[90:93], v[158:161], v[182:185], v[90:93]
	v_mfma_f32_16x16x32_bf16 v[78:81], v[150:153], v[190:193], v[78:81]
	v_mfma_f32_16x16x32_bf16 v[74:77], v[158:161], v[190:193], v[74:77]
	v_mfma_f32_16x16x32_bf16 v[126:129], v[154:157], v[170:173], v[126:129]
	v_mfma_f32_16x16x32_bf16 v[122:125], v[162:165], v[170:173], v[122:125]
	v_mfma_f32_16x16x32_bf16 v[110:113], v[154:157], v[178:181], v[110:113]
	v_mfma_f32_16x16x32_bf16 v[106:109], v[162:165], v[178:181], v[106:109]
	v_mfma_f32_16x16x32_bf16 v[94:97], v[154:157], v[186:189], v[94:97]
	v_mfma_f32_16x16x32_bf16 v[90:93], v[162:165], v[186:189], v[90:93]
	v_mfma_f32_16x16x32_bf16 v[78:81], v[154:157], v[194:197], v[78:81]
	v_mfma_f32_16x16x32_bf16 v[74:77], v[162:165], v[194:197], v[74:77]
	s_barrier
	s_add_i32 s72, s49, s40
	v_lshl_add_u64 v[214:215], s[34:35], 0, v[130:131]
	s_mov_b32 m0, s72
	ds_read_b128 v[198:201], v148
	ds_read_b128 v[202:205], v148 offset:1024
	ds_read_b128 v[206:209], v148 offset:2048
	ds_read_b128 v[210:213], v148 offset:3072
	global_load_lds_dwordx4 v[214:215], off
	v_lshl_add_u64 v[216:217], s[34:35], 0, v[132:133]
	s_add_i32 m0, s72, 0x2000
	s_nop 0
	global_load_lds_dwordx4 v[216:217], off
	s_barrier
	s_waitcnt lgkmcnt(0)
	s_waitcnt lgkmcnt(0)
	v_mfma_f32_16x16x32_bf16 v[118:121], v[198:201], v[166:169], v[118:121]
	v_mfma_f32_16x16x32_bf16 v[114:117], v[206:209], v[166:169], v[114:117]
	v_mfma_f32_16x16x32_bf16 v[102:105], v[198:201], v[174:177], v[102:105]
	v_mfma_f32_16x16x32_bf16 v[98:101], v[206:209], v[174:177], v[98:101]
	v_mfma_f32_16x16x32_bf16 v[86:89], v[198:201], v[182:185], v[86:89]
	v_mfma_f32_16x16x32_bf16 v[82:85], v[206:209], v[182:185], v[82:85]
	v_mfma_f32_16x16x32_bf16 v[70:73], v[198:201], v[190:193], v[70:73]
	v_mfma_f32_16x16x32_bf16 v[66:69], v[206:209], v[190:193], v[66:69]
	v_mfma_f32_16x16x32_bf16 v[118:121], v[202:205], v[170:173], v[118:121]
	v_mfma_f32_16x16x32_bf16 v[114:117], v[210:213], v[170:173], v[114:117]
	v_mfma_f32_16x16x32_bf16 v[102:105], v[202:205], v[178:181], v[102:105]
	v_mfma_f32_16x16x32_bf16 v[98:101], v[210:213], v[178:181], v[98:101]
	v_mfma_f32_16x16x32_bf16 v[86:89], v[202:205], v[186:189], v[86:89]
	v_mfma_f32_16x16x32_bf16 v[82:85], v[210:213], v[186:189], v[82:85]
	v_mfma_f32_16x16x32_bf16 v[70:73], v[202:205], v[194:197], v[70:73]
	v_mfma_f32_16x16x32_bf16 v[66:69], v[210:213], v[194:197], v[66:69]
	s_mov_b32 m0, s5
	v_lshl_add_u64 v[218:219], s[36:37], 0, v[130:131]
	s_barrier
	ds_read_b128 v[166:169], v147 offset:16384
	ds_read_b128 v[170:173], v147 offset:17408
	ds_read_b128 v[174:177], v147 offset:18432
	ds_read_b128 v[178:181], v147 offset:19456
	ds_read_b128 v[182:185], v147 offset:20480
	ds_read_b128 v[186:189], v147 offset:21504
	ds_read_b128 v[190:193], v147 offset:22528
	ds_read_b128 v[194:197], v147 offset:23552
	global_load_lds_dwordx4 v[218:219], off
	v_lshl_add_u64 v[220:221], s[36:37], 0, v[132:133]
	s_mov_b32 m0, s41
	s_nop 0
	global_load_lds_dwordx4 v[220:221], off
	s_barrier
	s_waitcnt lgkmcnt(0)
	s_waitcnt lgkmcnt(0)
	v_mfma_f32_16x16x32_bf16 v[62:65], v[150:153], v[166:169], v[62:65]
	v_mfma_f32_16x16x32_bf16 v[58:61], v[158:161], v[166:169], v[58:61]
	v_mfma_f32_16x16x32_bf16 v[46:49], v[150:153], v[174:177], v[46:49]
	v_mfma_f32_16x16x32_bf16 v[42:45], v[158:161], v[174:177], v[42:45]
	v_mfma_f32_16x16x32_bf16 v[30:33], v[150:153], v[182:185], v[30:33]
	v_mfma_f32_16x16x32_bf16 v[26:29], v[158:161], v[182:185], v[26:29]
	v_mfma_f32_16x16x32_bf16 v[14:17], v[150:153], v[190:193], v[14:17]
	v_mfma_f32_16x16x32_bf16 v[10:13], v[158:161], v[190:193], v[10:13]
	v_mfma_f32_16x16x32_bf16 v[62:65], v[154:157], v[170:173], v[62:65]
	v_mfma_f32_16x16x32_bf16 v[58:61], v[162:165], v[170:173], v[58:61]
	v_mfma_f32_16x16x32_bf16 v[46:49], v[154:157], v[178:181], v[46:49]
	v_mfma_f32_16x16x32_bf16 v[42:45], v[162:165], v[178:181], v[42:45]
	v_mfma_f32_16x16x32_bf16 v[30:33], v[154:157], v[186:189], v[30:33]
	v_mfma_f32_16x16x32_bf16 v[26:29], v[162:165], v[186:189], v[26:29]
	v_mfma_f32_16x16x32_bf16 v[14:17], v[154:157], v[194:197], v[14:17]
	v_mfma_f32_16x16x32_bf16 v[10:13], v[162:165], v[194:197], v[10:13]
	s_barrier
	s_add_u32 s72, s34, 0x40000
	s_addc_u32 s73, s35, 0
	s_add_i32 s74, s51, s40
	v_lshl_add_u64 v[150:151], s[72:73], 0, v[130:131]
	s_mov_b32 m0, s74
	s_nop 0
	global_load_lds_dwordx4 v[150:151], off
	v_lshl_add_u64 v[150:151], s[72:73], 0, v[132:133]
	s_add_i32 m0, s74, 0x2000
	s_nop 0
	global_load_lds_dwordx4 v[150:151], off
	s_waitcnt vmcnt(6)
	s_barrier
	v_mfma_f32_16x16x32_bf16 v[54:57], v[198:201], v[166:169], v[54:57]
	v_mfma_f32_16x16x32_bf16 v[50:53], v[206:209], v[166:169], v[50:53]
	v_mfma_f32_16x16x32_bf16 v[38:41], v[198:201], v[174:177], v[38:41]
	v_mfma_f32_16x16x32_bf16 v[34:37], v[206:209], v[174:177], v[34:37]
	v_mfma_f32_16x16x32_bf16 v[22:25], v[198:201], v[182:185], v[22:25]
	v_mfma_f32_16x16x32_bf16 v[18:21], v[206:209], v[182:185], v[18:21]
	v_mfma_f32_16x16x32_bf16 v[6:9], v[198:201], v[190:193], v[6:9]
	v_mfma_f32_16x16x32_bf16 v[2:5], v[206:209], v[190:193], v[2:5]
	v_mfma_f32_16x16x32_bf16 v[54:57], v[202:205], v[170:173], v[54:57]
	v_mfma_f32_16x16x32_bf16 v[50:53], v[210:213], v[170:173], v[50:53]
	v_mfma_f32_16x16x32_bf16 v[38:41], v[202:205], v[178:181], v[38:41]
	v_mfma_f32_16x16x32_bf16 v[34:37], v[210:213], v[178:181], v[34:37]
	v_mfma_f32_16x16x32_bf16 v[22:25], v[202:205], v[186:189], v[22:25]
	v_mfma_f32_16x16x32_bf16 v[18:21], v[210:213], v[186:189], v[18:21]
	v_mfma_f32_16x16x32_bf16 v[6:9], v[202:205], v[194:197], v[6:9]
	v_mfma_f32_16x16x32_bf16 v[2:5], v[210:213], v[194:197], v[2:5]
	s_add_i32 s72, 0, 0x18000
	v_add_u32_e32 v134, s72, v137
	s_barrier
	ds_read_b128 v[150:153], v134
	ds_read_b128 v[154:157], v134 offset:1024
	ds_read_b128 v[158:161], v134 offset:2048
	ds_read_b128 v[162:165], v134 offset:3072
	s_add_u32 s36, s36, 0x40000
	s_addc_u32 s37, s37, 0
	s_mov_b32 m0, s42
	v_lshl_add_u64 v[198:199], s[36:37], 0, v[130:131]
	ds_read_b128 v[166:169], v147 offset:32768
	ds_read_b128 v[170:173], v147 offset:33792
	ds_read_b128 v[174:177], v147 offset:34816
	ds_read_b128 v[178:181], v147 offset:35840
	ds_read_b128 v[182:185], v147 offset:36864
	ds_read_b128 v[186:189], v147 offset:37888
	ds_read_b128 v[190:193], v147 offset:38912
	ds_read_b128 v[194:197], v147 offset:39936
	global_load_lds_dwordx4 v[198:199], off
	v_lshl_add_u64 v[198:199], s[36:37], 0, v[132:133]
	s_mov_b32 m0, s43
	s_nop 0
	global_load_lds_dwordx4 v[198:199], off
	s_waitcnt lgkmcnt(8)
	s_barrier
	s_waitcnt lgkmcnt(0)
	s_waitcnt lgkmcnt(0)
	v_mfma_f32_16x16x32_bf16 v[126:129], v[150:153], v[166:169], v[126:129]
	v_mfma_f32_16x16x32_bf16 v[122:125], v[158:161], v[166:169], v[122:125]
	v_mfma_f32_16x16x32_bf16 v[110:113], v[150:153], v[174:177], v[110:113]
	v_mfma_f32_16x16x32_bf16 v[106:109], v[158:161], v[174:177], v[106:109]
	v_mfma_f32_16x16x32_bf16 v[94:97], v[150:153], v[182:185], v[94:97]
	v_mfma_f32_16x16x32_bf16 v[90:93], v[158:161], v[182:185], v[90:93]
	v_mfma_f32_16x16x32_bf16 v[78:81], v[150:153], v[190:193], v[78:81]
	v_mfma_f32_16x16x32_bf16 v[74:77], v[158:161], v[190:193], v[74:77]
	v_mfma_f32_16x16x32_bf16 v[126:129], v[154:157], v[170:173], v[126:129]
	v_mfma_f32_16x16x32_bf16 v[122:125], v[162:165], v[170:173], v[122:125]
	v_mfma_f32_16x16x32_bf16 v[110:113], v[154:157], v[178:181], v[110:113]
	v_mfma_f32_16x16x32_bf16 v[106:109], v[162:165], v[178:181], v[106:109]
	v_mfma_f32_16x16x32_bf16 v[94:97], v[154:157], v[186:189], v[94:97]
	v_mfma_f32_16x16x32_bf16 v[90:93], v[162:165], v[186:189], v[90:93]
	v_mfma_f32_16x16x32_bf16 v[78:81], v[154:157], v[194:197], v[78:81]
	v_mfma_f32_16x16x32_bf16 v[74:77], v[162:165], v[194:197], v[74:77]
	s_barrier
	s_add_i32 s36, 0, 0x1c000
	s_add_i32 s37, s72, s40
	v_add_u32_e32 v134, s36, v137
	v_lshl_add_u64 v[214:215], v[214:215], 0, s[2:3]
	s_mov_b32 m0, s37
	ds_read_b128 v[198:201], v134
	ds_read_b128 v[202:205], v134 offset:1024
	ds_read_b128 v[206:209], v134 offset:2048
	ds_read_b128 v[210:213], v134 offset:3072
	global_load_lds_dwordx4 v[214:215], off
	v_lshl_add_u64 v[214:215], v[216:217], 0, s[2:3]
	s_add_i32 m0, s37, 0x2000
	s_nop 0
	global_load_lds_dwordx4 v[214:215], off
	s_barrier
	s_waitcnt lgkmcnt(0)
	s_waitcnt lgkmcnt(0)
	v_mfma_f32_16x16x32_bf16 v[118:121], v[198:201], v[166:169], v[118:121]
	v_mfma_f32_16x16x32_bf16 v[114:117], v[206:209], v[166:169], v[114:117]
	v_mfma_f32_16x16x32_bf16 v[102:105], v[198:201], v[174:177], v[102:105]
	v_mfma_f32_16x16x32_bf16 v[98:101], v[206:209], v[174:177], v[98:101]
	v_mfma_f32_16x16x32_bf16 v[86:89], v[198:201], v[182:185], v[86:89]
	v_mfma_f32_16x16x32_bf16 v[82:85], v[206:209], v[182:185], v[82:85]
	v_mfma_f32_16x16x32_bf16 v[70:73], v[198:201], v[190:193], v[70:73]
	v_mfma_f32_16x16x32_bf16 v[66:69], v[206:209], v[190:193], v[66:69]
	v_mfma_f32_16x16x32_bf16 v[118:121], v[202:205], v[170:173], v[118:121]
	v_mfma_f32_16x16x32_bf16 v[114:117], v[210:213], v[170:173], v[114:117]
	v_mfma_f32_16x16x32_bf16 v[102:105], v[202:205], v[178:181], v[102:105]
	v_mfma_f32_16x16x32_bf16 v[98:101], v[210:213], v[178:181], v[98:101]
	v_mfma_f32_16x16x32_bf16 v[86:89], v[202:205], v[186:189], v[86:89]
	v_mfma_f32_16x16x32_bf16 v[82:85], v[210:213], v[186:189], v[82:85]
	v_mfma_f32_16x16x32_bf16 v[70:73], v[202:205], v[194:197], v[70:73]
	v_mfma_f32_16x16x32_bf16 v[66:69], v[210:213], v[194:197], v[66:69]
	s_mov_b32 m0, s45
	v_lshl_add_u64 v[214:215], v[218:219], 0, s[2:3]
	s_barrier
	ds_read_b128 v[166:169], v147 offset:49152
	ds_read_b128 v[170:173], v147 offset:50176
	ds_read_b128 v[174:177], v147 offset:51200
	ds_read_b128 v[178:181], v147 offset:52224
	ds_read_b128 v[182:185], v147 offset:53248
	ds_read_b128 v[186:189], v147 offset:54272
	ds_read_b128 v[190:193], v147 offset:55296
	ds_read_b128 v[194:197], v147 offset:56320
	global_load_lds_dwordx4 v[214:215], off
	v_lshl_add_u64 v[214:215], v[220:221], 0, s[2:3]
	s_mov_b32 m0, s46
	s_nop 0
	global_load_lds_dwordx4 v[214:215], off
	s_barrier
	s_waitcnt lgkmcnt(0)
	s_waitcnt lgkmcnt(0)
	v_mfma_f32_16x16x32_bf16 v[62:65], v[150:153], v[166:169], v[62:65]
	v_mfma_f32_16x16x32_bf16 v[58:61], v[158:161], v[166:169], v[58:61]
	v_mfma_f32_16x16x32_bf16 v[46:49], v[150:153], v[174:177], v[46:49]
	v_mfma_f32_16x16x32_bf16 v[42:45], v[158:161], v[174:177], v[42:45]
	v_mfma_f32_16x16x32_bf16 v[30:33], v[150:153], v[182:185], v[30:33]
	v_mfma_f32_16x16x32_bf16 v[26:29], v[158:161], v[182:185], v[26:29]
	v_mfma_f32_16x16x32_bf16 v[14:17], v[150:153], v[190:193], v[14:17]
	v_mfma_f32_16x16x32_bf16 v[10:13], v[158:161], v[190:193], v[10:13]
	v_mfma_f32_16x16x32_bf16 v[62:65], v[154:157], v[170:173], v[62:65]
	v_mfma_f32_16x16x32_bf16 v[58:61], v[162:165], v[170:173], v[58:61]
	v_mfma_f32_16x16x32_bf16 v[46:49], v[154:157], v[178:181], v[46:49]
	v_mfma_f32_16x16x32_bf16 v[42:45], v[162:165], v[178:181], v[42:45]
	v_mfma_f32_16x16x32_bf16 v[30:33], v[154:157], v[186:189], v[30:33]
	v_mfma_f32_16x16x32_bf16 v[26:29], v[162:165], v[186:189], v[26:29]
	v_mfma_f32_16x16x32_bf16 v[14:17], v[154:157], v[194:197], v[14:17]
	v_mfma_f32_16x16x32_bf16 v[10:13], v[162:165], v[194:197], v[10:13]
	s_barrier
	s_add_u32 s34, s34, 0x40080
	s_addc_u32 s35, s35, 0
	s_add_i32 s36, s36, s40
	v_lshl_add_u64 v[150:151], s[34:35], 0, v[130:131]
	s_mov_b32 m0, s36
	s_nop 0
	global_load_lds_dwordx4 v[150:151], off
	v_lshl_add_u64 v[150:151], s[34:35], 0, v[132:133]
	s_add_i32 m0, s36, 0x2000
	s_nop 0
	global_load_lds_dwordx4 v[150:151], off
	s_waitcnt vmcnt(6)
	s_barrier
	v_mfma_f32_16x16x32_bf16 v[54:57], v[198:201], v[166:169], v[54:57]
	v_mfma_f32_16x16x32_bf16 v[50:53], v[206:209], v[166:169], v[50:53]
	v_mfma_f32_16x16x32_bf16 v[38:41], v[198:201], v[174:177], v[38:41]
	v_mfma_f32_16x16x32_bf16 v[34:37], v[206:209], v[174:177], v[34:37]
	v_mfma_f32_16x16x32_bf16 v[22:25], v[198:201], v[182:185], v[22:25]
	v_mfma_f32_16x16x32_bf16 v[18:21], v[206:209], v[182:185], v[18:21]
	v_mfma_f32_16x16x32_bf16 v[6:9], v[198:201], v[190:193], v[6:9]
	v_mfma_f32_16x16x32_bf16 v[2:5], v[206:209], v[190:193], v[2:5]
	v_mfma_f32_16x16x32_bf16 v[54:57], v[202:205], v[170:173], v[54:57]
	v_mfma_f32_16x16x32_bf16 v[50:53], v[210:213], v[170:173], v[50:53]
	v_mfma_f32_16x16x32_bf16 v[38:41], v[202:205], v[178:181], v[38:41]
	v_mfma_f32_16x16x32_bf16 v[34:37], v[210:213], v[178:181], v[34:37]
	v_mfma_f32_16x16x32_bf16 v[22:25], v[202:205], v[186:189], v[22:25]
	v_mfma_f32_16x16x32_bf16 v[18:21], v[210:213], v[186:189], v[18:21]
	v_mfma_f32_16x16x32_bf16 v[6:9], v[202:205], v[194:197], v[6:9]
	v_mfma_f32_16x16x32_bf16 v[2:5], v[210:213], v[194:197], v[2:5]
	s_add_i32 s71, s71, 2
	s_add_u32 s30, s30, 0x100
	s_addc_u32 s31, s31, 0
	s_add_u32 s55, s55, 0x100
	s_addc_u32 s70, s70, 0
	s_cmp_gt_u32 s71, 13
	s_barrier
	s_cbranch_scc0 .LBB0_302
	s_lshl_b32 s21, s28, 8
	v_add_u32_e32 v149, s21, v1
	v_cmp_gt_i32_e32 vcc, s52, v149
	s_and_saveexec_b64 s[28:29], vcc
	s_cbranch_execz .LBB0_305
	s_load_dwordx16 s[56:71], s[78:79], 0x80
	s_lshl_b32 s23, s4, 8
	v_or_b32_e32 v134, s23, v136
	v_ashrrev_i32_e32 v157, 31, v134
	v_mov_b32_e32 v156, v134
	s_waitcnt lgkmcnt(0)
	v_lshl_add_u64 v[154:155], v[134:135], 2, s[66:67]
	s_load_dwordx16 s[56:71], s[78:79], 0x40
	v_lshl_add_u64 v[150:151], v[154:155], 0, s[6:7]
	v_cmp_gt_i32_e32 vcc, s53, v134
	s_load_dwordx2 s[30:31], s[78:79], 0x1d0
	v_or_b32_e32 v162, 16, v134
	s_waitcnt lgkmcnt(0)
	v_lshl_add_u64 v[158:159], v[156:157], 2, s[60:61]
	v_cndmask_b32_e32 v151, v151, v159, vcc
	v_cndmask_b32_e32 v150, v150, v158, vcc
	global_load_dwordx4 v[150:153], v[150:151], off
	v_mov_b64_e32 v[160:161], s[30:31]
	v_mad_i64_i32 v[160:161], s[30:31], v149, s50, v[160:161]
	v_cndmask_b32_e32 v157, 0, v157, vcc
	v_lshl_add_u64 v[164:165], v[154:155], 0, s[8:9]
	v_lshl_add_u64 v[158:159], v[158:159], 0, 64
	v_lshl_add_u64 v[156:157], v[156:157], 2, v[160:161]
	v_cmp_gt_i32_e32 vcc, s53, v162
	s_waitcnt vmcnt(0)
	v_pk_add_f32 v[128:129], v[128:129], v[152:153]
	v_pk_add_f32 v[126:127], v[126:127], v[150:151]
	v_cndmask_b32_e32 v159, v165, v159, vcc
	v_cndmask_b32_e32 v158, v164, v158, vcc
	global_store_dwordx4 v[156:157], v[126:129], off
	global_load_dwordx4 v[126:129], v[158:159], off
	v_or_b32_e32 v150, s23, v142
	s_ashr_i32 s23, s23, 31
	v_mov_b32_e32 v153, s23
	v_mov_b32_e32 v152, v134
	v_ashrrev_i32_e32 v134, 31, v162
	v_lshl_add_u64 v[152:153], v[152:153], 2, s[60:61]
	v_lshl_add_u64 v[156:157], v[154:155], 0, s[10:11]
	v_lshl_add_u64 v[158:159], v[152:153], 0, s[12:13]
	v_cndmask_b32_e32 v163, 0, v134, vcc
	v_cmp_gt_i32_e32 vcc, s53, v150
	v_lshl_add_u64 v[152:153], v[152:153], 0, s[16:17]
	s_waitcnt vmcnt(0)
	v_pk_add_f32 v[124:125], v[124:125], v[128:129]
	v_cndmask_b32_e32 v157, v157, v159, vcc
	v_cndmask_b32_e32 v156, v156, v158, vcc
	v_lshl_add_u64 v[158:159], v[162:163], 2, v[160:161]
	v_pk_add_f32 v[122:123], v[122:123], v[126:127]
	global_store_dwordx4 v[158:159], v[122:125], off
	global_load_dwordx4 v[122:125], v[156:157], off
	v_ashrrev_i32_e32 v127, 31, v150
	v_or_b32_e32 v126, 16, v150
	v_cndmask_b32_e32 v151, 0, v127, vcc
	v_lshl_add_u64 v[128:129], v[154:155], 0, s[14:15]
	v_cmp_gt_i32_e32 vcc, s53, v126
	v_lshl_add_u64 v[150:151], v[150:151], 2, v[160:161]
	s_waitcnt vmcnt(0)
	v_pk_add_f32 v[120:121], v[120:121], v[124:125]
	v_pk_add_f32 v[118:119], v[118:119], v[122:123]
	v_cndmask_b32_e32 v129, v129, v153, vcc
	v_cndmask_b32_e32 v128, v128, v152, vcc
	global_store_dwordx4 v[150:151], v[118:121], off
	global_load_dwordx4 v[118:121], v[128:129], off
	v_ashrrev_i32_e32 v122, 31, v126
	v_cndmask_b32_e32 v127, 0, v122, vcc
	s_waitcnt vmcnt(0)
	v_pk_add_f32 v[116:117], v[116:117], v[120:121]
	v_pk_add_f32 v[114:115], v[114:115], v[118:119]
	v_lshl_add_u64 v[118:119], v[126:127], 2, v[160:161]
	global_store_dwordx4 v[118:119], v[114:117], off

.LBB0_473:
	s_load_dwordx16 s[80:95], s[78:79], 0x1e0
	s_ashr_i32 s17, s16, 31
	v_cmp_lt_i64_e32 vcc, s[18:19], v[140:141]
	s_lshl_b64 s[18:19], s[16:17], 19
	s_load_dwordx16 s[52:67], s[78:79], 0x180
	s_waitcnt lgkmcnt(0)
	s_add_u32 s18, s92, s18
	s_addc_u32 s19, s93, s19
	s_and_b64 s[20:21], vcc, exec
	s_cselect_b32 s7, s19, s23
	s_cselect_b32 s17, s18, s22
	s_ashr_i32 s9, s8, 31
	s_lshl_b64 s[20:21], s[8:9], 19
	s_add_u32 s20, s52, s20
	s_addc_u32 s21, s53, s21
	s_and_b64 s[26:27], vcc, exec
	s_cselect_b32 s9, s21, s25
	s_cselect_b32 s28, s20, s24
	s_add_u32 s22, s22, 0x40080
	s_addc_u32 s23, s23, 0
	s_add_u32 s29, s24, 0x100
	v_mov_b32_e32 v2, 0
	s_addc_u32 s50, s25, 0
	s_mov_b32 s51, -2
	v_mov_b32_e32 v3, v2
	v_mov_b32_e32 v4, v2
	v_mov_b32_e32 v5, v2
	v_mov_b32_e32 v6, v2
	v_mov_b32_e32 v7, v2
	v_mov_b32_e32 v8, v2
	v_mov_b32_e32 v9, v2
	v_mov_b32_e32 v18, v2
	v_mov_b32_e32 v19, v2
	v_mov_b32_e32 v20, v2
	v_mov_b32_e32 v21, v2
	v_mov_b32_e32 v22, v2
	v_mov_b32_e32 v23, v2
	v_mov_b32_e32 v24, v2
	v_mov_b32_e32 v25, v2
	v_mov_b32_e32 v34, v2
	v_mov_b32_e32 v35, v2
	v_mov_b32_e32 v36, v2
	v_mov_b32_e32 v37, v2
	v_mov_b32_e32 v38, v2
	v_mov_b32_e32 v39, v2
	v_mov_b32_e32 v40, v2
	v_mov_b32_e32 v41, v2
	v_mov_b32_e32 v50, v2
	v_mov_b32_e32 v51, v2
	v_mov_b32_e32 v52, v2
	v_mov_b32_e32 v53, v2
	v_mov_b32_e32 v54, v2
	v_mov_b32_e32 v55, v2
	v_mov_b32_e32 v56, v2
	v_mov_b32_e32 v57, v2
	v_mov_b32_e32 v10, v2
	v_mov_b32_e32 v11, v2
	v_mov_b32_e32 v12, v2
	v_mov_b32_e32 v13, v2
	v_mov_b32_e32 v14, v2
	v_mov_b32_e32 v15, v2
	v_mov_b32_e32 v16, v2
	v_mov_b32_e32 v17, v2
	v_mov_b32_e32 v26, v2
	v_mov_b32_e32 v27, v2
	v_mov_b32_e32 v28, v2
	v_mov_b32_e32 v29, v2
	v_mov_b32_e32 v30, v2
	v_mov_b32_e32 v31, v2
	v_mov_b32_e32 v32, v2
	v_mov_b32_e32 v33, v2
	v_mov_b32_e32 v42, v2
	v_mov_b32_e32 v43, v2
	v_mov_b32_e32 v44, v2
	v_mov_b32_e32 v45, v2
	v_mov_b32_e32 v46, v2
	v_mov_b32_e32 v47, v2
	v_mov_b32_e32 v48, v2
	v_mov_b32_e32 v49, v2
	v_mov_b32_e32 v58, v2
	v_mov_b32_e32 v59, v2
	v_mov_b32_e32 v60, v2
	v_mov_b32_e32 v61, v2
	v_mov_b32_e32 v62, v2
	v_mov_b32_e32 v63, v2
	v_mov_b32_e32 v64, v2
	v_mov_b32_e32 v65, v2
	v_mov_b32_e32 v66, v2
	v_mov_b32_e32 v67, v2
	v_mov_b32_e32 v68, v2
	v_mov_b32_e32 v69, v2
	v_mov_b32_e32 v70, v2
	v_mov_b32_e32 v71, v2
	v_mov_b32_e32 v72, v2
	v_mov_b32_e32 v73, v2
	v_mov_b32_e32 v82, v2
	v_mov_b32_e32 v83, v2
	v_mov_b32_e32 v84, v2
	v_mov_b32_e32 v85, v2
	v_mov_b32_e32 v86, v2
	v_mov_b32_e32 v87, v2
	v_mov_b32_e32 v88, v2
	v_mov_b32_e32 v89, v2
	v_mov_b32_e32 v98, v2
	v_mov_b32_e32 v99, v2
	v_mov_b32_e32 v100, v2
	v_mov_b32_e32 v101, v2
	v_mov_b32_e32 v102, v2
	v_mov_b32_e32 v103, v2
	v_mov_b32_e32 v104, v2
	v_mov_b32_e32 v105, v2
	v_mov_b32_e32 v114, v2
	v_mov_b32_e32 v115, v2
	v_mov_b32_e32 v116, v2
	v_mov_b32_e32 v117, v2
	v_mov_b32_e32 v118, v2
	v_mov_b32_e32 v119, v2
	v_mov_b32_e32 v120, v2
	v_mov_b32_e32 v121, v2
	v_mov_b32_e32 v74, v2
	v_mov_b32_e32 v75, v2
	v_mov_b32_e32 v76, v2
	v_mov_b32_e32 v77, v2
	v_mov_b32_e32 v78, v2
	v_mov_b32_e32 v79, v2
	v_mov_b32_e32 v80, v2
	v_mov_b32_e32 v81, v2
	v_mov_b32_e32 v90, v2
	v_mov_b32_e32 v91, v2
	v_mov_b32_e32 v92, v2
	v_mov_b32_e32 v93, v2
	v_mov_b32_e32 v94, v2
	v_mov_b32_e32 v95, v2
	v_mov_b32_e32 v96, v2
	v_mov_b32_e32 v97, v2
	v_mov_b32_e32 v106, v2
	v_mov_b32_e32 v107, v2
	v_mov_b32_e32 v108, v2
	v_mov_b32_e32 v109, v2
	v_mov_b32_e32 v110, v2
	v_mov_b32_e32 v111, v2
	v_mov_b32_e32 v112, v2
	v_mov_b32_e32 v113, v2
	v_mov_b32_e32 v122, v2
	v_mov_b32_e32 v123, v2
	v_mov_b32_e32 v124, v2
	v_mov_b32_e32 v125, v2
	v_mov_b32_e32 v126, v2
	v_mov_b32_e32 v127, v2
	v_mov_b32_e32 v128, v2
	v_mov_b32_e32 v129, v2
	v_readfirstlane_b32 s98, v248
	s_cmpk_lt_u32 s98, 0x100
	s_cbranch_scc0 .Lmy_lprio1
	s_setprio 1
.Lmy_lprio1:
.LBB0_474:
	ds_read_b128 v[144:147], v167
	ds_read_b128 v[148:151], v167 offset:1024
	ds_read_b128 v[152:155], v167 offset:2048
	ds_read_b128 v[156:159], v167 offset:3072
	s_add_u32 s24, s22, 0xfffc0080
	s_addc_u32 s25, s23, -1
	s_cmp_eq_u32 s51, 12
	s_cselect_b32 s27, s7, s25
	s_cselect_b32 s26, s17, s24
	s_cselect_b32 s25, s9, s50
	s_cselect_b32 s24, s28, s29
	v_lshl_add_u64 v[160:161], s[22:23], 0, v[136:137]
	s_add_i32 m0, s1, 0xc000
	ds_read_b128 v[172:175], v168
	ds_read_b128 v[176:179], v168 offset:1024
	ds_read_b128 v[180:183], v168 offset:2048
	ds_read_b128 v[184:187], v168 offset:3072
	ds_read_b128 v[188:191], v168 offset:4096
	ds_read_b128 v[192:195], v168 offset:5120
	ds_read_b128 v[196:199], v168 offset:6144
	ds_read_b128 v[200:203], v168 offset:7168
	global_load_lds_dwordx4 v[160:161], off
	v_lshl_add_u64 v[160:161], s[22:23], 0, v[138:139]
	s_add_i32 m0, s1, 0xe000
	s_nop 0
	global_load_lds_dwordx4 v[160:161], off
	s_waitcnt lgkmcnt(8)
	s_barrier
	s_waitcnt lgkmcnt(0)
	s_waitcnt lgkmcnt(0)
	v_mfma_f32_16x16x32_bf16 v[126:129], v[144:147], v[172:175], v[126:129]
	v_mfma_f32_16x16x32_bf16 v[122:125], v[152:155], v[172:175], v[122:125]
	v_mfma_f32_16x16x32_bf16 v[110:113], v[144:147], v[180:183], v[110:113]
	v_mfma_f32_16x16x32_bf16 v[106:109], v[152:155], v[180:183], v[106:109]
	v_mfma_f32_16x16x32_bf16 v[94:97], v[144:147], v[188:191], v[94:97]
	v_mfma_f32_16x16x32_bf16 v[90:93], v[152:155], v[188:191], v[90:93]
	v_mfma_f32_16x16x32_bf16 v[78:81], v[144:147], v[196:199], v[78:81]
	v_mfma_f32_16x16x32_bf16 v[74:77], v[152:155], v[196:199], v[74:77]
	v_mfma_f32_16x16x32_bf16 v[126:129], v[148:151], v[176:179], v[126:129]
	v_mfma_f32_16x16x32_bf16 v[122:125], v[156:159], v[176:179], v[122:125]
	v_mfma_f32_16x16x32_bf16 v[110:113], v[148:151], v[184:187], v[110:113]
	v_mfma_f32_16x16x32_bf16 v[106:109], v[156:159], v[184:187], v[106:109]
	v_mfma_f32_16x16x32_bf16 v[94:97], v[148:151], v[192:195], v[94:97]
	v_mfma_f32_16x16x32_bf16 v[90:93], v[156:159], v[192:195], v[90:93]
	v_mfma_f32_16x16x32_bf16 v[78:81], v[148:151], v[200:203], v[78:81]
	v_mfma_f32_16x16x32_bf16 v[74:77], v[156:159], v[200:203], v[74:77]
	s_barrier
	s_add_i32 s52, s45, s34
	v_lshl_add_u64 v[160:161], s[24:25], 0, v[130:131]
	s_mov_b32 m0, s52
	ds_read_b128 v[204:207], v169
	ds_read_b128 v[208:211], v169 offset:1024
	ds_read_b128 v[212:215], v169 offset:2048
	ds_read_b128 v[216:219], v169 offset:3072
	global_load_lds_dwordx4 v[160:161], off
	v_lshl_add_u64 v[220:221], s[24:25], 0, v[132:133]
	s_add_i32 m0, s52, 0x2000
	s_nop 0
	global_load_lds_dwordx4 v[220:221], off
	s_barrier
	s_waitcnt lgkmcnt(0)
	s_waitcnt lgkmcnt(0)
	v_mfma_f32_16x16x32_bf16 v[118:121], v[204:207], v[172:175], v[118:121]
	v_mfma_f32_16x16x32_bf16 v[114:117], v[212:215], v[172:175], v[114:117]
	v_mfma_f32_16x16x32_bf16 v[102:105], v[204:207], v[180:183], v[102:105]
	v_mfma_f32_16x16x32_bf16 v[98:101], v[212:215], v[180:183], v[98:101]
	v_mfma_f32_16x16x32_bf16 v[86:89], v[204:207], v[188:191], v[86:89]
	v_mfma_f32_16x16x32_bf16 v[82:85], v[212:215], v[188:191], v[82:85]
	v_mfma_f32_16x16x32_bf16 v[70:73], v[204:207], v[196:199], v[70:73]
	v_mfma_f32_16x16x32_bf16 v[66:69], v[212:215], v[196:199], v[66:69]
	v_mfma_f32_16x16x32_bf16 v[118:121], v[208:211], v[176:179], v[118:121]
	v_mfma_f32_16x16x32_bf16 v[114:117], v[216:219], v[176:179], v[114:117]
	v_mfma_f32_16x16x32_bf16 v[102:105], v[208:211], v[184:187], v[102:105]
	v_mfma_f32_16x16x32_bf16 v[98:101], v[216:219], v[184:187], v[98:101]
	v_mfma_f32_16x16x32_bf16 v[86:89], v[208:211], v[192:195], v[86:89]
	v_mfma_f32_16x16x32_bf16 v[82:85], v[216:219], v[192:195], v[82:85]
	v_mfma_f32_16x16x32_bf16 v[70:73], v[208:211], v[200:203], v[70:73]
	v_mfma_f32_16x16x32_bf16 v[66:69], v[216:219], v[200:203], v[66:69]
	s_mov_b32 m0, s1
	v_lshl_add_u64 v[222:223], s[26:27], 0, v[130:131]
	s_barrier
	ds_read_b128 v[172:175], v168 offset:16384
	ds_read_b128 v[176:179], v168 offset:17408
	ds_read_b128 v[180:183], v168 offset:18432
	ds_read_b128 v[184:187], v168 offset:19456
	ds_read_b128 v[188:191], v168 offset:20480
	ds_read_b128 v[192:195], v168 offset:21504
	ds_read_b128 v[196:199], v168 offset:22528
	ds_read_b128 v[200:203], v168 offset:23552
	global_load_lds_dwordx4 v[222:223], off
	v_lshl_add_u64 v[224:225], s[26:27], 0, v[132:133]
	s_mov_b32 m0, s35
	s_nop 0
	global_load_lds_dwordx4 v[224:225], off
	s_barrier
	s_waitcnt lgkmcnt(0)
	s_waitcnt lgkmcnt(0)
	v_mfma_f32_16x16x32_bf16 v[62:65], v[144:147], v[172:175], v[62:65]
	v_mfma_f32_16x16x32_bf16 v[58:61], v[152:155], v[172:175], v[58:61]
	v_mfma_f32_16x16x32_bf16 v[46:49], v[144:147], v[180:183], v[46:49]
	v_mfma_f32_16x16x32_bf16 v[42:45], v[152:155], v[180:183], v[42:45]
	v_mfma_f32_16x16x32_bf16 v[30:33], v[144:147], v[188:191], v[30:33]
	v_mfma_f32_16x16x32_bf16 v[26:29], v[152:155], v[188:191], v[26:29]
	v_mfma_f32_16x16x32_bf16 v[14:17], v[144:147], v[196:199], v[14:17]
	v_mfma_f32_16x16x32_bf16 v[10:13], v[152:155], v[196:199], v[10:13]
	v_mfma_f32_16x16x32_bf16 v[62:65], v[148:151], v[176:179], v[62:65]
	v_mfma_f32_16x16x32_bf16 v[58:61], v[156:159], v[176:179], v[58:61]
	v_mfma_f32_16x16x32_bf16 v[46:49], v[148:151], v[184:187], v[46:49]
	v_mfma_f32_16x16x32_bf16 v[42:45], v[156:159], v[184:187], v[42:45]
	v_mfma_f32_16x16x32_bf16 v[30:33], v[148:151], v[192:195], v[30:33]
	v_mfma_f32_16x16x32_bf16 v[26:29], v[156:159], v[192:195], v[26:29]
	v_mfma_f32_16x16x32_bf16 v[14:17], v[148:151], v[200:203], v[14:17]
	v_mfma_f32_16x16x32_bf16 v[10:13], v[156:159], v[200:203], v[10:13]
	s_barrier
	s_add_u32 s52, s24, 0x40000
	s_addc_u32 s53, s25, 0
	s_add_i32 s54, s46, s34
	v_lshl_add_u64 v[144:145], s[52:53], 0, v[130:131]
	s_mov_b32 m0, s54
	s_nop 0
	global_load_lds_dwordx4 v[144:145], off
	v_lshl_add_u64 v[144:145], s[52:53], 0, v[132:133]
	s_add_i32 m0, s54, 0x2000
	s_nop 0
	global_load_lds_dwordx4 v[144:145], off
	s_waitcnt vmcnt(6)
	s_barrier
	v_mfma_f32_16x16x32_bf16 v[54:57], v[204:207], v[172:175], v[54:57]
	v_mfma_f32_16x16x32_bf16 v[50:53], v[212:215], v[172:175], v[50:53]
	v_mfma_f32_16x16x32_bf16 v[38:41], v[204:207], v[180:183], v[38:41]
	v_mfma_f32_16x16x32_bf16 v[34:37], v[212:215], v[180:183], v[34:37]
	v_mfma_f32_16x16x32_bf16 v[22:25], v[204:207], v[188:191], v[22:25]
	v_mfma_f32_16x16x32_bf16 v[18:21], v[212:215], v[188:191], v[18:21]
	v_mfma_f32_16x16x32_bf16 v[6:9], v[204:207], v[196:199], v[6:9]
	v_mfma_f32_16x16x32_bf16 v[2:5], v[212:215], v[196:199], v[2:5]
	v_mfma_f32_16x16x32_bf16 v[54:57], v[208:211], v[176:179], v[54:57]
	v_mfma_f32_16x16x32_bf16 v[50:53], v[216:219], v[176:179], v[50:53]
	v_mfma_f32_16x16x32_bf16 v[38:41], v[208:211], v[184:187], v[38:41]
	v_mfma_f32_16x16x32_bf16 v[34:37], v[216:219], v[184:187], v[34:37]
	v_mfma_f32_16x16x32_bf16 v[22:25], v[208:211], v[192:195], v[22:25]
	v_mfma_f32_16x16x32_bf16 v[18:21], v[216:219], v[192:195], v[18:21]
	v_mfma_f32_16x16x32_bf16 v[6:9], v[208:211], v[200:203], v[6:9]
	v_mfma_f32_16x16x32_bf16 v[2:5], v[216:219], v[200:203], v[2:5]
	s_add_i32 s52, 0, 0x18000
	v_add_u32_e32 v134, s52, v164
	s_barrier
	ds_read_b128 v[144:147], v134
	ds_read_b128 v[148:151], v134 offset:1024
	ds_read_b128 v[152:155], v134 offset:2048
	ds_read_b128 v[156:159], v134 offset:3072
	s_add_u32 s26, s26, 0x40000
	s_addc_u32 s27, s27, 0
	s_mov_b32 m0, s36
	v_lshl_add_u64 v[204:205], s[26:27], 0, v[130:131]
	ds_read_b128 v[172:175], v168 offset:32768
	ds_read_b128 v[176:179], v168 offset:33792
	ds_read_b128 v[180:183], v168 offset:34816
	ds_read_b128 v[184:187], v168 offset:35840
	ds_read_b128 v[188:191], v168 offset:36864
	ds_read_b128 v[192:195], v168 offset:37888
	ds_read_b128 v[196:199], v168 offset:38912
	ds_read_b128 v[200:203], v168 offset:39936
	global_load_lds_dwordx4 v[204:205], off
	v_lshl_add_u64 v[204:205], s[26:27], 0, v[132:133]
	s_mov_b32 m0, s37
	s_nop 0
	global_load_lds_dwordx4 v[204:205], off
	s_waitcnt lgkmcnt(8)
	s_barrier
	s_waitcnt lgkmcnt(0)
	s_waitcnt lgkmcnt(0)
	v_mfma_f32_16x16x32_bf16 v[126:129], v[144:147], v[172:175], v[126:129]
	v_mfma_f32_16x16x32_bf16 v[122:125], v[152:155], v[172:175], v[122:125]
	v_mfma_f32_16x16x32_bf16 v[110:113], v[144:147], v[180:183], v[110:113]
	v_mfma_f32_16x16x32_bf16 v[106:109], v[152:155], v[180:183], v[106:109]
	v_mfma_f32_16x16x32_bf16 v[94:97], v[144:147], v[188:191], v[94:97]
	v_mfma_f32_16x16x32_bf16 v[90:93], v[152:155], v[188:191], v[90:93]
	v_mfma_f32_16x16x32_bf16 v[78:81], v[144:147], v[196:199], v[78:81]
	v_mfma_f32_16x16x32_bf16 v[74:77], v[152:155], v[196:199], v[74:77]
	v_mfma_f32_16x16x32_bf16 v[126:129], v[148:151], v[176:179], v[126:129]
	v_mfma_f32_16x16x32_bf16 v[122:125], v[156:159], v[176:179], v[122:125]
	v_mfma_f32_16x16x32_bf16 v[110:113], v[148:151], v[184:187], v[110:113]
	v_mfma_f32_16x16x32_bf16 v[106:109], v[156:159], v[184:187], v[106:109]
	v_mfma_f32_16x16x32_bf16 v[94:97], v[148:151], v[192:195], v[94:97]
	v_mfma_f32_16x16x32_bf16 v[90:93], v[156:159], v[192:195], v[90:93]
	v_mfma_f32_16x16x32_bf16 v[78:81], v[148:151], v[200:203], v[78:81]
	v_mfma_f32_16x16x32_bf16 v[74:77], v[156:159], v[200:203], v[74:77]
	s_barrier
	s_add_i32 s26, 0, 0x1c000
	s_add_i32 s27, s52, s34
	v_add_u32_e32 v134, s26, v164
	v_lshl_add_u64 v[160:161], v[160:161], 0, s[2:3]
	s_mov_b32 m0, s27
	ds_read_b128 v[204:207], v134
	ds_read_b128 v[208:211], v134 offset:1024
	ds_read_b128 v[212:215], v134 offset:2048
	ds_read_b128 v[216:219], v134 offset:3072
	global_load_lds_dwordx4 v[160:161], off
	v_lshl_add_u64 v[160:161], v[220:221], 0, s[2:3]
	s_add_i32 m0, s27, 0x2000
	s_nop 0
	global_load_lds_dwordx4 v[160:161], off
	s_barrier
	s_waitcnt lgkmcnt(0)
	s_waitcnt lgkmcnt(0)
	v_mfma_f32_16x16x32_bf16 v[118:121], v[204:207], v[172:175], v[118:121]
	v_mfma_f32_16x16x32_bf16 v[114:117], v[212:215], v[172:175], v[114:117]
	v_mfma_f32_16x16x32_bf16 v[102:105], v[204:207], v[180:183], v[102:105]
	v_mfma_f32_16x16x32_bf16 v[98:101], v[212:215], v[180:183], v[98:101]
	v_mfma_f32_16x16x32_bf16 v[86:89], v[204:207], v[188:191], v[86:89]
	v_mfma_f32_16x16x32_bf16 v[82:85], v[212:215], v[188:191], v[82:85]
	v_mfma_f32_16x16x32_bf16 v[70:73], v[204:207], v[196:199], v[70:73]
	v_mfma_f32_16x16x32_bf16 v[66:69], v[212:215], v[196:199], v[66:69]
	v_mfma_f32_16x16x32_bf16 v[118:121], v[208:211], v[176:179], v[118:121]
	v_mfma_f32_16x16x32_bf16 v[114:117], v[216:219], v[176:179], v[114:117]
	v_mfma_f32_16x16x32_bf16 v[102:105], v[208:211], v[184:187], v[102:105]
	v_mfma_f32_16x16x32_bf16 v[98:101], v[216:219], v[184:187], v[98:101]
	v_mfma_f32_16x16x32_bf16 v[86:89], v[208:211], v[192:195], v[86:89]
	v_mfma_f32_16x16x32_bf16 v[82:85], v[216:219], v[192:195], v[82:85]
	v_mfma_f32_16x16x32_bf16 v[70:73], v[208:211], v[200:203], v[70:73]
	v_mfma_f32_16x16x32_bf16 v[66:69], v[216:219], v[200:203], v[66:69]
	s_mov_b32 m0, s41
	v_lshl_add_u64 v[160:161], v[222:223], 0, s[2:3]
	s_barrier
	ds_read_b128 v[172:175], v168 offset:49152
	ds_read_b128 v[176:179], v168 offset:50176
	ds_read_b128 v[180:183], v168 offset:51200
	ds_read_b128 v[184:187], v168 offset:52224
	ds_read_b128 v[188:191], v168 offset:53248
	ds_read_b128 v[192:195], v168 offset:54272
	ds_read_b128 v[196:199], v168 offset:55296
	ds_read_b128 v[200:203], v168 offset:56320
	global_load_lds_dwordx4 v[160:161], off
	v_lshl_add_u64 v[160:161], v[224:225], 0, s[2:3]
	s_mov_b32 m0, s42
	s_nop 0
	global_load_lds_dwordx4 v[160:161], off
	s_barrier
	s_waitcnt lgkmcnt(0)
	s_waitcnt lgkmcnt(0)
	v_mfma_f32_16x16x32_bf16 v[62:65], v[144:147], v[172:175], v[62:65]
	v_mfma_f32_16x16x32_bf16 v[58:61], v[152:155], v[172:175], v[58:61]
	v_mfma_f32_16x16x32_bf16 v[46:49], v[144:147], v[180:183], v[46:49]
	v_mfma_f32_16x16x32_bf16 v[42:45], v[152:155], v[180:183], v[42:45]
	v_mfma_f32_16x16x32_bf16 v[30:33], v[144:147], v[188:191], v[30:33]
	v_mfma_f32_16x16x32_bf16 v[26:29], v[152:155], v[188:191], v[26:29]
	v_mfma_f32_16x16x32_bf16 v[14:17], v[144:147], v[196:199], v[14:17]
	v_mfma_f32_16x16x32_bf16 v[10:13], v[152:155], v[196:199], v[10:13]
	v_mfma_f32_16x16x32_bf16 v[62:65], v[148:151], v[176:179], v[62:65]
	v_mfma_f32_16x16x32_bf16 v[58:61], v[156:159], v[176:179], v[58:61]
	v_mfma_f32_16x16x32_bf16 v[46:49], v[148:151], v[184:187], v[46:49]
	v_mfma_f32_16x16x32_bf16 v[42:45], v[156:159], v[184:187], v[42:45]
	v_mfma_f32_16x16x32_bf16 v[30:33], v[148:151], v[192:195], v[30:33]
	v_mfma_f32_16x16x32_bf16 v[26:29], v[156:159], v[192:195], v[26:29]
	v_mfma_f32_16x16x32_bf16 v[14:17], v[148:151], v[200:203], v[14:17]
	v_mfma_f32_16x16x32_bf16 v[10:13], v[156:159], v[200:203], v[10:13]
	s_barrier
	s_add_u32 s24, s24, 0x40080
	s_addc_u32 s25, s25, 0
	s_add_i32 s26, s26, s34
	v_lshl_add_u64 v[144:145], s[24:25], 0, v[130:131]
	s_mov_b32 m0, s26
	s_nop 0
	global_load_lds_dwordx4 v[144:145], off
	v_lshl_add_u64 v[144:145], s[24:25], 0, v[132:133]
	s_add_i32 m0, s26, 0x2000
	s_nop 0
	global_load_lds_dwordx4 v[144:145], off
	s_waitcnt vmcnt(6)
	s_barrier
	v_mfma_f32_16x16x32_bf16 v[54:57], v[204:207], v[172:175], v[54:57]
	v_mfma_f32_16x16x32_bf16 v[50:53], v[212:215], v[172:175], v[50:53]
	v_mfma_f32_16x16x32_bf16 v[38:41], v[204:207], v[180:183], v[38:41]
	v_mfma_f32_16x16x32_bf16 v[34:37], v[212:215], v[180:183], v[34:37]
	v_mfma_f32_16x16x32_bf16 v[22:25], v[204:207], v[188:191], v[22:25]
	v_mfma_f32_16x16x32_bf16 v[18:21], v[212:215], v[188:191], v[18:21]
	v_mfma_f32_16x16x32_bf16 v[6:9], v[204:207], v[196:199], v[6:9]
	v_mfma_f32_16x16x32_bf16 v[2:5], v[212:215], v[196:199], v[2:5]
	v_mfma_f32_16x16x32_bf16 v[54:57], v[208:211], v[176:179], v[54:57]
	v_mfma_f32_16x16x32_bf16 v[50:53], v[216:219], v[176:179], v[50:53]
	v_mfma_f32_16x16x32_bf16 v[38:41], v[208:211], v[184:187], v[38:41]
	v_mfma_f32_16x16x32_bf16 v[34:37], v[216:219], v[184:187], v[34:37]
	v_mfma_f32_16x16x32_bf16 v[22:25], v[208:211], v[192:195], v[22:25]
	v_mfma_f32_16x16x32_bf16 v[18:21], v[216:219], v[192:195], v[18:21]
	v_mfma_f32_16x16x32_bf16 v[6:9], v[208:211], v[200:203], v[6:9]
	v_mfma_f32_16x16x32_bf16 v[2:5], v[216:219], v[200:203], v[2:5]
	s_add_i32 s51, s51, 2
	s_add_u32 s22, s22, 0x100
	s_addc_u32 s23, s23, 0
	s_add_u32 s29, s29, 0x100
	s_addc_u32 s50, s50, 0
	s_cmp_gt_u32 s51, 13
	s_barrier
	s_cbranch_scc0 .LBB0_474
	s_mov_b64 s[22:23], exec
	s_load_dwordx8 s[52:59], s[78:79], 0x220
	s_load_dwordx4 s[24:27], s[78:79], 0x240
	v_and_b32_e32 v144, 15, v248
	v_bfe_u32 v147, v248, 8, 1
	v_bfe_u32 v145, v248, 6, 2
	v_bfe_u32 v134, v248, 4, 2
	v_lshlrev_b32_e32 v145, 5, v145
	v_lshl_or_b32 v145, v134, 2, v145
	v_lshl_add_u32 v147, v147, 6, v144
	s_lshl_b32 s9, s6, 8
	v_add_u32_e32 v146, s9, v147
	s_cmp_lt_u32 s0, 4
	s_cbranch_scc1 .Lmy_ri_q
	s_cmp_lt_u32 s0, 8
	s_cbranch_scc1 .Lmy_ri_k
	s_cmp_lt_u32 s0, 16
	s_cbranch_scc1 .Lmy_ri_v
	s_branch .Lmy_ri_g

.LBB0_1854:
	s_add_u32 s47, s24, 0x100
	s_addc_u32 s48, s25, 0
	s_ashr_i32 s19, s18, 31
	s_lshl_b64 s[20:21], s[18:19], 20
	s_add_u32 s22, s16, s20
	s_addc_u32 s23, s17, s21
	s_and_b64 s[20:21], s[6:7], exec
	v_readlane_b32 s52, v253, 27
	s_cselect_b32 s19, s23, s1
	s_cselect_b32 s49, s22, s0
	s_ashr_i32 s15, s14, 31
	v_readlane_b32 s54, v253, 29
	v_readlane_b32 s55, v253, 30
	s_lshl_b64 s[20:21], s[14:15], 20
	s_mov_b64 s[50:51], s[54:55]
	s_add_u32 s20, s50, s20
	s_addc_u32 s21, s51, s21
	v_readlane_b32 s53, v253, 28
	v_readlane_b32 s56, v253, 31
	v_readlane_b32 s57, v253, 32
	v_readlane_b32 s58, v253, 33
	v_readlane_b32 s59, v253, 34
	v_readlane_b32 s60, v253, 35
	v_readlane_b32 s61, v253, 36
	v_readlane_b32 s62, v253, 37
	v_readlane_b32 s63, v253, 38
	s_and_b64 s[26:27], s[6:7], exec
	v_readlane_b32 s64, v253, 39
	v_readlane_b32 s65, v253, 40
	v_readlane_b32 s66, v253, 41
	v_readlane_b32 s67, v253, 42
	s_mov_b64 s[52:53], s[56:57]
	s_cselect_b32 s15, s21, s25
	s_cselect_b32 s50, s20, s24
	v_lshl_add_u64 v[142:143], s[0:1], 0, v[134:135]
	v_lshl_add_u64 v[144:145], s[0:1], 0, v[136:137]
	s_mov_b32 s51, -2
	s_mov_b64 s[24:25], 0
	s_mov_b64 s[54:55], s[58:59]
	s_mov_b64 s[56:57], s[60:61]
	s_mov_b64 s[58:59], s[62:63]
	s_mov_b64 s[60:61], s[64:65]
	s_mov_b64 s[62:63], s[66:67]
	v_readfirstlane_b32 s98, v248
	s_cmpk_lt_u32 s98, 0x100
	s_cbranch_scc0 .Lmy_lprio2
	s_setprio 1
.Lmy_lprio2:
.LBB0_1855:
	v_add_u32_e32 v149, s44, v147
	s_add_u32 s26, s0, s24
	ds_read_b128 v[150:153], v149
	ds_read_b128 v[154:157], v149 offset:1024
	ds_read_b128 v[158:161], v149 offset:2048
	ds_read_b128 v[162:165], v149 offset:3072
	s_addc_u32 s27, s1, s25
	s_add_u32 s26, s26, 0x100
	s_addc_u32 s27, s27, 0
	s_add_u32 s52, s47, s24
	s_addc_u32 s53, s48, s25
	s_cmpk_eq_i32 s24, 0xf00
	s_cselect_b32 s29, s19, s27
	s_cselect_b32 s28, s49, s26
	s_cselect_b32 s27, s15, s53
	s_cselect_b32 s26, s50, s52
	v_lshl_add_u64 v[202:203], v[142:143], 0, s[24:25]
	s_add_i32 m0, s36, 0xc000
	ds_read_b128 v[166:169], v148
	ds_read_b128 v[170:173], v148 offset:1024
	ds_read_b128 v[174:177], v148 offset:2048
	ds_read_b128 v[182:185], v148 offset:3072
	ds_read_b128 v[186:189], v148 offset:4096
	ds_read_b128 v[190:193], v148 offset:5120
	ds_read_b128 v[194:197], v148 offset:6144
	ds_read_b128 v[198:201], v148 offset:7168
	global_load_lds_dwordx4 v[202:203], off
	v_lshl_add_u64 v[202:203], v[144:145], 0, s[24:25]
	s_add_i32 m0, s36, 0xe000
	s_nop 0
	global_load_lds_dwordx4 v[202:203], off
	s_waitcnt lgkmcnt(8)
	s_barrier
	s_waitcnt lgkmcnt(0)
	s_waitcnt lgkmcnt(0)
	v_mfma_f32_16x16x32_bf16 v[126:129], v[150:153], v[166:169], v[126:129]
	v_mfma_f32_16x16x32_bf16 v[122:125], v[158:161], v[166:169], v[122:125]
	v_mfma_f32_16x16x32_bf16 v[110:113], v[150:153], v[174:177], v[110:113]
	v_mfma_f32_16x16x32_bf16 v[106:109], v[158:161], v[174:177], v[106:109]
	v_mfma_f32_16x16x32_bf16 v[94:97], v[150:153], v[186:189], v[94:97]
	v_mfma_f32_16x16x32_bf16 v[90:93], v[158:161], v[186:189], v[90:93]
	v_mfma_f32_16x16x32_bf16 v[78:81], v[150:153], v[194:197], v[78:81]
	v_mfma_f32_16x16x32_bf16 v[74:77], v[158:161], v[194:197], v[74:77]
	v_mfma_f32_16x16x32_bf16 v[126:129], v[154:157], v[170:173], v[126:129]
	v_mfma_f32_16x16x32_bf16 v[122:125], v[162:165], v[170:173], v[122:125]
	v_mfma_f32_16x16x32_bf16 v[110:113], v[154:157], v[182:185], v[110:113]
	v_mfma_f32_16x16x32_bf16 v[106:109], v[162:165], v[182:185], v[106:109]
	v_mfma_f32_16x16x32_bf16 v[94:97], v[154:157], v[190:193], v[94:97]
	v_mfma_f32_16x16x32_bf16 v[90:93], v[162:165], v[190:193], v[90:93]
	v_mfma_f32_16x16x32_bf16 v[78:81], v[154:157], v[198:201], v[78:81]
	v_mfma_f32_16x16x32_bf16 v[74:77], v[162:165], v[198:201], v[74:77]
	s_barrier
	s_add_i32 s52, s44, s35
	v_add_u32_e32 v149, s45, v147
	v_lshl_add_u64 v[218:219], s[26:27], 0, v[130:131]
	s_mov_b32 m0, s52
	ds_read_b128 v[202:205], v149
	ds_read_b128 v[206:209], v149 offset:1024
	ds_read_b128 v[210:213], v149 offset:2048
	ds_read_b128 v[214:217], v149 offset:3072
	global_load_lds_dwordx4 v[218:219], off
	v_lshl_add_u64 v[220:221], s[26:27], 0, v[132:133]
	s_add_i32 m0, s52, 0x2000
	s_nop 0
	global_load_lds_dwordx4 v[220:221], off
	s_barrier
	s_waitcnt lgkmcnt(0)
	s_waitcnt lgkmcnt(0)
	v_mfma_f32_16x16x32_bf16 v[118:121], v[202:205], v[166:169], v[118:121]
	v_mfma_f32_16x16x32_bf16 v[114:117], v[210:213], v[166:169], v[114:117]
	v_mfma_f32_16x16x32_bf16 v[102:105], v[202:205], v[174:177], v[102:105]
	v_mfma_f32_16x16x32_bf16 v[98:101], v[210:213], v[174:177], v[98:101]
	v_mfma_f32_16x16x32_bf16 v[86:89], v[202:205], v[186:189], v[86:89]
	v_mfma_f32_16x16x32_bf16 v[82:85], v[210:213], v[186:189], v[82:85]
	v_mfma_f32_16x16x32_bf16 v[70:73], v[202:205], v[194:197], v[70:73]
	v_mfma_f32_16x16x32_bf16 v[66:69], v[210:213], v[194:197], v[66:69]
	v_mfma_f32_16x16x32_bf16 v[118:121], v[206:209], v[170:173], v[118:121]
	v_mfma_f32_16x16x32_bf16 v[114:117], v[214:217], v[170:173], v[114:117]
	v_mfma_f32_16x16x32_bf16 v[102:105], v[206:209], v[182:185], v[102:105]
	v_mfma_f32_16x16x32_bf16 v[98:101], v[214:217], v[182:185], v[98:101]
	v_mfma_f32_16x16x32_bf16 v[86:89], v[206:209], v[190:193], v[86:89]
	v_mfma_f32_16x16x32_bf16 v[82:85], v[214:217], v[190:193], v[82:85]
	v_mfma_f32_16x16x32_bf16 v[70:73], v[206:209], v[198:201], v[70:73]
	v_mfma_f32_16x16x32_bf16 v[66:69], v[214:217], v[198:201], v[66:69]
	s_mov_b32 m0, s36
	v_lshl_add_u64 v[222:223], s[28:29], 0, v[130:131]
	s_barrier
	ds_read_b128 v[166:169], v148 offset:16384
	ds_read_b128 v[170:173], v148 offset:17408
	ds_read_b128 v[174:177], v148 offset:18432
	ds_read_b128 v[182:185], v148 offset:19456
	ds_read_b128 v[186:189], v148 offset:20480
	ds_read_b128 v[190:193], v148 offset:21504
	ds_read_b128 v[194:197], v148 offset:22528
	ds_read_b128 v[198:201], v148 offset:23552
	global_load_lds_dwordx4 v[222:223], off
	v_lshl_add_u64 v[224:225], s[28:29], 0, v[132:133]
	s_mov_b32 m0, s37
	s_nop 0
	global_load_lds_dwordx4 v[224:225], off
	s_barrier
	s_waitcnt lgkmcnt(0)
	s_waitcnt lgkmcnt(0)
	v_mfma_f32_16x16x32_bf16 v[62:65], v[150:153], v[166:169], v[62:65]
	v_mfma_f32_16x16x32_bf16 v[58:61], v[158:161], v[166:169], v[58:61]
	v_mfma_f32_16x16x32_bf16 v[46:49], v[150:153], v[174:177], v[46:49]
	v_mfma_f32_16x16x32_bf16 v[42:45], v[158:161], v[174:177], v[42:45]
	v_mfma_f32_16x16x32_bf16 v[30:33], v[150:153], v[186:189], v[30:33]
	v_mfma_f32_16x16x32_bf16 v[26:29], v[158:161], v[186:189], v[26:29]
	v_mfma_f32_16x16x32_bf16 v[14:17], v[150:153], v[194:197], v[14:17]
	v_mfma_f32_16x16x32_bf16 v[10:13], v[158:161], v[194:197], v[10:13]
	v_mfma_f32_16x16x32_bf16 v[62:65], v[154:157], v[170:173], v[62:65]
	v_mfma_f32_16x16x32_bf16 v[58:61], v[162:165], v[170:173], v[58:61]
	v_mfma_f32_16x16x32_bf16 v[46:49], v[154:157], v[182:185], v[46:49]
	v_mfma_f32_16x16x32_bf16 v[42:45], v[162:165], v[182:185], v[42:45]
	v_mfma_f32_16x16x32_bf16 v[30:33], v[154:157], v[190:193], v[30:33]
	v_mfma_f32_16x16x32_bf16 v[26:29], v[162:165], v[190:193], v[26:29]
	v_mfma_f32_16x16x32_bf16 v[14:17], v[154:157], v[198:201], v[14:17]
	v_mfma_f32_16x16x32_bf16 v[10:13], v[162:165], v[198:201], v[10:13]
	s_barrier
	s_add_u32 s52, s26, 0x80000
	s_addc_u32 s53, s27, 0
	s_add_i32 s54, s45, s35
	v_lshl_add_u64 v[150:151], s[52:53], 0, v[130:131]
	s_mov_b32 m0, s54
	s_nop 0
	global_load_lds_dwordx4 v[150:151], off
	v_lshl_add_u64 v[150:151], s[52:53], 0, v[132:133]
	s_add_i32 m0, s54, 0x2000
	s_nop 0
	global_load_lds_dwordx4 v[150:151], off
	s_waitcnt vmcnt(6)
	s_barrier
	v_mfma_f32_16x16x32_bf16 v[54:57], v[202:205], v[166:169], v[54:57]
	v_mfma_f32_16x16x32_bf16 v[50:53], v[210:213], v[166:169], v[50:53]
	v_mfma_f32_16x16x32_bf16 v[38:41], v[202:205], v[174:177], v[38:41]
	v_mfma_f32_16x16x32_bf16 v[34:37], v[210:213], v[174:177], v[34:37]
	v_mfma_f32_16x16x32_bf16 v[22:25], v[202:205], v[186:189], v[22:25]
	v_mfma_f32_16x16x32_bf16 v[18:21], v[210:213], v[186:189], v[18:21]
	v_mfma_f32_16x16x32_bf16 v[6:9], v[202:205], v[194:197], v[6:9]
	v_mfma_f32_16x16x32_bf16 v[2:5], v[210:213], v[194:197], v[2:5]
	v_mfma_f32_16x16x32_bf16 v[54:57], v[206:209], v[170:173], v[54:57]
	v_mfma_f32_16x16x32_bf16 v[50:53], v[214:217], v[170:173], v[50:53]
	v_mfma_f32_16x16x32_bf16 v[38:41], v[206:209], v[182:185], v[38:41]
	v_mfma_f32_16x16x32_bf16 v[34:37], v[214:217], v[182:185], v[34:37]
	v_mfma_f32_16x16x32_bf16 v[22:25], v[206:209], v[190:193], v[22:25]
	v_mfma_f32_16x16x32_bf16 v[18:21], v[214:217], v[190:193], v[18:21]
	v_mfma_f32_16x16x32_bf16 v[6:9], v[206:209], v[198:201], v[6:9]
	v_mfma_f32_16x16x32_bf16 v[2:5], v[214:217], v[198:201], v[2:5]
	s_add_i32 s52, 0, 0x18000
	v_add_u32_e32 v149, s52, v147
	s_barrier
	ds_read_b128 v[150:153], v149
	ds_read_b128 v[154:157], v149 offset:1024
	ds_read_b128 v[158:161], v149 offset:2048
	ds_read_b128 v[162:165], v149 offset:3072
	s_add_u32 s28, s28, 0x80000
	s_addc_u32 s29, s29, 0
	s_mov_b32 m0, s38
	v_lshl_add_u64 v[202:203], s[28:29], 0, v[130:131]
	ds_read_b128 v[166:169], v148 offset:32768
	ds_read_b128 v[170:173], v148 offset:33792
	ds_read_b128 v[174:177], v148 offset:34816
	ds_read_b128 v[182:185], v148 offset:35840
	ds_read_b128 v[186:189], v148 offset:36864
	ds_read_b128 v[190:193], v148 offset:37888
	ds_read_b128 v[194:197], v148 offset:38912
	ds_read_b128 v[198:201], v148 offset:39936
	global_load_lds_dwordx4 v[202:203], off
	v_lshl_add_u64 v[202:203], s[28:29], 0, v[132:133]
	s_mov_b32 m0, s39
	s_nop 0
	global_load_lds_dwordx4 v[202:203], off
	s_waitcnt lgkmcnt(8)
	s_barrier
	s_waitcnt lgkmcnt(0)
	s_waitcnt lgkmcnt(0)
	v_mfma_f32_16x16x32_bf16 v[126:129], v[150:153], v[166:169], v[126:129]
	v_mfma_f32_16x16x32_bf16 v[122:125], v[158:161], v[166:169], v[122:125]
	v_mfma_f32_16x16x32_bf16 v[110:113], v[150:153], v[174:177], v[110:113]
	v_mfma_f32_16x16x32_bf16 v[106:109], v[158:161], v[174:177], v[106:109]
	v_mfma_f32_16x16x32_bf16 v[94:97], v[150:153], v[186:189], v[94:97]
	v_mfma_f32_16x16x32_bf16 v[90:93], v[158:161], v[186:189], v[90:93]
	v_mfma_f32_16x16x32_bf16 v[78:81], v[150:153], v[194:197], v[78:81]
	v_mfma_f32_16x16x32_bf16 v[74:77], v[158:161], v[194:197], v[74:77]
	v_mfma_f32_16x16x32_bf16 v[126:129], v[154:157], v[170:173], v[126:129]
	v_mfma_f32_16x16x32_bf16 v[122:125], v[162:165], v[170:173], v[122:125]
	v_mfma_f32_16x16x32_bf16 v[110:113], v[154:157], v[182:185], v[110:113]
	v_mfma_f32_16x16x32_bf16 v[106:109], v[162:165], v[182:185], v[106:109]
	v_mfma_f32_16x16x32_bf16 v[94:97], v[154:157], v[190:193], v[94:97]
	v_mfma_f32_16x16x32_bf16 v[90:93], v[162:165], v[190:193], v[90:93]
	v_mfma_f32_16x16x32_bf16 v[78:81], v[154:157], v[198:201], v[78:81]
	v_mfma_f32_16x16x32_bf16 v[74:77], v[162:165], v[198:201], v[74:77]
	s_barrier
	s_add_i32 s28, 0, 0x1c000
	s_add_i32 s29, s52, s35
	v_add_u32_e32 v149, s28, v147
	v_lshl_add_u64 v[218:219], v[218:219], 0, s[2:3]
	s_mov_b32 m0, s29
	ds_read_b128 v[202:205], v149
	ds_read_b128 v[206:209], v149 offset:1024
	ds_read_b128 v[210:213], v149 offset:2048
	ds_read_b128 v[214:217], v149 offset:3072
	global_load_lds_dwordx4 v[218:219], off
	v_lshl_add_u64 v[218:219], v[220:221], 0, s[2:3]
	s_add_i32 m0, s29, 0x2000
	s_nop 0
	global_load_lds_dwordx4 v[218:219], off
	s_barrier
	s_waitcnt lgkmcnt(0)
	s_waitcnt lgkmcnt(0)
	v_mfma_f32_16x16x32_bf16 v[118:121], v[202:205], v[166:169], v[118:121]
	v_mfma_f32_16x16x32_bf16 v[114:117], v[210:213], v[166:169], v[114:117]
	v_mfma_f32_16x16x32_bf16 v[102:105], v[202:205], v[174:177], v[102:105]
	v_mfma_f32_16x16x32_bf16 v[98:101], v[210:213], v[174:177], v[98:101]
	v_mfma_f32_16x16x32_bf16 v[86:89], v[202:205], v[186:189], v[86:89]
	v_mfma_f32_16x16x32_bf16 v[82:85], v[210:213], v[186:189], v[82:85]
	v_mfma_f32_16x16x32_bf16 v[70:73], v[202:205], v[194:197], v[70:73]
	v_mfma_f32_16x16x32_bf16 v[66:69], v[210:213], v[194:197], v[66:69]
	v_mfma_f32_16x16x32_bf16 v[118:121], v[206:209], v[170:173], v[118:121]
	v_mfma_f32_16x16x32_bf16 v[114:117], v[214:217], v[170:173], v[114:117]
	v_mfma_f32_16x16x32_bf16 v[102:105], v[206:209], v[182:185], v[102:105]
	v_mfma_f32_16x16x32_bf16 v[98:101], v[214:217], v[182:185], v[98:101]
	v_mfma_f32_16x16x32_bf16 v[86:89], v[206:209], v[190:193], v[86:89]
	v_mfma_f32_16x16x32_bf16 v[82:85], v[214:217], v[190:193], v[82:85]
	v_mfma_f32_16x16x32_bf16 v[70:73], v[206:209], v[198:201], v[70:73]
	v_mfma_f32_16x16x32_bf16 v[66:69], v[214:217], v[198:201], v[66:69]
	s_mov_b32 m0, s42
	v_lshl_add_u64 v[218:219], v[222:223], 0, s[2:3]
	s_barrier
	ds_read_b128 v[166:169], v148 offset:49152
	ds_read_b128 v[170:173], v148 offset:50176
	ds_read_b128 v[174:177], v148 offset:51200
	ds_read_b128 v[182:185], v148 offset:52224
	ds_read_b128 v[186:189], v148 offset:53248
	ds_read_b128 v[190:193], v148 offset:54272
	ds_read_b128 v[194:197], v148 offset:55296
	ds_read_b128 v[198:201], v148 offset:56320
	global_load_lds_dwordx4 v[218:219], off
	v_lshl_add_u64 v[218:219], v[224:225], 0, s[2:3]
	s_mov_b32 m0, s43
	s_nop 0
	global_load_lds_dwordx4 v[218:219], off
	s_barrier
	s_waitcnt lgkmcnt(0)
	s_waitcnt lgkmcnt(0)
	v_mfma_f32_16x16x32_bf16 v[62:65], v[150:153], v[166:169], v[62:65]
	v_mfma_f32_16x16x32_bf16 v[58:61], v[158:161], v[166:169], v[58:61]
	v_mfma_f32_16x16x32_bf16 v[46:49], v[150:153], v[174:177], v[46:49]
	v_mfma_f32_16x16x32_bf16 v[42:45], v[158:161], v[174:177], v[42:45]
	v_mfma_f32_16x16x32_bf16 v[30:33], v[150:153], v[186:189], v[30:33]
	v_mfma_f32_16x16x32_bf16 v[26:29], v[158:161], v[186:189], v[26:29]
	v_mfma_f32_16x16x32_bf16 v[14:17], v[150:153], v[194:197], v[14:17]
	v_mfma_f32_16x16x32_bf16 v[10:13], v[158:161], v[194:197], v[10:13]
	v_mfma_f32_16x16x32_bf16 v[62:65], v[154:157], v[170:173], v[62:65]
	v_mfma_f32_16x16x32_bf16 v[58:61], v[162:165], v[170:173], v[58:61]
	v_mfma_f32_16x16x32_bf16 v[46:49], v[154:157], v[182:185], v[46:49]
	v_mfma_f32_16x16x32_bf16 v[42:45], v[162:165], v[182:185], v[42:45]
	v_mfma_f32_16x16x32_bf16 v[30:33], v[154:157], v[190:193], v[30:33]
	v_mfma_f32_16x16x32_bf16 v[26:29], v[162:165], v[190:193], v[26:29]
	v_mfma_f32_16x16x32_bf16 v[14:17], v[154:157], v[198:201], v[14:17]
	v_mfma_f32_16x16x32_bf16 v[10:13], v[162:165], v[198:201], v[10:13]
	s_barrier
	s_add_u32 s26, s26, 0x80080
	s_addc_u32 s27, s27, 0
	s_add_i32 s28, s28, s35
	v_lshl_add_u64 v[150:151], s[26:27], 0, v[130:131]
	s_mov_b32 m0, s28
	s_nop 0
	global_load_lds_dwordx4 v[150:151], off
	v_lshl_add_u64 v[150:151], s[26:27], 0, v[132:133]
	s_add_i32 m0, s28, 0x2000
	s_nop 0
	global_load_lds_dwordx4 v[150:151], off
	s_waitcnt vmcnt(6)
	s_barrier
	v_mfma_f32_16x16x32_bf16 v[54:57], v[202:205], v[166:169], v[54:57]
	v_mfma_f32_16x16x32_bf16 v[50:53], v[210:213], v[166:169], v[50:53]
	v_mfma_f32_16x16x32_bf16 v[38:41], v[202:205], v[174:177], v[38:41]
	v_mfma_f32_16x16x32_bf16 v[34:37], v[210:213], v[174:177], v[34:37]
	v_mfma_f32_16x16x32_bf16 v[22:25], v[202:205], v[186:189], v[22:25]
	v_mfma_f32_16x16x32_bf16 v[18:21], v[210:213], v[186:189], v[18:21]
	v_mfma_f32_16x16x32_bf16 v[6:9], v[202:205], v[194:197], v[6:9]
	v_mfma_f32_16x16x32_bf16 v[2:5], v[210:213], v[194:197], v[2:5]
	v_mfma_f32_16x16x32_bf16 v[54:57], v[206:209], v[170:173], v[54:57]
	v_mfma_f32_16x16x32_bf16 v[50:53], v[214:217], v[170:173], v[50:53]
	v_mfma_f32_16x16x32_bf16 v[38:41], v[206:209], v[182:185], v[38:41]
	v_mfma_f32_16x16x32_bf16 v[34:37], v[214:217], v[182:185], v[34:37]
	v_mfma_f32_16x16x32_bf16 v[22:25], v[206:209], v[190:193], v[22:25]
	v_mfma_f32_16x16x32_bf16 v[18:21], v[214:217], v[190:193], v[18:21]
	v_mfma_f32_16x16x32_bf16 v[6:9], v[206:209], v[198:201], v[6:9]
	v_mfma_f32_16x16x32_bf16 v[2:5], v[214:217], v[198:201], v[2:5]
	s_add_i32 s51, s51, 2
	s_add_u32 s24, s24, 0x100
	s_addc_u32 s25, s25, 0
	s_cmp_gt_u32 s51, 29
	s_barrier
	s_cbranch_scc0 .LBB0_1855
	s_add_u32 s24, s47, 0xffffff00
	s_addc_u32 s25, s48, -1
	s_andn2_b64 vcc, exec, s[6:7]
	s_cbranch_vccnz .LBB0_1846
	v_mov_b32_e32 v2, 0
	s_mov_b32 s12, s14
	s_mov_b32 s8, s18
	s_mov_b64 s[0:1], s[22:23]
	s_mov_b32 s41, s46
	v_mov_b32_e32 v3, v2
	v_mov_b32_e32 v4, v2
	v_mov_b32_e32 v5, v2
	v_mov_b32_e32 v6, v2
	v_mov_b32_e32 v7, v2
	v_mov_b32_e32 v8, v2
	v_mov_b32_e32 v9, v2
	v_mov_b32_e32 v18, v2
	v_mov_b32_e32 v19, v2
	v_mov_b32_e32 v20, v2
	v_mov_b32_e32 v21, v2
	v_mov_b32_e32 v22, v2
	v_mov_b32_e32 v23, v2
	v_mov_b32_e32 v24, v2
	v_mov_b32_e32 v25, v2
	v_mov_b32_e32 v34, v2
	v_mov_b32_e32 v35, v2
	v_mov_b32_e32 v36, v2
	v_mov_b32_e32 v37, v2
	v_mov_b32_e32 v38, v2
	v_mov_b32_e32 v39, v2
	v_mov_b32_e32 v40, v2
	v_mov_b32_e32 v41, v2
	v_mov_b32_e32 v50, v2
	v_mov_b32_e32 v51, v2
	v_mov_b32_e32 v52, v2
	v_mov_b32_e32 v53, v2
	v_mov_b32_e32 v54, v2
	v_mov_b32_e32 v55, v2
	v_mov_b32_e32 v56, v2
	v_mov_b32_e32 v57, v2
	v_mov_b32_e32 v10, v2
	v_mov_b32_e32 v11, v2
	v_mov_b32_e32 v12, v2
	v_mov_b32_e32 v13, v2
	v_mov_b32_e32 v14, v2
	v_mov_b32_e32 v15, v2
	v_mov_b32_e32 v16, v2
	v_mov_b32_e32 v17, v2
	v_mov_b32_e32 v26, v2
	v_mov_b32_e32 v27, v2
	v_mov_b32_e32 v28, v2
	v_mov_b32_e32 v29, v2
	v_mov_b32_e32 v30, v2
	v_mov_b32_e32 v31, v2
	v_mov_b32_e32 v32, v2
	v_mov_b32_e32 v33, v2
	v_mov_b32_e32 v42, v2
	v_mov_b32_e32 v43, v2
	v_mov_b32_e32 v44, v2
	v_mov_b32_e32 v45, v2
	v_mov_b32_e32 v46, v2
	v_mov_b32_e32 v47, v2
	v_mov_b32_e32 v48, v2
	v_mov_b32_e32 v49, v2
	v_mov_b32_e32 v58, v2
	v_mov_b32_e32 v59, v2
	v_mov_b32_e32 v60, v2
	v_mov_b32_e32 v61, v2
	v_mov_b32_e32 v62, v2
	v_mov_b32_e32 v63, v2
	v_mov_b32_e32 v64, v2
	v_mov_b32_e32 v65, v2
	v_mov_b32_e32 v66, v2
	v_mov_b32_e32 v67, v2
	v_mov_b32_e32 v68, v2
	v_mov_b32_e32 v69, v2
	v_mov_b32_e32 v70, v2
	v_mov_b32_e32 v71, v2
	v_mov_b32_e32 v72, v2
	v_mov_b32_e32 v73, v2
	v_mov_b32_e32 v82, v2
	v_mov_b32_e32 v83, v2
	v_mov_b32_e32 v84, v2
	v_mov_b32_e32 v85, v2
	v_mov_b32_e32 v86, v2
	v_mov_b32_e32 v87, v2
	v_mov_b32_e32 v88, v2
	v_mov_b32_e32 v89, v2
	v_mov_b32_e32 v98, v2
	v_mov_b32_e32 v99, v2
	v_mov_b32_e32 v100, v2
	v_mov_b32_e32 v101, v2
	v_mov_b32_e32 v102, v2
	v_mov_b32_e32 v103, v2
	v_mov_b32_e32 v104, v2
	v_mov_b32_e32 v105, v2
	v_mov_b32_e32 v114, v2
	v_mov_b32_e32 v115, v2
	v_mov_b32_e32 v116, v2
	v_mov_b32_e32 v117, v2
	v_mov_b32_e32 v118, v2
	v_mov_b32_e32 v119, v2
	v_mov_b32_e32 v120, v2
	v_mov_b32_e32 v121, v2
	v_mov_b32_e32 v74, v2
	v_mov_b32_e32 v75, v2
	v_mov_b32_e32 v76, v2
	v_mov_b32_e32 v77, v2
	v_mov_b32_e32 v78, v2
	v_mov_b32_e32 v79, v2
	v_mov_b32_e32 v80, v2
	v_mov_b32_e32 v81, v2
	v_mov_b32_e32 v90, v2
	v_mov_b32_e32 v91, v2
	v_mov_b32_e32 v92, v2
	v_mov_b32_e32 v93, v2
	v_mov_b32_e32 v94, v2
	v_mov_b32_e32 v95, v2
	v_mov_b32_e32 v96, v2
	v_mov_b32_e32 v97, v2
	v_mov_b32_e32 v106, v2
	v_mov_b32_e32 v107, v2
	v_mov_b32_e32 v108, v2
	v_mov_b32_e32 v109, v2
	v_mov_b32_e32 v110, v2
	v_mov_b32_e32 v111, v2
	v_mov_b32_e32 v112, v2
	v_mov_b32_e32 v113, v2
	v_mov_b32_e32 v122, v2
	v_mov_b32_e32 v123, v2
	v_mov_b32_e32 v124, v2
	v_mov_b32_e32 v125, v2
	v_mov_b32_e32 v126, v2
	v_mov_b32_e32 v127, v2
	v_mov_b32_e32 v128, v2
	v_mov_b32_e32 v129, v2
	s_andn2_b64 vcc, exec, s[4:5]
	s_cbranch_vccnz .LBB0_1847

.LBB0_2029:
	s_load_dwordx16 s[36:51], s[78:79], 0x1e0
	v_readlane_b32 s4, v255, 2
	v_readlane_b32 s5, v255, 3
	s_ashr_i32 s5, s4, 31
	v_cmp_lt_i64_e32 vcc, s[20:21], v[200:201]
	s_lshl_b64 s[20:21], s[4:5], 19
	s_mov_b32 s6, s4
	s_waitcnt lgkmcnt(0)
	s_add_u32 s4, s48, s20
	v_writelane_b32 v255, s6, 2
	s_addc_u32 s5, s49, s21
	s_and_b64 s[20:21], vcc, exec
	v_writelane_b32 v255, s7, 3
	s_cselect_b32 s13, s5, s17
	v_writelane_b32 v255, s4, 8
	s_cselect_b32 s15, s4, s16
	v_readlane_b32 s36, v253, 27
	v_writelane_b32 v255, s5, 9
	v_readlane_b32 s40, v253, 31
	v_readlane_b32 s0, v255, 0
	s_mov_b32 s4, s0
	s_ashr_i32 s5, s0, 31
	s_lshl_b64 s[20:21], s[4:5], 19
	v_readlane_b32 s1, v255, 1
	v_readlane_b32 s41, v253, 32
	s_add_u32 s4, s40, s20
	v_writelane_b32 v255, s0, 0
	s_addc_u32 s5, s41, s21
	s_and_b64 s[20:21], vcc, exec
	v_writelane_b32 v255, s1, 1
	s_cselect_b32 s22, s5, s19
	v_writelane_b32 v255, s4, 10
	s_cselect_b32 s23, s4, s18
	s_add_u32 s16, s16, 0x40080
	s_addc_u32 s17, s17, 0
	s_add_u32 s24, s18, 0x100
	v_mov_b32_e32 v2, 0
	v_writelane_b32 v255, s5, 11
	s_addc_u32 s25, s19, 0
	s_mov_b32 s26, -2
	v_mov_b32_e32 v3, v2
	v_mov_b32_e32 v4, v2
	v_mov_b32_e32 v5, v2
	v_mov_b32_e32 v66, v2
	v_mov_b32_e32 v67, v2
	v_mov_b32_e32 v68, v2
	v_mov_b32_e32 v69, v2
	s_waitcnt vmcnt(0)
	v_mov_b32_e32 v10, v2
	v_mov_b32_e32 v11, v2
	v_mov_b32_e32 v12, v2
	v_mov_b32_e32 v13, v2
	v_mov_b32_e32 v74, v2
	v_mov_b32_e32 v75, v2
	v_mov_b32_e32 v76, v2
	v_mov_b32_e32 v77, v2
	v_mov_b32_e32 v18, v2
	v_mov_b32_e32 v19, v2
	v_mov_b32_e32 v20, v2
	v_mov_b32_e32 v21, v2
	v_mov_b32_e32 v82, v2
	v_mov_b32_e32 v83, v2
	v_mov_b32_e32 v84, v2
	v_mov_b32_e32 v85, v2
	s_waitcnt vmcnt(0)
	v_mov_b32_e32 v26, v2
	v_mov_b32_e32 v27, v2
	v_mov_b32_e32 v28, v2
	v_mov_b32_e32 v29, v2
	v_mov_b32_e32 v90, v2
	v_mov_b32_e32 v91, v2
	v_mov_b32_e32 v92, v2
	v_mov_b32_e32 v93, v2
	v_mov_b32_e32 v6, v2
	v_mov_b32_e32 v7, v2
	v_mov_b32_e32 v8, v2
	v_mov_b32_e32 v9, v2
	v_mov_b32_e32 v70, v2
	v_mov_b32_e32 v71, v2
	v_mov_b32_e32 v72, v2
	v_mov_b32_e32 v73, v2
	v_mov_b32_e32 v14, v2
	v_mov_b32_e32 v15, v2
	v_mov_b32_e32 v16, v2
	v_mov_b32_e32 v17, v2
	v_mov_b32_e32 v78, v2
	v_mov_b32_e32 v79, v2
	v_mov_b32_e32 v80, v2
	v_mov_b32_e32 v81, v2
	v_mov_b32_e32 v22, v2
	v_mov_b32_e32 v23, v2
	v_mov_b32_e32 v24, v2
	v_mov_b32_e32 v25, v2
	v_mov_b32_e32 v86, v2
	v_mov_b32_e32 v87, v2
	v_mov_b32_e32 v88, v2
	v_mov_b32_e32 v89, v2
	v_mov_b32_e32 v30, v2
	v_mov_b32_e32 v31, v2
	v_mov_b32_e32 v32, v2
	v_mov_b32_e32 v33, v2
	v_mov_b32_e32 v94, v2
	v_mov_b32_e32 v95, v2
	v_mov_b32_e32 v96, v2
	v_mov_b32_e32 v97, v2
	v_mov_b32_e32 v34, v2
	v_mov_b32_e32 v35, v2
	v_mov_b32_e32 v36, v2
	v_mov_b32_e32 v37, v2
	v_mov_b32_e32 v98, v2
	v_mov_b32_e32 v99, v2
	v_mov_b32_e32 v100, v2
	v_mov_b32_e32 v101, v2
	v_mov_b32_e32 v42, v2
	v_mov_b32_e32 v43, v2
	v_mov_b32_e32 v44, v2
	v_mov_b32_e32 v45, v2
	v_mov_b32_e32 v106, v2
	v_mov_b32_e32 v107, v2
	v_mov_b32_e32 v108, v2
	v_mov_b32_e32 v109, v2
	v_mov_b32_e32 v50, v2
	v_mov_b32_e32 v51, v2
	v_mov_b32_e32 v52, v2
	v_mov_b32_e32 v53, v2
	v_mov_b32_e32 v114, v2
	v_mov_b32_e32 v115, v2
	v_mov_b32_e32 v116, v2
	v_mov_b32_e32 v117, v2
	v_mov_b32_e32 v58, v2
	v_mov_b32_e32 v59, v2
	v_mov_b32_e32 v60, v2
	v_mov_b32_e32 v61, v2
	v_mov_b32_e32 v122, v2
	v_mov_b32_e32 v123, v2
	v_mov_b32_e32 v124, v2
	v_mov_b32_e32 v125, v2
	v_mov_b32_e32 v38, v2
	v_mov_b32_e32 v39, v2
	v_mov_b32_e32 v40, v2
	v_mov_b32_e32 v41, v2
	v_mov_b32_e32 v102, v2
	v_mov_b32_e32 v103, v2
	v_mov_b32_e32 v104, v2
	v_mov_b32_e32 v105, v2
	v_mov_b32_e32 v46, v2
	v_mov_b32_e32 v47, v2
	v_mov_b32_e32 v48, v2
	v_mov_b32_e32 v49, v2
	v_mov_b32_e32 v110, v2
	v_mov_b32_e32 v111, v2
	v_mov_b32_e32 v112, v2
	v_mov_b32_e32 v113, v2
	v_mov_b32_e32 v54, v2
	v_mov_b32_e32 v55, v2
	v_mov_b32_e32 v56, v2
	v_mov_b32_e32 v57, v2
	v_mov_b32_e32 v118, v2
	v_mov_b32_e32 v119, v2
	v_mov_b32_e32 v120, v2
	v_mov_b32_e32 v121, v2
	v_mov_b32_e32 v62, v2
	v_mov_b32_e32 v63, v2
	v_mov_b32_e32 v64, v2
	v_mov_b32_e32 v65, v2
	v_mov_b32_e32 v126, v2
	v_mov_b32_e32 v127, v2
	v_mov_b32_e32 v128, v2
	v_mov_b32_e32 v129, v2
	v_readlane_b32 s37, v253, 28
	v_readlane_b32 s38, v253, 29
	v_readlane_b32 s39, v253, 30
	v_readlane_b32 s42, v253, 33
	v_readlane_b32 s43, v253, 34
	v_readlane_b32 s44, v253, 35
	v_readlane_b32 s45, v253, 36
	v_readlane_b32 s46, v253, 37
	v_readlane_b32 s47, v253, 38
	v_readlane_b32 s48, v253, 39
	v_readlane_b32 s49, v253, 40
	v_readlane_b32 s50, v253, 41
	v_readlane_b32 s51, v253, 42
	v_readfirstlane_b32 s98, v248
	s_cmpk_lt_u32 s98, 0x100
	s_cbranch_scc0 .Lmy_lprio3
	s_setprio 1
.Lmy_lprio3:
.LBB0_2030:
	ds_read_b128 v[130:133], v228
	ds_read_b128 v[134:137], v228 offset:1024
	ds_read_b128 v[138:141], v228 offset:2048
	ds_read_b128 v[142:145], v228 offset:3072
	s_add_u32 s18, s16, 0xfffc0080
	s_addc_u32 s19, s17, -1
	s_cmp_eq_u32 s26, 12
	s_cselect_b32 s21, s13, s19
	s_cselect_b32 s20, s15, s18
	s_cselect_b32 s19, s22, s25
	s_cselect_b32 s18, s23, s24
	v_lshl_add_u64 v[204:205], s[16:17], 0, v[196:197]
	s_add_i32 m0, s85, 0xc000
	ds_read_b128 v[146:149], v229
	ds_read_b128 v[150:153], v229 offset:1024
	ds_read_b128 v[154:157], v229 offset:2048
	ds_read_b128 v[158:161], v229 offset:3072
	ds_read_b128 v[162:165], v229 offset:4096
	ds_read_b128 v[166:169], v229 offset:5120
	ds_read_b128 v[170:173], v229 offset:6144
	ds_read_b128 v[174:177], v229 offset:7168
	global_load_lds_dwordx4 v[204:205], off
	v_lshl_add_u64 v[204:205], s[16:17], 0, v[198:199]
	s_add_i32 m0, s85, 0xe000
	s_nop 0
	global_load_lds_dwordx4 v[204:205], off
	s_waitcnt lgkmcnt(8)
	s_barrier
	s_waitcnt lgkmcnt(0)
	s_waitcnt lgkmcnt(0)
	v_mfma_f32_16x16x32_bf16 v[126:129], v[130:133], v[146:149], v[126:129]
	v_mfma_f32_16x16x32_bf16 v[62:65], v[138:141], v[146:149], v[62:65]
	v_mfma_f32_16x16x32_bf16 v[118:121], v[130:133], v[154:157], v[118:121]
	v_mfma_f32_16x16x32_bf16 v[54:57], v[138:141], v[154:157], v[54:57]
	v_mfma_f32_16x16x32_bf16 v[110:113], v[130:133], v[162:165], v[110:113]
	v_mfma_f32_16x16x32_bf16 v[46:49], v[138:141], v[162:165], v[46:49]
	v_mfma_f32_16x16x32_bf16 v[102:105], v[130:133], v[170:173], v[102:105]
	v_mfma_f32_16x16x32_bf16 v[38:41], v[138:141], v[170:173], v[38:41]
	v_mfma_f32_16x16x32_bf16 v[126:129], v[134:137], v[150:153], v[126:129]
	v_mfma_f32_16x16x32_bf16 v[62:65], v[142:145], v[150:153], v[62:65]
	v_mfma_f32_16x16x32_bf16 v[118:121], v[134:137], v[158:161], v[118:121]
	v_mfma_f32_16x16x32_bf16 v[54:57], v[142:145], v[158:161], v[54:57]
	v_mfma_f32_16x16x32_bf16 v[110:113], v[134:137], v[166:169], v[110:113]
	v_mfma_f32_16x16x32_bf16 v[46:49], v[142:145], v[166:169], v[46:49]
	v_mfma_f32_16x16x32_bf16 v[102:105], v[134:137], v[174:177], v[102:105]
	v_mfma_f32_16x16x32_bf16 v[38:41], v[142:145], v[174:177], v[38:41]
	s_barrier
	s_add_i32 s27, s64, s84
	v_lshl_add_u64 v[220:221], s[18:19], 0, v[184:185]
	s_mov_b32 m0, s27
	ds_read_b128 v[204:207], v230
	ds_read_b128 v[208:211], v230 offset:1024
	ds_read_b128 v[212:215], v230 offset:2048
	ds_read_b128 v[216:219], v230 offset:3072
	global_load_lds_dwordx4 v[220:221], off
	v_lshl_add_u64 v[222:223], s[18:19], 0, v[188:189]
	s_add_i32 m0, s27, 0x2000
	s_nop 0
	global_load_lds_dwordx4 v[222:223], off
	s_barrier
	s_waitcnt lgkmcnt(0)
	s_waitcnt lgkmcnt(0)
	v_mfma_f32_16x16x32_bf16 v[122:125], v[204:207], v[146:149], v[122:125]
	v_mfma_f32_16x16x32_bf16 v[58:61], v[212:215], v[146:149], v[58:61]
	v_mfma_f32_16x16x32_bf16 v[114:117], v[204:207], v[154:157], v[114:117]
	v_mfma_f32_16x16x32_bf16 v[50:53], v[212:215], v[154:157], v[50:53]
	v_mfma_f32_16x16x32_bf16 v[106:109], v[204:207], v[162:165], v[106:109]
	v_mfma_f32_16x16x32_bf16 v[42:45], v[212:215], v[162:165], v[42:45]
	v_mfma_f32_16x16x32_bf16 v[98:101], v[204:207], v[170:173], v[98:101]
	v_mfma_f32_16x16x32_bf16 v[34:37], v[212:215], v[170:173], v[34:37]
	v_mfma_f32_16x16x32_bf16 v[122:125], v[208:211], v[150:153], v[122:125]
	v_mfma_f32_16x16x32_bf16 v[58:61], v[216:219], v[150:153], v[58:61]
	v_mfma_f32_16x16x32_bf16 v[114:117], v[208:211], v[158:161], v[114:117]
	v_mfma_f32_16x16x32_bf16 v[50:53], v[216:219], v[158:161], v[50:53]
	v_mfma_f32_16x16x32_bf16 v[106:109], v[208:211], v[166:169], v[106:109]
	v_mfma_f32_16x16x32_bf16 v[42:45], v[216:219], v[166:169], v[42:45]
	v_mfma_f32_16x16x32_bf16 v[98:101], v[208:211], v[174:177], v[98:101]
	v_mfma_f32_16x16x32_bf16 v[34:37], v[216:219], v[174:177], v[34:37]
	s_mov_b32 m0, s85
	v_lshl_add_u64 v[224:225], s[20:21], 0, v[182:183]
	s_barrier
	ds_read_b128 v[146:149], v229 offset:16384
	ds_read_b128 v[150:153], v229 offset:17408
	ds_read_b128 v[154:157], v229 offset:18432
	ds_read_b128 v[158:161], v229 offset:19456
	ds_read_b128 v[162:165], v229 offset:20480
	ds_read_b128 v[166:169], v229 offset:21504
	ds_read_b128 v[170:173], v229 offset:22528
	ds_read_b128 v[174:177], v229 offset:23552
	global_load_lds_dwordx4 v[224:225], off
	v_lshl_add_u64 v[232:233], s[20:21], 0, v[186:187]
	s_mov_b32 m0, s86
	s_nop 0
	global_load_lds_dwordx4 v[232:233], off
	s_barrier
	s_waitcnt lgkmcnt(0)
	s_waitcnt lgkmcnt(0)
	v_mfma_f32_16x16x32_bf16 v[94:97], v[130:133], v[146:149], v[94:97]
	v_mfma_f32_16x16x32_bf16 v[30:33], v[138:141], v[146:149], v[30:33]
	v_mfma_f32_16x16x32_bf16 v[86:89], v[130:133], v[154:157], v[86:89]
	v_mfma_f32_16x16x32_bf16 v[22:25], v[138:141], v[154:157], v[22:25]
	v_mfma_f32_16x16x32_bf16 v[78:81], v[130:133], v[162:165], v[78:81]
	v_mfma_f32_16x16x32_bf16 v[14:17], v[138:141], v[162:165], v[14:17]
	v_mfma_f32_16x16x32_bf16 v[70:73], v[130:133], v[170:173], v[70:73]
	v_mfma_f32_16x16x32_bf16 v[6:9], v[138:141], v[170:173], v[6:9]
	v_mfma_f32_16x16x32_bf16 v[94:97], v[134:137], v[150:153], v[94:97]
	v_mfma_f32_16x16x32_bf16 v[30:33], v[142:145], v[150:153], v[30:33]
	v_mfma_f32_16x16x32_bf16 v[86:89], v[134:137], v[158:161], v[86:89]
	v_mfma_f32_16x16x32_bf16 v[22:25], v[142:145], v[158:161], v[22:25]
	v_mfma_f32_16x16x32_bf16 v[78:81], v[134:137], v[166:169], v[78:81]
	v_mfma_f32_16x16x32_bf16 v[14:17], v[142:145], v[166:169], v[14:17]
	v_mfma_f32_16x16x32_bf16 v[70:73], v[134:137], v[174:177], v[70:73]
	v_mfma_f32_16x16x32_bf16 v[6:9], v[142:145], v[174:177], v[6:9]
	s_barrier
	s_add_u32 s28, s18, 0x40000
	s_addc_u32 s29, s19, 0
	s_add_i32 s27, s65, s84
	v_lshl_add_u64 v[130:131], s[28:29], 0, v[184:185]
	s_mov_b32 m0, s27
	s_nop 0
	global_load_lds_dwordx4 v[130:131], off
	v_lshl_add_u64 v[130:131], s[28:29], 0, v[188:189]
	s_add_i32 m0, s27, 0x2000
	s_nop 0
	global_load_lds_dwordx4 v[130:131], off
	s_waitcnt vmcnt(6)
	s_barrier
	v_mfma_f32_16x16x32_bf16 v[90:93], v[204:207], v[146:149], v[90:93]
	v_mfma_f32_16x16x32_bf16 v[26:29], v[212:215], v[146:149], v[26:29]
	v_mfma_f32_16x16x32_bf16 v[82:85], v[204:207], v[154:157], v[82:85]
	v_mfma_f32_16x16x32_bf16 v[18:21], v[212:215], v[154:157], v[18:21]
	v_mfma_f32_16x16x32_bf16 v[74:77], v[204:207], v[162:165], v[74:77]
	v_mfma_f32_16x16x32_bf16 v[10:13], v[212:215], v[162:165], v[10:13]
	v_mfma_f32_16x16x32_bf16 v[66:69], v[204:207], v[170:173], v[66:69]
	v_mfma_f32_16x16x32_bf16 v[2:5], v[212:215], v[170:173], v[2:5]
	v_mfma_f32_16x16x32_bf16 v[90:93], v[208:211], v[150:153], v[90:93]
	v_mfma_f32_16x16x32_bf16 v[26:29], v[216:219], v[150:153], v[26:29]
	v_mfma_f32_16x16x32_bf16 v[82:85], v[208:211], v[158:161], v[82:85]
	v_mfma_f32_16x16x32_bf16 v[18:21], v[216:219], v[158:161], v[18:21]
	v_mfma_f32_16x16x32_bf16 v[74:77], v[208:211], v[166:169], v[74:77]
	v_mfma_f32_16x16x32_bf16 v[10:13], v[216:219], v[166:169], v[10:13]
	v_mfma_f32_16x16x32_bf16 v[66:69], v[208:211], v[174:177], v[66:69]
	v_mfma_f32_16x16x32_bf16 v[2:5], v[216:219], v[174:177], v[2:5]
	s_add_i32 s27, 0, 0x18000
	v_add_u32_e32 v142, s27, v1
	s_barrier
	ds_read_b128 v[130:133], v142
	ds_read_b128 v[134:137], v142 offset:1024
	ds_read_b128 v[138:141], v142 offset:2048
	ds_read_b128 v[142:145], v142 offset:3072
	s_add_u32 s20, s20, 0x40000
	s_addc_u32 s21, s21, 0
	s_mov_b32 m0, s87
	v_lshl_add_u64 v[204:205], s[20:21], 0, v[182:183]
	ds_read_b128 v[146:149], v229 offset:32768
	ds_read_b128 v[150:153], v229 offset:33792
	ds_read_b128 v[154:157], v229 offset:34816
	ds_read_b128 v[158:161], v229 offset:35840
	ds_read_b128 v[162:165], v229 offset:36864
	ds_read_b128 v[166:169], v229 offset:37888
	ds_read_b128 v[170:173], v229 offset:38912
	ds_read_b128 v[174:177], v229 offset:39936
	global_load_lds_dwordx4 v[204:205], off
	v_lshl_add_u64 v[204:205], s[20:21], 0, v[186:187]
	s_mov_b32 m0, s94
	s_nop 0
	global_load_lds_dwordx4 v[204:205], off
	s_waitcnt lgkmcnt(8)
	s_barrier
	s_waitcnt lgkmcnt(0)
	s_waitcnt lgkmcnt(0)
	v_mfma_f32_16x16x32_bf16 v[126:129], v[130:133], v[146:149], v[126:129]
	v_mfma_f32_16x16x32_bf16 v[62:65], v[138:141], v[146:149], v[62:65]
	v_mfma_f32_16x16x32_bf16 v[118:121], v[130:133], v[154:157], v[118:121]
	v_mfma_f32_16x16x32_bf16 v[54:57], v[138:141], v[154:157], v[54:57]
	v_mfma_f32_16x16x32_bf16 v[110:113], v[130:133], v[162:165], v[110:113]
	v_mfma_f32_16x16x32_bf16 v[46:49], v[138:141], v[162:165], v[46:49]
	v_mfma_f32_16x16x32_bf16 v[102:105], v[130:133], v[170:173], v[102:105]
	v_mfma_f32_16x16x32_bf16 v[38:41], v[138:141], v[170:173], v[38:41]
	v_mfma_f32_16x16x32_bf16 v[126:129], v[134:137], v[150:153], v[126:129]
	v_mfma_f32_16x16x32_bf16 v[62:65], v[142:145], v[150:153], v[62:65]
	v_mfma_f32_16x16x32_bf16 v[118:121], v[134:137], v[158:161], v[118:121]
	v_mfma_f32_16x16x32_bf16 v[54:57], v[142:145], v[158:161], v[54:57]
	v_mfma_f32_16x16x32_bf16 v[110:113], v[134:137], v[166:169], v[110:113]
	v_mfma_f32_16x16x32_bf16 v[46:49], v[142:145], v[166:169], v[46:49]
	v_mfma_f32_16x16x32_bf16 v[102:105], v[134:137], v[174:177], v[102:105]
	v_mfma_f32_16x16x32_bf16 v[38:41], v[142:145], v[174:177], v[38:41]
	s_barrier
	s_add_i32 s20, 0, 0x1c000
	s_add_i32 s21, s27, s84
	v_add_u32_e32 v190, s20, v1
	v_lshl_add_u64 v[220:221], v[220:221], 0, s[2:3]
	s_mov_b32 m0, s21
	ds_read_b128 v[204:207], v190
	ds_read_b128 v[208:211], v190 offset:1024
	ds_read_b128 v[212:215], v190 offset:2048
	ds_read_b128 v[216:219], v190 offset:3072
	global_load_lds_dwordx4 v[220:221], off
	v_lshl_add_u64 v[220:221], v[222:223], 0, s[2:3]
	s_add_i32 m0, s21, 0x2000
	s_nop 0
	global_load_lds_dwordx4 v[220:221], off
	s_barrier
	s_waitcnt lgkmcnt(0)
	s_waitcnt lgkmcnt(0)
	v_mfma_f32_16x16x32_bf16 v[122:125], v[204:207], v[146:149], v[122:125]
	v_mfma_f32_16x16x32_bf16 v[58:61], v[212:215], v[146:149], v[58:61]
	v_mfma_f32_16x16x32_bf16 v[114:117], v[204:207], v[154:157], v[114:117]
	v_mfma_f32_16x16x32_bf16 v[50:53], v[212:215], v[154:157], v[50:53]
	v_mfma_f32_16x16x32_bf16 v[106:109], v[204:207], v[162:165], v[106:109]
	v_mfma_f32_16x16x32_bf16 v[42:45], v[212:215], v[162:165], v[42:45]
	v_mfma_f32_16x16x32_bf16 v[98:101], v[204:207], v[170:173], v[98:101]
	v_mfma_f32_16x16x32_bf16 v[34:37], v[212:215], v[170:173], v[34:37]
	v_mfma_f32_16x16x32_bf16 v[122:125], v[208:211], v[150:153], v[122:125]
	v_mfma_f32_16x16x32_bf16 v[58:61], v[216:219], v[150:153], v[58:61]
	v_mfma_f32_16x16x32_bf16 v[114:117], v[208:211], v[158:161], v[114:117]
	v_mfma_f32_16x16x32_bf16 v[50:53], v[216:219], v[158:161], v[50:53]
	v_mfma_f32_16x16x32_bf16 v[106:109], v[208:211], v[166:169], v[106:109]
	v_mfma_f32_16x16x32_bf16 v[42:45], v[216:219], v[166:169], v[42:45]
	v_mfma_f32_16x16x32_bf16 v[98:101], v[208:211], v[174:177], v[98:101]
	v_mfma_f32_16x16x32_bf16 v[34:37], v[216:219], v[174:177], v[34:37]
	s_mov_b32 m0, s97
	v_lshl_add_u64 v[220:221], v[224:225], 0, s[2:3]
	s_barrier
	ds_read_b128 v[146:149], v229 offset:49152
	ds_read_b128 v[150:153], v229 offset:50176
	ds_read_b128 v[154:157], v229 offset:51200
	ds_read_b128 v[158:161], v229 offset:52224
	ds_read_b128 v[162:165], v229 offset:53248
	ds_read_b128 v[166:169], v229 offset:54272
	ds_read_b128 v[170:173], v229 offset:55296
	ds_read_b128 v[174:177], v229 offset:56320
	global_load_lds_dwordx4 v[220:221], off
	v_lshl_add_u64 v[220:221], v[232:233], 0, s[2:3]
	s_mov_b32 m0, s96
	s_nop 0
	global_load_lds_dwordx4 v[220:221], off
	s_barrier
	s_waitcnt lgkmcnt(0)
	s_waitcnt lgkmcnt(0)
	v_mfma_f32_16x16x32_bf16 v[94:97], v[130:133], v[146:149], v[94:97]
	v_mfma_f32_16x16x32_bf16 v[30:33], v[138:141], v[146:149], v[30:33]
	v_mfma_f32_16x16x32_bf16 v[86:89], v[130:133], v[154:157], v[86:89]
	v_mfma_f32_16x16x32_bf16 v[22:25], v[138:141], v[154:157], v[22:25]
	v_mfma_f32_16x16x32_bf16 v[78:81], v[130:133], v[162:165], v[78:81]
	v_mfma_f32_16x16x32_bf16 v[14:17], v[138:141], v[162:165], v[14:17]
	v_mfma_f32_16x16x32_bf16 v[70:73], v[130:133], v[170:173], v[70:73]
	v_mfma_f32_16x16x32_bf16 v[6:9], v[138:141], v[170:173], v[6:9]
	v_mfma_f32_16x16x32_bf16 v[94:97], v[134:137], v[150:153], v[94:97]
	v_mfma_f32_16x16x32_bf16 v[30:33], v[142:145], v[150:153], v[30:33]
	v_mfma_f32_16x16x32_bf16 v[86:89], v[134:137], v[158:161], v[86:89]
	v_mfma_f32_16x16x32_bf16 v[22:25], v[142:145], v[158:161], v[22:25]
	v_mfma_f32_16x16x32_bf16 v[78:81], v[134:137], v[166:169], v[78:81]
	v_mfma_f32_16x16x32_bf16 v[14:17], v[142:145], v[166:169], v[14:17]
	v_mfma_f32_16x16x32_bf16 v[70:73], v[134:137], v[174:177], v[70:73]
	v_mfma_f32_16x16x32_bf16 v[6:9], v[142:145], v[174:177], v[6:9]
	s_barrier
	s_add_u32 s18, s18, 0x40080
	s_addc_u32 s19, s19, 0
	s_add_i32 s20, s20, s84
	v_lshl_add_u64 v[130:131], s[18:19], 0, v[184:185]
	s_mov_b32 m0, s20
	s_nop 0
	global_load_lds_dwordx4 v[130:131], off
	v_lshl_add_u64 v[130:131], s[18:19], 0, v[188:189]
	s_add_i32 m0, s20, 0x2000
	s_nop 0
	global_load_lds_dwordx4 v[130:131], off
	s_waitcnt vmcnt(6)
	s_barrier
	v_mfma_f32_16x16x32_bf16 v[90:93], v[204:207], v[146:149], v[90:93]
	v_mfma_f32_16x16x32_bf16 v[26:29], v[212:215], v[146:149], v[26:29]
	v_mfma_f32_16x16x32_bf16 v[82:85], v[204:207], v[154:157], v[82:85]
	v_mfma_f32_16x16x32_bf16 v[18:21], v[212:215], v[154:157], v[18:21]
	v_mfma_f32_16x16x32_bf16 v[74:77], v[204:207], v[162:165], v[74:77]
	v_mfma_f32_16x16x32_bf16 v[10:13], v[212:215], v[162:165], v[10:13]
	v_mfma_f32_16x16x32_bf16 v[66:69], v[204:207], v[170:173], v[66:69]
	v_mfma_f32_16x16x32_bf16 v[2:5], v[212:215], v[170:173], v[2:5]
	v_mfma_f32_16x16x32_bf16 v[90:93], v[208:211], v[150:153], v[90:93]
	v_mfma_f32_16x16x32_bf16 v[26:29], v[216:219], v[150:153], v[26:29]
	v_mfma_f32_16x16x32_bf16 v[82:85], v[208:211], v[158:161], v[82:85]
	v_mfma_f32_16x16x32_bf16 v[18:21], v[216:219], v[158:161], v[18:21]
	v_mfma_f32_16x16x32_bf16 v[74:77], v[208:211], v[166:169], v[74:77]
	v_mfma_f32_16x16x32_bf16 v[10:13], v[216:219], v[166:169], v[10:13]
	v_mfma_f32_16x16x32_bf16 v[66:69], v[208:211], v[174:177], v[66:69]
	v_mfma_f32_16x16x32_bf16 v[2:5], v[216:219], v[174:177], v[2:5]
	s_add_i32 s26, s26, 2
	s_add_u32 s16, s16, 0x100
	s_addc_u32 s17, s17, 0
	s_add_u32 s24, s24, 0x100
	s_addc_u32 s25, s25, 0
	s_cmp_gt_u32 s26, 13
	s_barrier
	s_cbranch_scc0 .LBB0_2030
	s_mov_b64 s[16:17], -1
	s_cmp_lt_i32 s12, 64
	v_lshl_or_b32 v204, s14, 7, v181
	s_cbranch_scc0 .Lmy_ffnA_sample
	s_load_dwordx2 s[36:37], s[78:79], 0x268
	s_load_dwordx2 s[38:39], s[78:79], 0x2a0
	s_load_dwordx4 s[40:43], s[78:79], 0x70
	s_load_dwordx2 s[44:45], s[78:79], 0x120
	v_and_b32_e32 v204, 15, v248
	v_bfe_u32 v205, v248, 8, 1
	v_bfe_u32 v206, v248, 6, 2
	v_bfe_u32 v207, v248, 4, 2
	v_lshlrev_b32_e32 v206, 5, v206
	v_lshl_or_b32 v206, v207, 3, v206
	s_lshl_b32 s13, s14, 7
	v_add_u32_e32 v206, s13, v206
	s_lshl_b32 s13, s12, 8
	v_lshl_add_u32 v207, v205, 6, v204
	v_add_u32_e32 v207, s13, v207
	v_mul_u32_u24_e32 v231, 0x1600, v207
	v_lshl_add_u32 v231, v206, 1, v231
	v_lshlrev_b32_e32 v232, 2, v206
	s_lshl_b32 s13, s12, 4
	v_lshl_add_u32 v233, v205, 2, s13
	v_add_u32_e32 v208, -12, v204
	v_cmp_gt_u32_e32 vcc, 2, v204
	s_nop 1
	v_cndmask_b32_e32 v208, v208, v204, vcc
	v_add_u32_e32 v233, v233, v208
	v_mul_u32_u24_e32 v233, 0x2c00, v233
	v_lshl_add_u32 v233, v206, 1, v233
	s_lshr_b32 s13, s12, 3
	s_lshl_b32 s13, s13, 1
	s_add_i32 s13, s13, -14
	v_add_u32_e32 v234, s13, v204
	v_mul_u32_u24_e32 v234, 0x5800, v234
	v_lshl_add_u32 v234, v206, 2, v234
	v_readfirstlane_b32 s4, v248
	s_lshr_b32 s4, s4, 8
	s_and_b32 s5, s12, 7
	s_cmp_eq_u32 s5, 7
	s_cselect_b32 s5, 1, 0
	s_and_b32 s5, s5, s4
	s_waitcnt lgkmcnt(0)
	global_load_dwordx4 v[130:133], v232, s[40:41]
	v_add_u32_e32 v213, 0x5800, v232
	global_load_dwordx4 v[134:137], v213, s[40:41]
	v_add_u32_e32 v214, 0xb000, v232
	global_load_dwordx4 v[138:141], v214, s[40:41]
	global_load_dwordx4 v[142:145], v232, s[42:43]
	v_add_u32_e32 v215, 0x2c00, v232
	global_load_dwordx4 v[146:149], v215, s[40:41]
	v_add_u32_e32 v216, 0x8400, v232
	global_load_dwordx4 v[150:153], v216, s[40:41]
	v_add_u32_e32 v217, 0xdc00, v232
	global_load_dwordx4 v[154:157], v217, s[40:41]
	v_add_u32_e32 v218, 0x2c00, v232
	global_load_dwordx4 v[158:161], v218, s[42:43]
	s_mov_b32 exec_lo, 0x30003
	s_mov_b32 exec_hi, 0x30003
	v_cvt_pk_bf16_f32 v162, v126, v127
	v_cvt_pk_bf16_f32 v163, v128, v129
	global_store_dwordx2 v233, v[162:163], s[38:39]
	v_cvt_pk_bf16_f32 v164, v122, v123
	v_cvt_pk_bf16_f32 v165, v124, v125
	v_add_u32_e32 v220, 0x1600, v233
	global_store_dwordx2 v220, v[164:165], s[38:39]
	v_cvt_pk_bf16_f32 v166, v94, v95
	v_cvt_pk_bf16_f32 v167, v96, v97
	v_add_u32_e32 v221, 0x16000, v233
	global_store_dwordx2 v221, v[166:167], s[38:39]
	v_cvt_pk_bf16_f32 v168, v90, v91
	v_cvt_pk_bf16_f32 v169, v92, v93
	v_add_u32_e32 v222, 0x17600, v233
	global_store_dwordx2 v222, v[168:169], s[38:39]
	v_cvt_pk_bf16_f32 v170, v62, v63
	v_cvt_pk_bf16_f32 v171, v64, v65
	v_add_u32_e32 v223, 0x8, v233
	global_store_dwordx2 v223, v[170:171], s[38:39]
	v_cvt_pk_bf16_f32 v172, v58, v59
	v_cvt_pk_bf16_f32 v173, v60, v61
	v_add_u32_e32 v224, 0x1608, v233
	global_store_dwordx2 v224, v[172:173], s[38:39]
	v_cvt_pk_bf16_f32 v174, v30, v31
	v_cvt_pk_bf16_f32 v175, v32, v33
	v_add_u32_e32 v225, 0x16008, v233
	global_store_dwordx2 v225, v[174:175], s[38:39]
	v_cvt_pk_bf16_f32 v176, v26, v27
	v_cvt_pk_bf16_f32 v177, v28, v29
	v_add_u32_e32 v226, 0x17608, v233
	global_store_dwordx2 v226, v[176:177], s[38:39]
	s_mov_b32 exec_lo, 0xc000c000
	s_mov_b32 exec_hi, 0xc000c000
	v_cvt_pk_bf16_f32 v162, v102, v103
	v_cvt_pk_bf16_f32 v163, v104, v105
	global_store_dwordx2 v233, v[162:163], s[38:39]
	v_cvt_pk_bf16_f32 v164, v98, v99
	v_cvt_pk_bf16_f32 v165, v100, v101
	v_add_u32_e32 v220, 0x1600, v233
	global_store_dwordx2 v220, v[164:165], s[38:39]
	v_cvt_pk_bf16_f32 v166, v70, v71
	v_cvt_pk_bf16_f32 v167, v72, v73
	v_add_u32_e32 v221, 0x16000, v233
	global_store_dwordx2 v221, v[166:167], s[38:39]
	v_cvt_pk_bf16_f32 v168, v66, v67
	v_cvt_pk_bf16_f32 v169, v68, v69
	v_add_u32_e32 v222, 0x17600, v233
	global_store_dwordx2 v222, v[168:169], s[38:39]
	v_cvt_pk_bf16_f32 v170, v38, v39
	v_cvt_pk_bf16_f32 v171, v40, v41
	v_add_u32_e32 v223, 0x8, v233
	global_store_dwordx2 v223, v[170:171], s[38:39]
	v_cvt_pk_bf16_f32 v172, v34, v35
	v_cvt_pk_bf16_f32 v173, v36, v37
	v_add_u32_e32 v224, 0x1608, v233
	global_store_dwordx2 v224, v[172:173], s[38:39]
	v_cvt_pk_bf16_f32 v174, v6, v7
	v_cvt_pk_bf16_f32 v175, v8, v9
	v_add_u32_e32 v225, 0x16008, v233
	global_store_dwordx2 v225, v[174:175], s[38:39]
	v_cvt_pk_bf16_f32 v176, v2, v3
	v_cvt_pk_bf16_f32 v177, v4, v5
	v_add_u32_e32 v226, 0x17608, v233
	global_store_dwordx2 v226, v[176:177], s[38:39]
	s_cmp_lg_u32 s5, 0
	s_cbranch_scc0 .Lmy_ffnA_ncp
	global_store_dwordx4 v234, v[70:73], s[44:45]
	v_add_u32_e32 v220, 0x2c00, v234
	global_store_dwordx4 v220, v[66:69], s[44:45]
	v_add_u32_e32 v221, 0x10, v234
	global_store_dwordx4 v221, v[6:9], s[44:45]
	v_add_u32_e32 v222, 0x2c10, v234
	global_store_dwordx4 v222, v[2:5], s[44:45]

.LBB0_2513:
	s_add_u32 s45, s18, 0x100
	s_addc_u32 s46, s19, 0
	v_lshl_add_u64 v[142:143], s[8:9], 0, v[134:135]
	v_lshl_add_u64 v[144:145], s[8:9], 0, v[136:137]
	s_mov_b32 s47, -2
	s_mov_b64 s[18:19], 0
	v_readfirstlane_b32 s98, v248
	s_cmpk_lt_u32 s98, 0x100
	s_cbranch_scc0 .Lmy_lprio4
	s_setprio 1
.Lmy_lprio4:
.LBB0_2514:
	v_add_u32_e32 v149, s40, v147
	s_add_u32 s20, s8, s18
	ds_read_b128 v[150:153], v149
	ds_read_b128 v[154:157], v149 offset:1024
	ds_read_b128 v[158:161], v149 offset:2048
	ds_read_b128 v[162:165], v149 offset:3072
	s_addc_u32 s21, s9, s19
	s_add_u32 s20, s20, 0x100
	s_addc_u32 s21, s21, 0
	s_add_u32 s48, s45, s18
	s_addc_u32 s49, s46, s19
	s_cmpk_eq_i32 s18, 0x1500
	s_cselect_b32 s23, s17, s21
	s_cselect_b32 s22, s16, s20
	s_cselect_b32 s21, s1, s49
	s_cselect_b32 s20, s0, s48
	v_lshl_add_u64 v[202:203], v[142:143], 0, s[18:19]
	s_add_i32 m0, s31, 0xc000
	ds_read_b128 v[166:169], v148
	ds_read_b128 v[170:173], v148 offset:1024
	ds_read_b128 v[174:177], v148 offset:2048
	ds_read_b128 v[182:185], v148 offset:3072
	ds_read_b128 v[186:189], v148 offset:4096
	ds_read_b128 v[190:193], v148 offset:5120
	ds_read_b128 v[194:197], v148 offset:6144
	ds_read_b128 v[198:201], v148 offset:7168
	global_load_lds_dwordx4 v[202:203], off
	v_lshl_add_u64 v[202:203], v[144:145], 0, s[18:19]
	s_add_i32 m0, s31, 0xe000
	s_nop 0
	global_load_lds_dwordx4 v[202:203], off
	s_waitcnt lgkmcnt(8)
	s_barrier
	s_waitcnt lgkmcnt(0)
	s_waitcnt lgkmcnt(0)
	v_mfma_f32_16x16x32_bf16 v[126:129], v[150:153], v[166:169], v[126:129]
	v_mfma_f32_16x16x32_bf16 v[122:125], v[158:161], v[166:169], v[122:125]
	v_mfma_f32_16x16x32_bf16 v[110:113], v[150:153], v[174:177], v[110:113]
	v_mfma_f32_16x16x32_bf16 v[106:109], v[158:161], v[174:177], v[106:109]
	v_mfma_f32_16x16x32_bf16 v[94:97], v[150:153], v[186:189], v[94:97]
	v_mfma_f32_16x16x32_bf16 v[90:93], v[158:161], v[186:189], v[90:93]
	v_mfma_f32_16x16x32_bf16 v[78:81], v[150:153], v[194:197], v[78:81]
	v_mfma_f32_16x16x32_bf16 v[74:77], v[158:161], v[194:197], v[74:77]
	v_mfma_f32_16x16x32_bf16 v[126:129], v[154:157], v[170:173], v[126:129]
	v_mfma_f32_16x16x32_bf16 v[122:125], v[162:165], v[170:173], v[122:125]
	v_mfma_f32_16x16x32_bf16 v[110:113], v[154:157], v[182:185], v[110:113]
	v_mfma_f32_16x16x32_bf16 v[106:109], v[162:165], v[182:185], v[106:109]
	v_mfma_f32_16x16x32_bf16 v[94:97], v[154:157], v[190:193], v[94:97]
	v_mfma_f32_16x16x32_bf16 v[90:93], v[162:165], v[190:193], v[90:93]
	v_mfma_f32_16x16x32_bf16 v[78:81], v[154:157], v[198:201], v[78:81]
	v_mfma_f32_16x16x32_bf16 v[74:77], v[162:165], v[198:201], v[74:77]
	s_barrier
	s_add_i32 s48, s40, s30
	v_add_u32_e32 v149, s41, v147
	v_lshl_add_u64 v[218:219], s[20:21], 0, v[130:131]
	s_mov_b32 m0, s48
	ds_read_b128 v[202:205], v149
	ds_read_b128 v[206:209], v149 offset:1024
	ds_read_b128 v[210:213], v149 offset:2048
	ds_read_b128 v[214:217], v149 offset:3072
	global_load_lds_dwordx4 v[218:219], off
	v_lshl_add_u64 v[220:221], s[20:21], 0, v[132:133]
	s_add_i32 m0, s48, 0x2000
	s_nop 0
	global_load_lds_dwordx4 v[220:221], off
	s_barrier
	s_waitcnt lgkmcnt(0)
	s_waitcnt lgkmcnt(0)
	v_mfma_f32_16x16x32_bf16 v[118:121], v[202:205], v[166:169], v[118:121]
	v_mfma_f32_16x16x32_bf16 v[114:117], v[210:213], v[166:169], v[114:117]
	v_mfma_f32_16x16x32_bf16 v[102:105], v[202:205], v[174:177], v[102:105]
	v_mfma_f32_16x16x32_bf16 v[98:101], v[210:213], v[174:177], v[98:101]
	v_mfma_f32_16x16x32_bf16 v[86:89], v[202:205], v[186:189], v[86:89]
	v_mfma_f32_16x16x32_bf16 v[82:85], v[210:213], v[186:189], v[82:85]
	v_mfma_f32_16x16x32_bf16 v[70:73], v[202:205], v[194:197], v[70:73]
	v_mfma_f32_16x16x32_bf16 v[66:69], v[210:213], v[194:197], v[66:69]
	v_mfma_f32_16x16x32_bf16 v[118:121], v[206:209], v[170:173], v[118:121]
	v_mfma_f32_16x16x32_bf16 v[114:117], v[214:217], v[170:173], v[114:117]
	v_mfma_f32_16x16x32_bf16 v[102:105], v[206:209], v[182:185], v[102:105]
	v_mfma_f32_16x16x32_bf16 v[98:101], v[214:217], v[182:185], v[98:101]
	v_mfma_f32_16x16x32_bf16 v[86:89], v[206:209], v[190:193], v[86:89]
	v_mfma_f32_16x16x32_bf16 v[82:85], v[214:217], v[190:193], v[82:85]
	v_mfma_f32_16x16x32_bf16 v[70:73], v[206:209], v[198:201], v[70:73]
	v_mfma_f32_16x16x32_bf16 v[66:69], v[214:217], v[198:201], v[66:69]
	s_mov_b32 m0, s31
	v_lshl_add_u64 v[222:223], s[22:23], 0, v[130:131]
	s_barrier
	ds_read_b128 v[166:169], v148 offset:16384
	ds_read_b128 v[170:173], v148 offset:17408
	ds_read_b128 v[174:177], v148 offset:18432
	ds_read_b128 v[182:185], v148 offset:19456
	ds_read_b128 v[186:189], v148 offset:20480
	ds_read_b128 v[190:193], v148 offset:21504
	ds_read_b128 v[194:197], v148 offset:22528
	ds_read_b128 v[198:201], v148 offset:23552
	global_load_lds_dwordx4 v[222:223], off
	v_lshl_add_u64 v[224:225], s[22:23], 0, v[132:133]
	s_mov_b32 m0, s33
	s_nop 0
	global_load_lds_dwordx4 v[224:225], off
	s_barrier
	s_waitcnt lgkmcnt(0)
	s_waitcnt lgkmcnt(0)
	v_mfma_f32_16x16x32_bf16 v[62:65], v[150:153], v[166:169], v[62:65]
	v_mfma_f32_16x16x32_bf16 v[58:61], v[158:161], v[166:169], v[58:61]
	v_mfma_f32_16x16x32_bf16 v[46:49], v[150:153], v[174:177], v[46:49]
	v_mfma_f32_16x16x32_bf16 v[42:45], v[158:161], v[174:177], v[42:45]
	v_mfma_f32_16x16x32_bf16 v[30:33], v[150:153], v[186:189], v[30:33]
	v_mfma_f32_16x16x32_bf16 v[26:29], v[158:161], v[186:189], v[26:29]
	v_mfma_f32_16x16x32_bf16 v[14:17], v[150:153], v[194:197], v[14:17]
	v_mfma_f32_16x16x32_bf16 v[10:13], v[158:161], v[194:197], v[10:13]
	v_mfma_f32_16x16x32_bf16 v[62:65], v[154:157], v[170:173], v[62:65]
	v_mfma_f32_16x16x32_bf16 v[58:61], v[162:165], v[170:173], v[58:61]
	v_mfma_f32_16x16x32_bf16 v[46:49], v[154:157], v[182:185], v[46:49]
	v_mfma_f32_16x16x32_bf16 v[42:45], v[162:165], v[182:185], v[42:45]
	v_mfma_f32_16x16x32_bf16 v[30:33], v[154:157], v[190:193], v[30:33]
	v_mfma_f32_16x16x32_bf16 v[26:29], v[162:165], v[190:193], v[26:29]
	v_mfma_f32_16x16x32_bf16 v[14:17], v[154:157], v[198:201], v[14:17]
	v_mfma_f32_16x16x32_bf16 v[10:13], v[162:165], v[198:201], v[10:13]
	s_barrier
	s_add_u32 s48, s20, 0xb0000
	s_addc_u32 s49, s21, 0
	s_add_i32 s50, s41, s30
	v_lshl_add_u64 v[150:151], s[48:49], 0, v[130:131]
	s_mov_b32 m0, s50
	s_nop 0
	global_load_lds_dwordx4 v[150:151], off
	v_lshl_add_u64 v[150:151], s[48:49], 0, v[132:133]
	s_add_i32 m0, s50, 0x2000
	s_nop 0
	global_load_lds_dwordx4 v[150:151], off
	s_waitcnt vmcnt(6)
	s_barrier
	v_mfma_f32_16x16x32_bf16 v[54:57], v[202:205], v[166:169], v[54:57]
	v_mfma_f32_16x16x32_bf16 v[50:53], v[210:213], v[166:169], v[50:53]
	v_mfma_f32_16x16x32_bf16 v[38:41], v[202:205], v[174:177], v[38:41]
	v_mfma_f32_16x16x32_bf16 v[34:37], v[210:213], v[174:177], v[34:37]
	v_mfma_f32_16x16x32_bf16 v[22:25], v[202:205], v[186:189], v[22:25]
	v_mfma_f32_16x16x32_bf16 v[18:21], v[210:213], v[186:189], v[18:21]
	v_mfma_f32_16x16x32_bf16 v[6:9], v[202:205], v[194:197], v[6:9]
	v_mfma_f32_16x16x32_bf16 v[2:5], v[210:213], v[194:197], v[2:5]
	v_mfma_f32_16x16x32_bf16 v[54:57], v[206:209], v[170:173], v[54:57]
	v_mfma_f32_16x16x32_bf16 v[50:53], v[214:217], v[170:173], v[50:53]
	v_mfma_f32_16x16x32_bf16 v[38:41], v[206:209], v[182:185], v[38:41]
	v_mfma_f32_16x16x32_bf16 v[34:37], v[214:217], v[182:185], v[34:37]
	v_mfma_f32_16x16x32_bf16 v[22:25], v[206:209], v[190:193], v[22:25]
	v_mfma_f32_16x16x32_bf16 v[18:21], v[214:217], v[190:193], v[18:21]
	v_mfma_f32_16x16x32_bf16 v[6:9], v[206:209], v[198:201], v[6:9]
	v_mfma_f32_16x16x32_bf16 v[2:5], v[214:217], v[198:201], v[2:5]
	s_add_i32 s48, 0, 0x18000
	v_add_u32_e32 v149, s48, v147
	s_barrier
	ds_read_b128 v[150:153], v149
	ds_read_b128 v[154:157], v149 offset:1024
	ds_read_b128 v[158:161], v149 offset:2048
	ds_read_b128 v[162:165], v149 offset:3072
	s_add_u32 s22, s22, 0xb0000
	s_addc_u32 s23, s23, 0
	s_mov_b32 m0, s34
	v_lshl_add_u64 v[202:203], s[22:23], 0, v[130:131]
	ds_read_b128 v[166:169], v148 offset:32768
	ds_read_b128 v[170:173], v148 offset:33792
	ds_read_b128 v[174:177], v148 offset:34816
	ds_read_b128 v[182:185], v148 offset:35840
	ds_read_b128 v[186:189], v148 offset:36864
	ds_read_b128 v[190:193], v148 offset:37888
	ds_read_b128 v[194:197], v148 offset:38912
	ds_read_b128 v[198:201], v148 offset:39936
	global_load_lds_dwordx4 v[202:203], off
	v_lshl_add_u64 v[202:203], s[22:23], 0, v[132:133]
	s_mov_b32 m0, s35
	s_nop 0
	global_load_lds_dwordx4 v[202:203], off
	s_waitcnt lgkmcnt(8)
	s_barrier
	s_waitcnt lgkmcnt(0)
	s_waitcnt lgkmcnt(0)
	v_mfma_f32_16x16x32_bf16 v[126:129], v[150:153], v[166:169], v[126:129]
	v_mfma_f32_16x16x32_bf16 v[122:125], v[158:161], v[166:169], v[122:125]
	v_mfma_f32_16x16x32_bf16 v[110:113], v[150:153], v[174:177], v[110:113]
	v_mfma_f32_16x16x32_bf16 v[106:109], v[158:161], v[174:177], v[106:109]
	v_mfma_f32_16x16x32_bf16 v[94:97], v[150:153], v[186:189], v[94:97]
	v_mfma_f32_16x16x32_bf16 v[90:93], v[158:161], v[186:189], v[90:93]
	v_mfma_f32_16x16x32_bf16 v[78:81], v[150:153], v[194:197], v[78:81]
	v_mfma_f32_16x16x32_bf16 v[74:77], v[158:161], v[194:197], v[74:77]
	v_mfma_f32_16x16x32_bf16 v[126:129], v[154:157], v[170:173], v[126:129]
	v_mfma_f32_16x16x32_bf16 v[122:125], v[162:165], v[170:173], v[122:125]
	v_mfma_f32_16x16x32_bf16 v[110:113], v[154:157], v[182:185], v[110:113]
	v_mfma_f32_16x16x32_bf16 v[106:109], v[162:165], v[182:185], v[106:109]
	v_mfma_f32_16x16x32_bf16 v[94:97], v[154:157], v[190:193], v[94:97]
	v_mfma_f32_16x16x32_bf16 v[90:93], v[162:165], v[190:193], v[90:93]
	v_mfma_f32_16x16x32_bf16 v[78:81], v[154:157], v[198:201], v[78:81]
	v_mfma_f32_16x16x32_bf16 v[74:77], v[162:165], v[198:201], v[74:77]
	s_barrier
	s_add_i32 s22, 0, 0x1c000
	s_add_i32 s23, s48, s30
	v_add_u32_e32 v149, s22, v147
	v_lshl_add_u64 v[218:219], v[218:219], 0, s[10:11]
	s_mov_b32 m0, s23
	ds_read_b128 v[202:205], v149
	ds_read_b128 v[206:209], v149 offset:1024
	ds_read_b128 v[210:213], v149 offset:2048
	ds_read_b128 v[214:217], v149 offset:3072
	global_load_lds_dwordx4 v[218:219], off
	v_lshl_add_u64 v[218:219], v[220:221], 0, s[10:11]
	s_add_i32 m0, s23, 0x2000
	s_nop 0
	global_load_lds_dwordx4 v[218:219], off
	s_barrier
	s_waitcnt lgkmcnt(0)
	s_waitcnt lgkmcnt(0)
	v_mfma_f32_16x16x32_bf16 v[118:121], v[202:205], v[166:169], v[118:121]
	v_mfma_f32_16x16x32_bf16 v[114:117], v[210:213], v[166:169], v[114:117]
	v_mfma_f32_16x16x32_bf16 v[102:105], v[202:205], v[174:177], v[102:105]
	v_mfma_f32_16x16x32_bf16 v[98:101], v[210:213], v[174:177], v[98:101]
	v_mfma_f32_16x16x32_bf16 v[86:89], v[202:205], v[186:189], v[86:89]
	v_mfma_f32_16x16x32_bf16 v[82:85], v[210:213], v[186:189], v[82:85]
	v_mfma_f32_16x16x32_bf16 v[70:73], v[202:205], v[194:197], v[70:73]
	v_mfma_f32_16x16x32_bf16 v[66:69], v[210:213], v[194:197], v[66:69]
	v_mfma_f32_16x16x32_bf16 v[118:121], v[206:209], v[170:173], v[118:121]
	v_mfma_f32_16x16x32_bf16 v[114:117], v[214:217], v[170:173], v[114:117]
	v_mfma_f32_16x16x32_bf16 v[102:105], v[206:209], v[182:185], v[102:105]
	v_mfma_f32_16x16x32_bf16 v[98:101], v[214:217], v[182:185], v[98:101]
	v_mfma_f32_16x16x32_bf16 v[86:89], v[206:209], v[190:193], v[86:89]
	v_mfma_f32_16x16x32_bf16 v[82:85], v[214:217], v[190:193], v[82:85]
	v_mfma_f32_16x16x32_bf16 v[70:73], v[206:209], v[198:201], v[70:73]
	v_mfma_f32_16x16x32_bf16 v[66:69], v[214:217], v[198:201], v[66:69]
	s_mov_b32 m0, s38
	v_lshl_add_u64 v[218:219], v[222:223], 0, s[10:11]
	s_barrier
	ds_read_b128 v[166:169], v148 offset:49152
	ds_read_b128 v[170:173], v148 offset:50176
	ds_read_b128 v[174:177], v148 offset:51200
	ds_read_b128 v[182:185], v148 offset:52224
	ds_read_b128 v[186:189], v148 offset:53248
	ds_read_b128 v[190:193], v148 offset:54272
	ds_read_b128 v[194:197], v148 offset:55296
	ds_read_b128 v[198:201], v148 offset:56320
	global_load_lds_dwordx4 v[218:219], off
	v_lshl_add_u64 v[218:219], v[224:225], 0, s[10:11]
	s_mov_b32 m0, s39
	s_nop 0
	global_load_lds_dwordx4 v[218:219], off
	s_barrier
	s_waitcnt lgkmcnt(0)
	s_waitcnt lgkmcnt(0)
	v_mfma_f32_16x16x32_bf16 v[62:65], v[150:153], v[166:169], v[62:65]
	v_mfma_f32_16x16x32_bf16 v[58:61], v[158:161], v[166:169], v[58:61]
	v_mfma_f32_16x16x32_bf16 v[46:49], v[150:153], v[174:177], v[46:49]
	v_mfma_f32_16x16x32_bf16 v[42:45], v[158:161], v[174:177], v[42:45]
	v_mfma_f32_16x16x32_bf16 v[30:33], v[150:153], v[186:189], v[30:33]
	v_mfma_f32_16x16x32_bf16 v[26:29], v[158:161], v[186:189], v[26:29]
	v_mfma_f32_16x16x32_bf16 v[14:17], v[150:153], v[194:197], v[14:17]
	v_mfma_f32_16x16x32_bf16 v[10:13], v[158:161], v[194:197], v[10:13]
	v_mfma_f32_16x16x32_bf16 v[62:65], v[154:157], v[170:173], v[62:65]
	v_mfma_f32_16x16x32_bf16 v[58:61], v[162:165], v[170:173], v[58:61]
	v_mfma_f32_16x16x32_bf16 v[46:49], v[154:157], v[182:185], v[46:49]
	v_mfma_f32_16x16x32_bf16 v[42:45], v[162:165], v[182:185], v[42:45]
	v_mfma_f32_16x16x32_bf16 v[30:33], v[154:157], v[190:193], v[30:33]
	v_mfma_f32_16x16x32_bf16 v[26:29], v[162:165], v[190:193], v[26:29]
	v_mfma_f32_16x16x32_bf16 v[14:17], v[154:157], v[198:201], v[14:17]
	v_mfma_f32_16x16x32_bf16 v[10:13], v[162:165], v[198:201], v[10:13]
	s_barrier
	s_add_u32 s20, s20, 0xb0080
	s_addc_u32 s21, s21, 0
	s_add_i32 s22, s22, s30
	v_lshl_add_u64 v[150:151], s[20:21], 0, v[130:131]
	s_mov_b32 m0, s22
	s_nop 0
	global_load_lds_dwordx4 v[150:151], off
	v_lshl_add_u64 v[150:151], s[20:21], 0, v[132:133]
	s_add_i32 m0, s22, 0x2000
	s_nop 0
	global_load_lds_dwordx4 v[150:151], off
	s_waitcnt vmcnt(6)
	s_barrier
	v_mfma_f32_16x16x32_bf16 v[54:57], v[202:205], v[166:169], v[54:57]
	v_mfma_f32_16x16x32_bf16 v[50:53], v[210:213], v[166:169], v[50:53]
	v_mfma_f32_16x16x32_bf16 v[38:41], v[202:205], v[174:177], v[38:41]
	v_mfma_f32_16x16x32_bf16 v[34:37], v[210:213], v[174:177], v[34:37]
	v_mfma_f32_16x16x32_bf16 v[22:25], v[202:205], v[186:189], v[22:25]
	v_mfma_f32_16x16x32_bf16 v[18:21], v[210:213], v[186:189], v[18:21]
	v_mfma_f32_16x16x32_bf16 v[6:9], v[202:205], v[194:197], v[6:9]
	v_mfma_f32_16x16x32_bf16 v[2:5], v[210:213], v[194:197], v[2:5]
	v_mfma_f32_16x16x32_bf16 v[54:57], v[206:209], v[170:173], v[54:57]
	v_mfma_f32_16x16x32_bf16 v[50:53], v[214:217], v[170:173], v[50:53]
	v_mfma_f32_16x16x32_bf16 v[38:41], v[206:209], v[182:185], v[38:41]
	v_mfma_f32_16x16x32_bf16 v[34:37], v[214:217], v[182:185], v[34:37]
	v_mfma_f32_16x16x32_bf16 v[22:25], v[206:209], v[190:193], v[22:25]
	v_mfma_f32_16x16x32_bf16 v[18:21], v[214:217], v[190:193], v[18:21]
	v_mfma_f32_16x16x32_bf16 v[6:9], v[206:209], v[198:201], v[6:9]
	v_mfma_f32_16x16x32_bf16 v[2:5], v[214:217], v[198:201], v[2:5]
	s_add_i32 s47, s47, 2
	s_add_u32 s18, s18, 0x100
	s_addc_u32 s19, s19, 0
	s_cmp_gt_u32 s47, 41
	s_barrier
	s_cbranch_scc0 .LBB0_2514
	s_add_u32 s18, s45, 0xffffff00
	s_addc_u32 s19, s46, -1
	s_and_b64 vcc, exec, s[6:7]
	s_cbranch_vccnz .LBB0_2501
	v_mov_b32_e32 v2, 0
	s_mov_b32 s2, s42
	s_mov_b32 s26, s43
	s_mov_b64 s[8:9], s[16:17]
	s_mov_b32 s37, s44
	v_mov_b32_e32 v3, v2
	v_mov_b32_e32 v4, v2
	v_mov_b32_e32 v5, v2
	v_mov_b32_e32 v6, v2
	v_mov_b32_e32 v7, v2
	v_mov_b32_e32 v8, v2
	v_mov_b32_e32 v9, v2
	v_mov_b32_e32 v18, v2
	v_mov_b32_e32 v19, v2
	v_mov_b32_e32 v20, v2
	v_mov_b32_e32 v21, v2
	v_mov_b32_e32 v22, v2
	v_mov_b32_e32 v23, v2
	v_mov_b32_e32 v24, v2
	v_mov_b32_e32 v25, v2
	v_mov_b32_e32 v34, v2
	v_mov_b32_e32 v35, v2
	v_mov_b32_e32 v36, v2
	v_mov_b32_e32 v37, v2
	v_mov_b32_e32 v38, v2
	v_mov_b32_e32 v39, v2
	v_mov_b32_e32 v40, v2
	v_mov_b32_e32 v41, v2
	v_mov_b32_e32 v50, v2
	v_mov_b32_e32 v51, v2
	v_mov_b32_e32 v52, v2
	v_mov_b32_e32 v53, v2
	v_mov_b32_e32 v54, v2
	v_mov_b32_e32 v55, v2
	v_mov_b32_e32 v56, v2
	v_mov_b32_e32 v57, v2
	v_mov_b32_e32 v10, v2
	v_mov_b32_e32 v11, v2
	v_mov_b32_e32 v12, v2
	v_mov_b32_e32 v13, v2
	v_mov_b32_e32 v14, v2
	v_mov_b32_e32 v15, v2
	v_mov_b32_e32 v16, v2
	v_mov_b32_e32 v17, v2
	v_mov_b32_e32 v26, v2
	v_mov_b32_e32 v27, v2
	v_mov_b32_e32 v28, v2
	v_mov_b32_e32 v29, v2
	v_mov_b32_e32 v30, v2
	v_mov_b32_e32 v31, v2
	v_mov_b32_e32 v32, v2
	v_mov_b32_e32 v33, v2
	v_mov_b32_e32 v42, v2
	v_mov_b32_e32 v43, v2
	v_mov_b32_e32 v44, v2
	v_mov_b32_e32 v45, v2
	v_mov_b32_e32 v46, v2
	v_mov_b32_e32 v47, v2
	v_mov_b32_e32 v48, v2
	v_mov_b32_e32 v49, v2
	v_mov_b32_e32 v58, v2
	v_mov_b32_e32 v59, v2
	v_mov_b32_e32 v60, v2
	v_mov_b32_e32 v61, v2
	v_mov_b32_e32 v62, v2
	v_mov_b32_e32 v63, v2
	v_mov_b32_e32 v64, v2
	v_mov_b32_e32 v65, v2
	v_mov_b32_e32 v66, v2
	v_mov_b32_e32 v67, v2
	v_mov_b32_e32 v68, v2
	v_mov_b32_e32 v69, v2
	v_mov_b32_e32 v70, v2
	v_mov_b32_e32 v71, v2
	v_mov_b32_e32 v72, v2
	v_mov_b32_e32 v73, v2
	v_mov_b32_e32 v82, v2
	v_mov_b32_e32 v83, v2
	v_mov_b32_e32 v84, v2
	v_mov_b32_e32 v85, v2
	v_mov_b32_e32 v86, v2
	v_mov_b32_e32 v87, v2
	v_mov_b32_e32 v88, v2
	v_mov_b32_e32 v89, v2
	v_mov_b32_e32 v98, v2
	v_mov_b32_e32 v99, v2
	v_mov_b32_e32 v100, v2
	v_mov_b32_e32 v101, v2
	v_mov_b32_e32 v102, v2
	v_mov_b32_e32 v103, v2
	v_mov_b32_e32 v104, v2
	v_mov_b32_e32 v105, v2
	v_mov_b32_e32 v114, v2
	v_mov_b32_e32 v115, v2
	v_mov_b32_e32 v116, v2
	v_mov_b32_e32 v117, v2
	v_mov_b32_e32 v118, v2
	v_mov_b32_e32 v119, v2
	v_mov_b32_e32 v120, v2
	v_mov_b32_e32 v121, v2
	v_mov_b32_e32 v74, v2
	v_mov_b32_e32 v75, v2
	v_mov_b32_e32 v76, v2
	v_mov_b32_e32 v77, v2
	v_mov_b32_e32 v78, v2
	v_mov_b32_e32 v79, v2
	v_mov_b32_e32 v80, v2
	v_mov_b32_e32 v81, v2
	v_mov_b32_e32 v90, v2
	v_mov_b32_e32 v91, v2
	v_mov_b32_e32 v92, v2
	v_mov_b32_e32 v93, v2
	v_mov_b32_e32 v94, v2
	v_mov_b32_e32 v95, v2
	v_mov_b32_e32 v96, v2
	v_mov_b32_e32 v97, v2
	v_mov_b32_e32 v106, v2
	v_mov_b32_e32 v107, v2
	v_mov_b32_e32 v108, v2
	v_mov_b32_e32 v109, v2
	v_mov_b32_e32 v110, v2
	v_mov_b32_e32 v111, v2
	v_mov_b32_e32 v112, v2
	v_mov_b32_e32 v113, v2
	v_mov_b32_e32 v122, v2
	v_mov_b32_e32 v123, v2
	v_mov_b32_e32 v124, v2
	v_mov_b32_e32 v125, v2
	v_mov_b32_e32 v126, v2
	v_mov_b32_e32 v127, v2
	v_mov_b32_e32 v128, v2
	v_mov_b32_e32 v129, v2
	s_andn2_b64 vcc, exec, s[4:5]
	s_cbranch_vccnz .LBB0_2502

.LBB0_2767:
	s_load_dwordx16 s[80:95], s[78:79], 0x1e0
	s_and_b64 s[22:23], s[22:23], exec
	v_mov_b32_e32 v2, 0
	s_mov_b32 s24, -2
	v_mov_b32_e32 v3, v2
	s_waitcnt lgkmcnt(0)
	s_cselect_b32 s7, s95, s93
	s_cselect_b32 s12, s94, s92
	s_ashr_i32 s19, s18, 31
	s_lshl_b64 s[22:23], s[18:19], 19
	s_add_u32 s22, s12, s22
	s_addc_u32 s23, s7, s23
	s_and_b64 s[0:1], s[0:1], exec
	s_cselect_b32 s7, s23, s9
	s_cselect_b32 s12, s22, s8
	s_add_u32 s0, s8, 0x40080
	s_addc_u32 s1, s9, 0
	s_add_u32 s17, s10, 0x100
	s_addc_u32 s19, s11, 0
	v_mov_b32_e32 v4, v2
	v_mov_b32_e32 v5, v2
	v_mov_b32_e32 v6, v2
	v_mov_b32_e32 v7, v2
	v_mov_b32_e32 v8, v2
	v_mov_b32_e32 v9, v2
	v_mov_b32_e32 v18, v2
	v_mov_b32_e32 v19, v2
	v_mov_b32_e32 v20, v2
	v_mov_b32_e32 v21, v2
	v_mov_b32_e32 v22, v2
	v_mov_b32_e32 v23, v2
	v_mov_b32_e32 v24, v2
	v_mov_b32_e32 v25, v2
	v_mov_b32_e32 v34, v2
	v_mov_b32_e32 v35, v2
	v_mov_b32_e32 v36, v2
	v_mov_b32_e32 v37, v2
	v_mov_b32_e32 v38, v2
	v_mov_b32_e32 v39, v2
	v_mov_b32_e32 v40, v2
	v_mov_b32_e32 v41, v2
	v_mov_b32_e32 v50, v2
	v_mov_b32_e32 v51, v2
	v_mov_b32_e32 v52, v2
	v_mov_b32_e32 v53, v2
	v_mov_b32_e32 v54, v2
	v_mov_b32_e32 v55, v2
	v_mov_b32_e32 v56, v2
	v_mov_b32_e32 v57, v2
	v_mov_b32_e32 v10, v2
	v_mov_b32_e32 v11, v2
	v_mov_b32_e32 v12, v2
	v_mov_b32_e32 v13, v2
	v_mov_b32_e32 v14, v2
	v_mov_b32_e32 v15, v2
	v_mov_b32_e32 v16, v2
	v_mov_b32_e32 v17, v2
	v_mov_b32_e32 v26, v2
	v_mov_b32_e32 v27, v2
	v_mov_b32_e32 v28, v2
	v_mov_b32_e32 v29, v2
	v_mov_b32_e32 v30, v2
	v_mov_b32_e32 v31, v2
	v_mov_b32_e32 v32, v2
	v_mov_b32_e32 v33, v2
	v_mov_b32_e32 v42, v2
	v_mov_b32_e32 v43, v2
	v_mov_b32_e32 v44, v2
	v_mov_b32_e32 v45, v2
	v_mov_b32_e32 v46, v2
	v_mov_b32_e32 v47, v2
	v_mov_b32_e32 v48, v2
	v_mov_b32_e32 v49, v2
	v_mov_b32_e32 v58, v2
	v_mov_b32_e32 v59, v2
	v_mov_b32_e32 v60, v2
	v_mov_b32_e32 v61, v2
	v_mov_b32_e32 v62, v2
	v_mov_b32_e32 v63, v2
	v_mov_b32_e32 v64, v2
	v_mov_b32_e32 v65, v2
	v_mov_b32_e32 v66, v2
	v_mov_b32_e32 v67, v2
	v_mov_b32_e32 v68, v2
	v_mov_b32_e32 v69, v2
	v_mov_b32_e32 v70, v2
	v_mov_b32_e32 v71, v2
	v_mov_b32_e32 v72, v2
	v_mov_b32_e32 v73, v2
	v_mov_b32_e32 v82, v2
	v_mov_b32_e32 v83, v2
	v_mov_b32_e32 v84, v2
	v_mov_b32_e32 v85, v2
	v_mov_b32_e32 v86, v2
	v_mov_b32_e32 v87, v2
	v_mov_b32_e32 v88, v2
	v_mov_b32_e32 v89, v2
	v_mov_b32_e32 v98, v2
	v_mov_b32_e32 v99, v2
	v_mov_b32_e32 v100, v2
	v_mov_b32_e32 v101, v2
	v_mov_b32_e32 v102, v2
	v_mov_b32_e32 v103, v2
	v_mov_b32_e32 v104, v2
	v_mov_b32_e32 v105, v2
	v_mov_b32_e32 v114, v2
	v_mov_b32_e32 v115, v2
	v_mov_b32_e32 v116, v2
	v_mov_b32_e32 v117, v2
	v_mov_b32_e32 v118, v2
	v_mov_b32_e32 v119, v2
	v_mov_b32_e32 v120, v2
	v_mov_b32_e32 v121, v2
	v_mov_b32_e32 v74, v2
	v_mov_b32_e32 v75, v2
	v_mov_b32_e32 v76, v2
	v_mov_b32_e32 v77, v2
	v_mov_b32_e32 v78, v2
	v_mov_b32_e32 v79, v2
	v_mov_b32_e32 v80, v2
	v_mov_b32_e32 v81, v2
	v_mov_b32_e32 v90, v2
	v_mov_b32_e32 v91, v2
	v_mov_b32_e32 v92, v2
	v_mov_b32_e32 v93, v2
	v_mov_b32_e32 v94, v2
	v_mov_b32_e32 v95, v2
	v_mov_b32_e32 v96, v2
	v_mov_b32_e32 v97, v2
	v_mov_b32_e32 v106, v2
	v_mov_b32_e32 v107, v2
	v_mov_b32_e32 v108, v2
	v_mov_b32_e32 v109, v2
	v_mov_b32_e32 v110, v2
	v_mov_b32_e32 v111, v2
	v_mov_b32_e32 v112, v2
	v_mov_b32_e32 v113, v2
	v_mov_b32_e32 v122, v2
	v_mov_b32_e32 v123, v2
	v_mov_b32_e32 v124, v2
	v_mov_b32_e32 v125, v2
	v_mov_b32_e32 v126, v2
	v_mov_b32_e32 v127, v2
	v_mov_b32_e32 v128, v2
	v_mov_b32_e32 v129, v2
	v_readfirstlane_b32 s98, v248
	s_cmpk_lt_u32 s98, 0x100
	s_cbranch_scc0 .Lmy_lprio5
	s_setprio 1
.Lmy_lprio5:
.LBB0_2768:
	ds_read_b128 v[148:151], v173
	ds_read_b128 v[152:155], v173 offset:1024
	ds_read_b128 v[156:159], v173 offset:2048
	ds_read_b128 v[160:163], v173 offset:3072
	s_add_u32 s8, s0, 0xfffc0080
	s_addc_u32 s9, s1, -1
	s_cmp_eq_u32 s24, 12
	s_cselect_b32 s11, s7, s9
	s_cselect_b32 s10, s12, s8
	s_cselect_b32 s9, s21, s19
	s_cselect_b32 s8, s20, s17
	v_lshl_add_u64 v[206:207], s[0:1], 0, v[140:141]
	s_add_i32 m0, s42, 0xc000
	ds_read_b128 v[164:167], v174
	ds_read_b128 v[168:171], v174 offset:1024
	ds_read_b128 v[182:185], v174 offset:2048
	ds_read_b128 v[186:189], v174 offset:3072
	ds_read_b128 v[190:193], v174 offset:4096
	ds_read_b128 v[194:197], v174 offset:5120
	ds_read_b128 v[198:201], v174 offset:6144
	ds_read_b128 v[202:205], v174 offset:7168
	global_load_lds_dwordx4 v[206:207], off
	v_lshl_add_u64 v[206:207], s[0:1], 0, v[142:143]
	s_add_i32 m0, s42, 0xe000
	s_nop 0
	global_load_lds_dwordx4 v[206:207], off
	s_waitcnt lgkmcnt(8)
	s_barrier
	s_waitcnt lgkmcnt(0)
	s_waitcnt lgkmcnt(0)
	v_mfma_f32_16x16x32_bf16 v[126:129], v[148:151], v[164:167], v[126:129]
	v_mfma_f32_16x16x32_bf16 v[122:125], v[156:159], v[164:167], v[122:125]
	v_mfma_f32_16x16x32_bf16 v[110:113], v[148:151], v[182:185], v[110:113]
	v_mfma_f32_16x16x32_bf16 v[106:109], v[156:159], v[182:185], v[106:109]
	v_mfma_f32_16x16x32_bf16 v[94:97], v[148:151], v[190:193], v[94:97]
	v_mfma_f32_16x16x32_bf16 v[90:93], v[156:159], v[190:193], v[90:93]
	v_mfma_f32_16x16x32_bf16 v[78:81], v[148:151], v[198:201], v[78:81]
	v_mfma_f32_16x16x32_bf16 v[74:77], v[156:159], v[198:201], v[74:77]
	v_mfma_f32_16x16x32_bf16 v[126:129], v[152:155], v[168:171], v[126:129]
	v_mfma_f32_16x16x32_bf16 v[122:125], v[160:163], v[168:171], v[122:125]
	v_mfma_f32_16x16x32_bf16 v[110:113], v[152:155], v[186:189], v[110:113]
	v_mfma_f32_16x16x32_bf16 v[106:109], v[160:163], v[186:189], v[106:109]
	v_mfma_f32_16x16x32_bf16 v[94:97], v[152:155], v[194:197], v[94:97]
	v_mfma_f32_16x16x32_bf16 v[90:93], v[160:163], v[194:197], v[90:93]
	v_mfma_f32_16x16x32_bf16 v[78:81], v[152:155], v[202:205], v[78:81]
	v_mfma_f32_16x16x32_bf16 v[74:77], v[160:163], v[202:205], v[74:77]
	s_barrier
	s_add_i32 s25, s52, s41
	v_lshl_add_u64 v[222:223], s[8:9], 0, v[130:131]
	s_mov_b32 m0, s25
	ds_read_b128 v[206:209], v175
	ds_read_b128 v[210:213], v175 offset:1024
	ds_read_b128 v[214:217], v175 offset:2048
	ds_read_b128 v[218:221], v175 offset:3072
	global_load_lds_dwordx4 v[222:223], off
	v_lshl_add_u64 v[224:225], s[8:9], 0, v[132:133]
	s_add_i32 m0, s25, 0x2000
	s_nop 0
	global_load_lds_dwordx4 v[224:225], off
	s_barrier
	s_waitcnt lgkmcnt(0)
	s_waitcnt lgkmcnt(0)
	v_mfma_f32_16x16x32_bf16 v[118:121], v[206:209], v[164:167], v[118:121]
	v_mfma_f32_16x16x32_bf16 v[114:117], v[214:217], v[164:167], v[114:117]
	v_mfma_f32_16x16x32_bf16 v[102:105], v[206:209], v[182:185], v[102:105]
	v_mfma_f32_16x16x32_bf16 v[98:101], v[214:217], v[182:185], v[98:101]
	v_mfma_f32_16x16x32_bf16 v[86:89], v[206:209], v[190:193], v[86:89]
	v_mfma_f32_16x16x32_bf16 v[82:85], v[214:217], v[190:193], v[82:85]
	v_mfma_f32_16x16x32_bf16 v[70:73], v[206:209], v[198:201], v[70:73]
	v_mfma_f32_16x16x32_bf16 v[66:69], v[214:217], v[198:201], v[66:69]
	v_mfma_f32_16x16x32_bf16 v[118:121], v[210:213], v[168:171], v[118:121]
	v_mfma_f32_16x16x32_bf16 v[114:117], v[218:221], v[168:171], v[114:117]
	v_mfma_f32_16x16x32_bf16 v[102:105], v[210:213], v[186:189], v[102:105]
	v_mfma_f32_16x16x32_bf16 v[98:101], v[218:221], v[186:189], v[98:101]
	v_mfma_f32_16x16x32_bf16 v[86:89], v[210:213], v[194:197], v[86:89]
	v_mfma_f32_16x16x32_bf16 v[82:85], v[218:221], v[194:197], v[82:85]
	v_mfma_f32_16x16x32_bf16 v[70:73], v[210:213], v[202:205], v[70:73]
	v_mfma_f32_16x16x32_bf16 v[66:69], v[218:221], v[202:205], v[66:69]
	s_mov_b32 m0, s42
	v_lshl_add_u64 v[228:229], s[10:11], 0, v[130:131]
	s_barrier
	ds_read_b128 v[164:167], v174 offset:16384
	ds_read_b128 v[168:171], v174 offset:17408
	ds_read_b128 v[182:185], v174 offset:18432
	ds_read_b128 v[186:189], v174 offset:19456
	ds_read_b128 v[190:193], v174 offset:20480
	ds_read_b128 v[194:197], v174 offset:21504
	ds_read_b128 v[198:201], v174 offset:22528
	ds_read_b128 v[202:205], v174 offset:23552
	global_load_lds_dwordx4 v[228:229], off
	v_lshl_add_u64 v[230:231], s[10:11], 0, v[132:133]
	s_mov_b32 m0, s43
	s_nop 0
	global_load_lds_dwordx4 v[230:231], off
	s_barrier
	s_waitcnt lgkmcnt(0)
	s_waitcnt lgkmcnt(0)
	v_mfma_f32_16x16x32_bf16 v[62:65], v[148:151], v[164:167], v[62:65]
	v_mfma_f32_16x16x32_bf16 v[58:61], v[156:159], v[164:167], v[58:61]
	v_mfma_f32_16x16x32_bf16 v[46:49], v[148:151], v[182:185], v[46:49]
	v_mfma_f32_16x16x32_bf16 v[42:45], v[156:159], v[182:185], v[42:45]
	v_mfma_f32_16x16x32_bf16 v[30:33], v[148:151], v[190:193], v[30:33]
	v_mfma_f32_16x16x32_bf16 v[26:29], v[156:159], v[190:193], v[26:29]
	v_mfma_f32_16x16x32_bf16 v[14:17], v[148:151], v[198:201], v[14:17]
	v_mfma_f32_16x16x32_bf16 v[10:13], v[156:159], v[198:201], v[10:13]
	v_mfma_f32_16x16x32_bf16 v[62:65], v[152:155], v[168:171], v[62:65]
	v_mfma_f32_16x16x32_bf16 v[58:61], v[160:163], v[168:171], v[58:61]
	v_mfma_f32_16x16x32_bf16 v[46:49], v[152:155], v[186:189], v[46:49]
	v_mfma_f32_16x16x32_bf16 v[42:45], v[160:163], v[186:189], v[42:45]
	v_mfma_f32_16x16x32_bf16 v[30:33], v[152:155], v[194:197], v[30:33]
	v_mfma_f32_16x16x32_bf16 v[26:29], v[160:163], v[194:197], v[26:29]
	v_mfma_f32_16x16x32_bf16 v[14:17], v[152:155], v[202:205], v[14:17]
	v_mfma_f32_16x16x32_bf16 v[10:13], v[160:163], v[202:205], v[10:13]
	s_barrier
	s_add_u32 s26, s8, 0x40000
	s_addc_u32 s27, s9, 0
	s_add_i32 s25, s53, s41
	v_lshl_add_u64 v[148:149], s[26:27], 0, v[130:131]
	s_mov_b32 m0, s25
	s_nop 0
	global_load_lds_dwordx4 v[148:149], off
	v_lshl_add_u64 v[148:149], s[26:27], 0, v[132:133]
	s_add_i32 m0, s25, 0x2000
	s_nop 0
	global_load_lds_dwordx4 v[148:149], off
	s_waitcnt vmcnt(6)
	s_barrier
	v_mfma_f32_16x16x32_bf16 v[54:57], v[206:209], v[164:167], v[54:57]
	v_mfma_f32_16x16x32_bf16 v[50:53], v[214:217], v[164:167], v[50:53]
	v_mfma_f32_16x16x32_bf16 v[38:41], v[206:209], v[182:185], v[38:41]
	v_mfma_f32_16x16x32_bf16 v[34:37], v[214:217], v[182:185], v[34:37]
	v_mfma_f32_16x16x32_bf16 v[22:25], v[206:209], v[190:193], v[22:25]
	v_mfma_f32_16x16x32_bf16 v[18:21], v[214:217], v[190:193], v[18:21]
	v_mfma_f32_16x16x32_bf16 v[6:9], v[206:209], v[198:201], v[6:9]
	v_mfma_f32_16x16x32_bf16 v[2:5], v[214:217], v[198:201], v[2:5]
	v_mfma_f32_16x16x32_bf16 v[54:57], v[210:213], v[168:171], v[54:57]
	v_mfma_f32_16x16x32_bf16 v[50:53], v[218:221], v[168:171], v[50:53]
	v_mfma_f32_16x16x32_bf16 v[38:41], v[210:213], v[186:189], v[38:41]
	v_mfma_f32_16x16x32_bf16 v[34:37], v[218:221], v[186:189], v[34:37]
	v_mfma_f32_16x16x32_bf16 v[22:25], v[210:213], v[194:197], v[22:25]
	v_mfma_f32_16x16x32_bf16 v[18:21], v[218:221], v[194:197], v[18:21]
	v_mfma_f32_16x16x32_bf16 v[6:9], v[210:213], v[202:205], v[6:9]
	v_mfma_f32_16x16x32_bf16 v[2:5], v[218:221], v[202:205], v[2:5]
	s_add_i32 s25, 0, 0x18000
	v_add_u32_e32 v134, s25, v172
	s_barrier
	ds_read_b128 v[148:151], v134
	ds_read_b128 v[152:155], v134 offset:1024
	ds_read_b128 v[156:159], v134 offset:2048
	ds_read_b128 v[160:163], v134 offset:3072
	s_add_u32 s10, s10, 0x40000
	s_addc_u32 s11, s11, 0
	s_mov_b32 m0, s44
	v_lshl_add_u64 v[206:207], s[10:11], 0, v[130:131]
	ds_read_b128 v[164:167], v174 offset:32768
	ds_read_b128 v[168:171], v174 offset:33792
	ds_read_b128 v[182:185], v174 offset:34816
	ds_read_b128 v[186:189], v174 offset:35840
	ds_read_b128 v[190:193], v174 offset:36864
	ds_read_b128 v[194:197], v174 offset:37888
	ds_read_b128 v[198:201], v174 offset:38912
	ds_read_b128 v[202:205], v174 offset:39936
	global_load_lds_dwordx4 v[206:207], off
	v_lshl_add_u64 v[206:207], s[10:11], 0, v[132:133]
	s_mov_b32 m0, s45
	s_nop 0
	global_load_lds_dwordx4 v[206:207], off
	s_waitcnt lgkmcnt(8)
	s_barrier
	s_waitcnt lgkmcnt(0)
	s_waitcnt lgkmcnt(0)
	v_mfma_f32_16x16x32_bf16 v[126:129], v[148:151], v[164:167], v[126:129]
	v_mfma_f32_16x16x32_bf16 v[122:125], v[156:159], v[164:167], v[122:125]
	v_mfma_f32_16x16x32_bf16 v[110:113], v[148:151], v[182:185], v[110:113]
	v_mfma_f32_16x16x32_bf16 v[106:109], v[156:159], v[182:185], v[106:109]
	v_mfma_f32_16x16x32_bf16 v[94:97], v[148:151], v[190:193], v[94:97]
	v_mfma_f32_16x16x32_bf16 v[90:93], v[156:159], v[190:193], v[90:93]
	v_mfma_f32_16x16x32_bf16 v[78:81], v[148:151], v[198:201], v[78:81]
	v_mfma_f32_16x16x32_bf16 v[74:77], v[156:159], v[198:201], v[74:77]
	v_mfma_f32_16x16x32_bf16 v[126:129], v[152:155], v[168:171], v[126:129]
	v_mfma_f32_16x16x32_bf16 v[122:125], v[160:163], v[168:171], v[122:125]
	v_mfma_f32_16x16x32_bf16 v[110:113], v[152:155], v[186:189], v[110:113]
	v_mfma_f32_16x16x32_bf16 v[106:109], v[160:163], v[186:189], v[106:109]
	v_mfma_f32_16x16x32_bf16 v[94:97], v[152:155], v[194:197], v[94:97]
	v_mfma_f32_16x16x32_bf16 v[90:93], v[160:163], v[194:197], v[90:93]
	v_mfma_f32_16x16x32_bf16 v[78:81], v[152:155], v[202:205], v[78:81]
	v_mfma_f32_16x16x32_bf16 v[74:77], v[160:163], v[202:205], v[74:77]
	s_barrier
	s_add_i32 s10, 0, 0x1c000
	s_add_i32 s11, s25, s41
	v_add_u32_e32 v134, s10, v172
	v_lshl_add_u64 v[222:223], v[222:223], 0, s[14:15]
	s_mov_b32 m0, s11
	ds_read_b128 v[206:209], v134
	ds_read_b128 v[210:213], v134 offset:1024
	ds_read_b128 v[214:217], v134 offset:2048
	ds_read_b128 v[218:221], v134 offset:3072
	global_load_lds_dwordx4 v[222:223], off
	v_lshl_add_u64 v[222:223], v[224:225], 0, s[14:15]
	s_add_i32 m0, s11, 0x2000
	s_nop 0
	global_load_lds_dwordx4 v[222:223], off
	s_barrier
	s_waitcnt lgkmcnt(0)
	s_waitcnt lgkmcnt(0)
	v_mfma_f32_16x16x32_bf16 v[118:121], v[206:209], v[164:167], v[118:121]
	v_mfma_f32_16x16x32_bf16 v[114:117], v[214:217], v[164:167], v[114:117]
	v_mfma_f32_16x16x32_bf16 v[102:105], v[206:209], v[182:185], v[102:105]
	v_mfma_f32_16x16x32_bf16 v[98:101], v[214:217], v[182:185], v[98:101]
	v_mfma_f32_16x16x32_bf16 v[86:89], v[206:209], v[190:193], v[86:89]
	v_mfma_f32_16x16x32_bf16 v[82:85], v[214:217], v[190:193], v[82:85]
	v_mfma_f32_16x16x32_bf16 v[70:73], v[206:209], v[198:201], v[70:73]
	v_mfma_f32_16x16x32_bf16 v[66:69], v[214:217], v[198:201], v[66:69]
	v_mfma_f32_16x16x32_bf16 v[118:121], v[210:213], v[168:171], v[118:121]
	v_mfma_f32_16x16x32_bf16 v[114:117], v[218:221], v[168:171], v[114:117]
	v_mfma_f32_16x16x32_bf16 v[102:105], v[210:213], v[186:189], v[102:105]
	v_mfma_f32_16x16x32_bf16 v[98:101], v[218:221], v[186:189], v[98:101]
	v_mfma_f32_16x16x32_bf16 v[86:89], v[210:213], v[194:197], v[86:89]
	v_mfma_f32_16x16x32_bf16 v[82:85], v[218:221], v[194:197], v[82:85]
	v_mfma_f32_16x16x32_bf16 v[70:73], v[210:213], v[202:205], v[70:73]
	v_mfma_f32_16x16x32_bf16 v[66:69], v[218:221], v[202:205], v[66:69]
	s_mov_b32 m0, s47
	v_lshl_add_u64 v[222:223], v[228:229], 0, s[14:15]
	s_barrier
	ds_read_b128 v[164:167], v174 offset:49152
	ds_read_b128 v[168:171], v174 offset:50176
	ds_read_b128 v[182:185], v174 offset:51200
	ds_read_b128 v[186:189], v174 offset:52224
	ds_read_b128 v[190:193], v174 offset:53248
	ds_read_b128 v[194:197], v174 offset:54272
	ds_read_b128 v[198:201], v174 offset:55296
	ds_read_b128 v[202:205], v174 offset:56320
	global_load_lds_dwordx4 v[222:223], off
	v_lshl_add_u64 v[222:223], v[230:231], 0, s[14:15]
	s_mov_b32 m0, s48
	s_nop 0
	global_load_lds_dwordx4 v[222:223], off
	s_barrier
	s_waitcnt lgkmcnt(0)
	s_waitcnt lgkmcnt(0)
	v_mfma_f32_16x16x32_bf16 v[62:65], v[148:151], v[164:167], v[62:65]
	v_mfma_f32_16x16x32_bf16 v[58:61], v[156:159], v[164:167], v[58:61]
	v_mfma_f32_16x16x32_bf16 v[46:49], v[148:151], v[182:185], v[46:49]
	v_mfma_f32_16x16x32_bf16 v[42:45], v[156:159], v[182:185], v[42:45]
	v_mfma_f32_16x16x32_bf16 v[30:33], v[148:151], v[190:193], v[30:33]
	v_mfma_f32_16x16x32_bf16 v[26:29], v[156:159], v[190:193], v[26:29]
	v_mfma_f32_16x16x32_bf16 v[14:17], v[148:151], v[198:201], v[14:17]
	v_mfma_f32_16x16x32_bf16 v[10:13], v[156:159], v[198:201], v[10:13]
	v_mfma_f32_16x16x32_bf16 v[62:65], v[152:155], v[168:171], v[62:65]
	v_mfma_f32_16x16x32_bf16 v[58:61], v[160:163], v[168:171], v[58:61]
	v_mfma_f32_16x16x32_bf16 v[46:49], v[152:155], v[186:189], v[46:49]
	v_mfma_f32_16x16x32_bf16 v[42:45], v[160:163], v[186:189], v[42:45]
	v_mfma_f32_16x16x32_bf16 v[30:33], v[152:155], v[194:197], v[30:33]
	v_mfma_f32_16x16x32_bf16 v[26:29], v[160:163], v[194:197], v[26:29]
	v_mfma_f32_16x16x32_bf16 v[14:17], v[152:155], v[202:205], v[14:17]
	v_mfma_f32_16x16x32_bf16 v[10:13], v[160:163], v[202:205], v[10:13]
	s_barrier
	s_add_u32 s8, s8, 0x40080
	s_addc_u32 s9, s9, 0
	s_add_i32 s10, s10, s41
	v_lshl_add_u64 v[148:149], s[8:9], 0, v[130:131]
	s_mov_b32 m0, s10
	s_nop 0
	global_load_lds_dwordx4 v[148:149], off
	v_lshl_add_u64 v[148:149], s[8:9], 0, v[132:133]
	s_add_i32 m0, s10, 0x2000
	s_nop 0
	global_load_lds_dwordx4 v[148:149], off
	s_waitcnt vmcnt(6)
	s_barrier
	v_mfma_f32_16x16x32_bf16 v[54:57], v[206:209], v[164:167], v[54:57]
	v_mfma_f32_16x16x32_bf16 v[50:53], v[214:217], v[164:167], v[50:53]
	v_mfma_f32_16x16x32_bf16 v[38:41], v[206:209], v[182:185], v[38:41]
	v_mfma_f32_16x16x32_bf16 v[34:37], v[214:217], v[182:185], v[34:37]
	v_mfma_f32_16x16x32_bf16 v[22:25], v[206:209], v[190:193], v[22:25]
	v_mfma_f32_16x16x32_bf16 v[18:21], v[214:217], v[190:193], v[18:21]
	v_mfma_f32_16x16x32_bf16 v[6:9], v[206:209], v[198:201], v[6:9]
	v_mfma_f32_16x16x32_bf16 v[2:5], v[214:217], v[198:201], v[2:5]
	v_mfma_f32_16x16x32_bf16 v[54:57], v[210:213], v[168:171], v[54:57]
	v_mfma_f32_16x16x32_bf16 v[50:53], v[218:221], v[168:171], v[50:53]
	v_mfma_f32_16x16x32_bf16 v[38:41], v[210:213], v[186:189], v[38:41]
	v_mfma_f32_16x16x32_bf16 v[34:37], v[218:221], v[186:189], v[34:37]
	v_mfma_f32_16x16x32_bf16 v[22:25], v[210:213], v[194:197], v[22:25]
	v_mfma_f32_16x16x32_bf16 v[18:21], v[218:221], v[194:197], v[18:21]
	v_mfma_f32_16x16x32_bf16 v[6:9], v[210:213], v[202:205], v[6:9]
	v_mfma_f32_16x16x32_bf16 v[2:5], v[218:221], v[202:205], v[2:5]
	s_add_i32 s24, s24, 2
	s_add_u32 s0, s0, 0x100
	s_addc_u32 s1, s1, 0
	s_add_u32 s17, s17, 0x100
	s_addc_u32 s19, s19, 0
	s_cmp_gt_u32 s24, 13
	s_barrier
	s_cbranch_scc0 .LBB0_2768
	s_mov_b64 s[30:31], exec
	s_load_dwordx8 s[80:87], s[78:79], 0x130
	s_load_dwordx4 s[88:91], s[78:79], 0x270
	s_load_dwordx2 s[92:93], s[78:79], 0x280
	s_load_dwordx2 s[94:95], s[78:79], 0x200
	s_load_dwordx2 s[64:65], s[78:79], 0x220
	s_load_dwordx2 s[66:67], s[78:79], 0x1e0
	v_and_b32_e32 v148, 15, v248
	v_bfe_u32 v149, v248, 8, 1
	v_bfe_u32 v150, v248, 6, 2
	v_bfe_u32 v151, v248, 4, 2
	v_lshlrev_b32_e32 v152, 5, v150
	v_lshl_or_b32 v152, v151, 2, v152
	v_lshl_add_u32 v153, v149, 6, v148
	s_lshl_b32 s0, s6, 8
	v_add_u32_e32 v154, s0, v153
	s_cmp_ge_u32 s28, 6
	s_cbranch_scc1 .Lmy_kn_nsa
	s_cmp_ge_u32 s6, 64
	s_cbranch_scc1 .Lmy_kn_smp
	s_cmp_ge_u32 s28, 4
	s_cbranch_scc1 .Lmy_kn_p_bf
	s_lshl_b32 s0, s28, 10
	v_lshlrev_b32_e32 v155, 12, v154
	v_lshl_add_u32 v155, v152, 2, v155
	v_add_u32_e32 v155, s0, v155
	s_waitcnt lgkmcnt(0)
	global_store_dwordx4 v155, v[126:129], s[80:81]
	global_store_dwordx4 v155, v[122:125], s[80:81] offset:64
	global_store_dwordx4 v155, v[118:121], s[80:81] offset:512
	global_store_dwordx4 v155, v[114:117], s[80:81] offset:576
	v_add_u32_e32 v134, 0x10000, v155
	global_store_dwordx4 v134, v[110:113], s[80:81]
	v_add_u32_e32 v134, 0x10040, v155
	global_store_dwordx4 v134, v[106:109], s[80:81]
	v_add_u32_e32 v134, 0x10200, v155
	global_store_dwordx4 v134, v[102:105], s[80:81]
	v_add_u32_e32 v134, 0x10240, v155
	global_store_dwordx4 v134, v[98:101], s[80:81]
	v_add_u32_e32 v134, 0x20000, v155
	global_store_dwordx4 v134, v[94:97], s[80:81]
	v_add_u32_e32 v134, 0x20040, v155
	global_store_dwordx4 v134, v[90:93], s[80:81]
	v_add_u32_e32 v134, 0x20200, v155
	global_store_dwordx4 v134, v[86:89], s[80:81]
	v_add_u32_e32 v134, 0x20240, v155
	global_store_dwordx4 v134, v[82:85], s[80:81]
	v_add_u32_e32 v134, 0x30000, v155
	global_store_dwordx4 v134, v[78:81], s[80:81]
	v_add_u32_e32 v134, 0x30040, v155
	global_store_dwordx4 v134, v[74:77], s[80:81]
	v_add_u32_e32 v134, 0x30200, v155
	global_store_dwordx4 v134, v[70:73], s[80:81]
	v_add_u32_e32 v134, 0x30240, v155
	global_store_dwordx4 v134, v[66:69], s[80:81]
	v_add_u32_e32 v134, 0x80000, v155
	global_store_dwordx4 v134, v[62:65], s[80:81]
	v_add_u32_e32 v134, 0x80040, v155
	global_store_dwordx4 v134, v[58:61], s[80:81]
	v_add_u32_e32 v134, 0x80200, v155
	global_store_dwordx4 v134, v[54:57], s[80:81]
	v_add_u32_e32 v134, 0x80240, v155
	global_store_dwordx4 v134, v[50:53], s[80:81]
	v_add_u32_e32 v134, 0x90000, v155
	global_store_dwordx4 v134, v[46:49], s[80:81]
	v_add_u32_e32 v134, 0x90040, v155
	global_store_dwordx4 v134, v[42:45], s[80:81]
	v_add_u32_e32 v134, 0x90200, v155
	global_store_dwordx4 v134, v[38:41], s[80:81]
	v_add_u32_e32 v134, 0x90240, v155
	global_store_dwordx4 v134, v[34:37], s[80:81]
	v_add_u32_e32 v134, 0xa0000, v155
	global_store_dwordx4 v134, v[30:33], s[80:81]
	v_add_u32_e32 v134, 0xa0040, v155
	global_store_dwordx4 v134, v[26:29], s[80:81]
	v_add_u32_e32 v134, 0xa0200, v155
	global_store_dwordx4 v134, v[22:25], s[80:81]
	v_add_u32_e32 v134, 0xa0240, v155
	global_store_dwordx4 v134, v[18:21], s[80:81]
	v_add_u32_e32 v134, 0xb0000, v155
	global_store_dwordx4 v134, v[14:17], s[80:81]
	v_add_u32_e32 v134, 0xb0040, v155
	global_store_dwordx4 v134, v[10:13], s[80:81]
	v_add_u32_e32 v134, 0xb0200, v155
	global_store_dwordx4 v134, v[6:9], s[80:81]
	v_add_u32_e32 v134, 0xb0240, v155
	global_store_dwordx4 v134, v[2:5], s[80:81]

.LBB0_3963:
	s_load_dwordx16 s[40:55], s[78:79], 0x1e0
	s_ashr_i32 s9, s8, 31
	v_cmp_lt_i64_e64 s[20:21], s[10:11], 16
	s_lshl_b64 s[10:11], s[8:9], 19
	v_mov_b32_e32 v2, 0
	s_waitcnt lgkmcnt(0)
	s_add_u32 s10, s48, s10
	s_addc_u32 s11, s49, s11
	v_readlane_b32 s44, v253, 27
	s_and_b64 s[12:13], s[20:21], exec
	v_readlane_b32 s52, v253, 35
	v_readlane_b32 s53, v253, 36
	v_readlane_b32 s54, v253, 37
	v_readlane_b32 s55, v253, 38
	v_readlane_b32 s56, v253, 39
	v_readlane_b32 s57, v253, 40
	s_cselect_b32 s9, s11, s17
	s_cselect_b32 s40, s10, s16
	s_ashr_i32 s7, s6, 31
	v_readlane_b32 s58, v253, 41
	v_readlane_b32 s59, v253, 42
	s_mov_b64 s[52:53], s[56:57]
	s_lshl_b64 s[12:13], s[6:7], 19
	s_mov_b64 s[54:55], s[58:59]
	s_add_u32 s12, s54, s12
	s_addc_u32 s13, s55, s13
	s_and_b64 s[20:21], s[20:21], exec
	s_cselect_b32 s7, s13, s19
	s_cselect_b32 s41, s12, s18
	s_add_u32 s16, s16, 0x40080
	s_addc_u32 s17, s17, 0
	s_add_u32 s42, s18, 0x100
	s_addc_u32 s43, s19, 0
	s_mov_b32 s44, -2
	v_mov_b32_e32 v3, v2
	v_mov_b32_e32 v4, v2
	v_mov_b32_e32 v5, v2
	v_mov_b32_e32 v6, v2
	v_mov_b32_e32 v7, v2
	v_mov_b32_e32 v8, v2
	v_mov_b32_e32 v9, v2
	v_mov_b32_e32 v14, v2
	v_mov_b32_e32 v15, v2
	v_mov_b32_e32 v16, v2
	v_mov_b32_e32 v17, v2
	v_mov_b32_e32 v22, v2
	v_mov_b32_e32 v23, v2
	v_mov_b32_e32 v24, v2
	v_mov_b32_e32 v25, v2
	v_mov_b32_e32 v30, v2
	v_mov_b32_e32 v31, v2
	v_mov_b32_e32 v32, v2
	v_mov_b32_e32 v33, v2
	v_mov_b32_e32 v38, v2
	v_mov_b32_e32 v39, v2
	v_mov_b32_e32 v40, v2
	v_mov_b32_e32 v41, v2
	v_mov_b32_e32 v46, v2
	v_mov_b32_e32 v47, v2
	v_mov_b32_e32 v48, v2
	v_mov_b32_e32 v49, v2
	v_mov_b32_e32 v54, v2
	v_mov_b32_e32 v55, v2
	v_mov_b32_e32 v56, v2
	v_mov_b32_e32 v57, v2
	v_mov_b32_e32 v10, v2
	v_mov_b32_e32 v11, v2
	v_mov_b32_e32 v12, v2
	v_mov_b32_e32 v13, v2
	v_mov_b32_e32 v18, v2
	v_mov_b32_e32 v19, v2
	v_mov_b32_e32 v20, v2
	v_mov_b32_e32 v21, v2
	v_mov_b32_e32 v26, v2
	v_mov_b32_e32 v27, v2
	v_mov_b32_e32 v28, v2
	v_mov_b32_e32 v29, v2
	v_mov_b32_e32 v34, v2
	v_mov_b32_e32 v35, v2
	v_mov_b32_e32 v36, v2
	v_mov_b32_e32 v37, v2
	v_mov_b32_e32 v42, v2
	v_mov_b32_e32 v43, v2
	v_mov_b32_e32 v44, v2
	v_mov_b32_e32 v45, v2
	v_mov_b32_e32 v50, v2
	v_mov_b32_e32 v51, v2
	v_mov_b32_e32 v52, v2
	v_mov_b32_e32 v53, v2
	v_mov_b32_e32 v58, v2
	v_mov_b32_e32 v59, v2
	v_mov_b32_e32 v60, v2
	v_mov_b32_e32 v61, v2
	v_mov_b32_e32 v62, v2
	v_mov_b32_e32 v63, v2
	v_mov_b32_e32 v64, v2
	v_mov_b32_e32 v65, v2
	v_mov_b32_e32 v66, v2
	v_mov_b32_e32 v67, v2
	v_mov_b32_e32 v68, v2
	v_mov_b32_e32 v69, v2
	v_mov_b32_e32 v70, v2
	v_mov_b32_e32 v71, v2
	v_mov_b32_e32 v72, v2
	v_mov_b32_e32 v73, v2
	v_mov_b32_e32 v78, v2
	v_mov_b32_e32 v79, v2
	v_mov_b32_e32 v80, v2
	v_mov_b32_e32 v81, v2
	v_mov_b32_e32 v86, v2
	v_mov_b32_e32 v87, v2
	v_mov_b32_e32 v88, v2
	v_mov_b32_e32 v89, v2
	v_mov_b32_e32 v94, v2
	v_mov_b32_e32 v95, v2
	v_mov_b32_e32 v96, v2
	v_mov_b32_e32 v97, v2
	v_mov_b32_e32 v102, v2
	v_mov_b32_e32 v103, v2
	v_mov_b32_e32 v104, v2
	v_mov_b32_e32 v105, v2
	v_mov_b32_e32 v110, v2
	v_mov_b32_e32 v111, v2
	v_mov_b32_e32 v112, v2
	v_mov_b32_e32 v113, v2
	v_mov_b32_e32 v118, v2
	v_mov_b32_e32 v119, v2
	v_mov_b32_e32 v120, v2
	v_mov_b32_e32 v121, v2
	v_mov_b32_e32 v74, v2
	v_mov_b32_e32 v75, v2
	v_mov_b32_e32 v76, v2
	v_mov_b32_e32 v77, v2
	v_mov_b32_e32 v82, v2
	v_mov_b32_e32 v83, v2
	v_mov_b32_e32 v84, v2
	v_mov_b32_e32 v85, v2
	v_mov_b32_e32 v90, v2
	v_mov_b32_e32 v91, v2
	v_mov_b32_e32 v92, v2
	v_mov_b32_e32 v93, v2
	v_mov_b32_e32 v98, v2
	v_mov_b32_e32 v99, v2
	v_mov_b32_e32 v100, v2
	v_mov_b32_e32 v101, v2
	v_mov_b32_e32 v106, v2
	v_mov_b32_e32 v107, v2
	v_mov_b32_e32 v108, v2
	v_mov_b32_e32 v109, v2
	v_mov_b32_e32 v114, v2
	v_mov_b32_e32 v115, v2
	v_mov_b32_e32 v116, v2
	v_mov_b32_e32 v117, v2
	v_mov_b32_e32 v122, v2
	v_mov_b32_e32 v123, v2
	v_mov_b32_e32 v124, v2
	v_mov_b32_e32 v125, v2
	v_mov_b32_e32 v126, v2
	v_mov_b32_e32 v127, v2
	v_mov_b32_e32 v128, v2
	v_mov_b32_e32 v129, v2
	v_readlane_b32 s45, v253, 28
	v_readlane_b32 s46, v253, 29
	v_readlane_b32 s47, v253, 30
	v_readlane_b32 s48, v253, 31
	v_readlane_b32 s49, v253, 32
	v_readlane_b32 s50, v253, 33
	v_readlane_b32 s51, v253, 34
	v_readfirstlane_b32 s98, v248
	s_cmpk_lt_u32 s98, 0x100
	s_cbranch_scc0 .Lmy_lprio6
	s_setprio 1
.Lmy_lprio6:
.LBB0_3964:
	ds_read_b128 v[142:145], v155
	ds_read_b128 v[158:161], v155 offset:1024
	ds_read_b128 v[162:165], v155 offset:2048
	ds_read_b128 v[166:169], v155 offset:3072
	s_add_u32 s18, s16, 0xfffc0080
	s_addc_u32 s19, s17, -1
	s_cmp_eq_u32 s44, 12
	s_cselect_b32 s21, s9, s19
	s_cselect_b32 s20, s40, s18
	s_cselect_b32 s19, s7, s43
	s_cselect_b32 s18, s41, s42
	v_lshl_add_u64 v[206:207], s[16:17], 0, v[138:139]
	s_add_i32 m0, s27, 0xc000
	ds_read_b128 v[170:173], v156
	ds_read_b128 v[174:177], v156 offset:1024
	ds_read_b128 v[182:185], v156 offset:2048
	ds_read_b128 v[186:189], v156 offset:3072
	ds_read_b128 v[190:193], v156 offset:4096
	ds_read_b128 v[194:197], v156 offset:5120
	ds_read_b128 v[198:201], v156 offset:6144
	ds_read_b128 v[202:205], v156 offset:7168
	global_load_lds_dwordx4 v[206:207], off
	v_lshl_add_u64 v[206:207], s[16:17], 0, v[140:141]
	s_add_i32 m0, s27, 0xe000
	s_nop 0
	global_load_lds_dwordx4 v[206:207], off
	s_waitcnt lgkmcnt(8)
	s_barrier
	s_waitcnt lgkmcnt(0)
	s_waitcnt lgkmcnt(0)
	v_mfma_f32_16x16x32_bf16 v[126:129], v[142:145], v[170:173], v[126:129]
	v_mfma_f32_16x16x32_bf16 v[122:125], v[162:165], v[170:173], v[122:125]
	v_mfma_f32_16x16x32_bf16 v[114:117], v[142:145], v[182:185], v[114:117]
	v_mfma_f32_16x16x32_bf16 v[106:109], v[162:165], v[182:185], v[106:109]
	v_mfma_f32_16x16x32_bf16 v[98:101], v[142:145], v[190:193], v[98:101]
	v_mfma_f32_16x16x32_bf16 v[90:93], v[162:165], v[190:193], v[90:93]
	v_mfma_f32_16x16x32_bf16 v[82:85], v[142:145], v[198:201], v[82:85]
	v_mfma_f32_16x16x32_bf16 v[74:77], v[162:165], v[198:201], v[74:77]
	v_mfma_f32_16x16x32_bf16 v[126:129], v[158:161], v[174:177], v[126:129]
	v_mfma_f32_16x16x32_bf16 v[122:125], v[166:169], v[174:177], v[122:125]
	v_mfma_f32_16x16x32_bf16 v[114:117], v[158:161], v[186:189], v[114:117]
	v_mfma_f32_16x16x32_bf16 v[106:109], v[166:169], v[186:189], v[106:109]
	v_mfma_f32_16x16x32_bf16 v[98:101], v[158:161], v[194:197], v[98:101]
	v_mfma_f32_16x16x32_bf16 v[90:93], v[166:169], v[194:197], v[90:93]
	v_mfma_f32_16x16x32_bf16 v[82:85], v[158:161], v[202:205], v[82:85]
	v_mfma_f32_16x16x32_bf16 v[74:77], v[166:169], v[202:205], v[74:77]
	s_barrier
	s_add_i32 s45, s36, s25
	v_lshl_add_u64 v[222:223], s[18:19], 0, v[132:133]
	s_mov_b32 m0, s45
	ds_read_b128 v[206:209], v157
	ds_read_b128 v[210:213], v157 offset:1024
	ds_read_b128 v[214:217], v157 offset:2048
	ds_read_b128 v[218:221], v157 offset:3072
	global_load_lds_dwordx4 v[222:223], off
	v_lshl_add_u64 v[224:225], s[18:19], 0, v[136:137]
	s_add_i32 m0, s45, 0x2000
	s_nop 0
	global_load_lds_dwordx4 v[224:225], off
	s_barrier
	s_waitcnt lgkmcnt(0)
	s_waitcnt lgkmcnt(0)
	v_mfma_f32_16x16x32_bf16 v[118:121], v[206:209], v[170:173], v[118:121]
	v_mfma_f32_16x16x32_bf16 v[110:113], v[214:217], v[170:173], v[110:113]
	v_mfma_f32_16x16x32_bf16 v[102:105], v[206:209], v[182:185], v[102:105]
	v_mfma_f32_16x16x32_bf16 v[94:97], v[214:217], v[182:185], v[94:97]
	v_mfma_f32_16x16x32_bf16 v[86:89], v[206:209], v[190:193], v[86:89]
	v_mfma_f32_16x16x32_bf16 v[78:81], v[214:217], v[190:193], v[78:81]
	v_mfma_f32_16x16x32_bf16 v[70:73], v[206:209], v[198:201], v[70:73]
	v_mfma_f32_16x16x32_bf16 v[66:69], v[214:217], v[198:201], v[66:69]
	v_mfma_f32_16x16x32_bf16 v[118:121], v[210:213], v[174:177], v[118:121]
	v_mfma_f32_16x16x32_bf16 v[110:113], v[218:221], v[174:177], v[110:113]
	v_mfma_f32_16x16x32_bf16 v[102:105], v[210:213], v[186:189], v[102:105]
	v_mfma_f32_16x16x32_bf16 v[94:97], v[218:221], v[186:189], v[94:97]
	v_mfma_f32_16x16x32_bf16 v[86:89], v[210:213], v[194:197], v[86:89]
	v_mfma_f32_16x16x32_bf16 v[78:81], v[218:221], v[194:197], v[78:81]
	v_mfma_f32_16x16x32_bf16 v[70:73], v[210:213], v[202:205], v[70:73]
	v_mfma_f32_16x16x32_bf16 v[66:69], v[218:221], v[202:205], v[66:69]
	s_mov_b32 m0, s27
	v_lshl_add_u64 v[228:229], s[20:21], 0, v[130:131]
	s_barrier
	ds_read_b128 v[170:173], v156 offset:16384
	ds_read_b128 v[174:177], v156 offset:17408
	ds_read_b128 v[182:185], v156 offset:18432
	ds_read_b128 v[186:189], v156 offset:19456
	ds_read_b128 v[190:193], v156 offset:20480
	ds_read_b128 v[194:197], v156 offset:21504
	ds_read_b128 v[198:201], v156 offset:22528
	ds_read_b128 v[202:205], v156 offset:23552
	global_load_lds_dwordx4 v[228:229], off
	v_lshl_add_u64 v[230:231], s[20:21], 0, v[134:135]
	s_mov_b32 m0, s28
	s_nop 0
	global_load_lds_dwordx4 v[230:231], off
	s_barrier
	s_waitcnt lgkmcnt(0)
	s_waitcnt lgkmcnt(0)
	v_mfma_f32_16x16x32_bf16 v[62:65], v[142:145], v[170:173], v[62:65]
	v_mfma_f32_16x16x32_bf16 v[58:61], v[162:165], v[170:173], v[58:61]
	v_mfma_f32_16x16x32_bf16 v[50:53], v[142:145], v[182:185], v[50:53]
	v_mfma_f32_16x16x32_bf16 v[42:45], v[162:165], v[182:185], v[42:45]
	v_mfma_f32_16x16x32_bf16 v[34:37], v[142:145], v[190:193], v[34:37]
	v_mfma_f32_16x16x32_bf16 v[26:29], v[162:165], v[190:193], v[26:29]
	v_mfma_f32_16x16x32_bf16 v[18:21], v[142:145], v[198:201], v[18:21]
	v_mfma_f32_16x16x32_bf16 v[10:13], v[162:165], v[198:201], v[10:13]
	v_mfma_f32_16x16x32_bf16 v[62:65], v[158:161], v[174:177], v[62:65]
	v_mfma_f32_16x16x32_bf16 v[58:61], v[166:169], v[174:177], v[58:61]
	v_mfma_f32_16x16x32_bf16 v[50:53], v[158:161], v[186:189], v[50:53]
	v_mfma_f32_16x16x32_bf16 v[42:45], v[166:169], v[186:189], v[42:45]
	v_mfma_f32_16x16x32_bf16 v[34:37], v[158:161], v[194:197], v[34:37]
	v_mfma_f32_16x16x32_bf16 v[26:29], v[166:169], v[194:197], v[26:29]
	v_mfma_f32_16x16x32_bf16 v[18:21], v[158:161], v[202:205], v[18:21]
	v_mfma_f32_16x16x32_bf16 v[10:13], v[166:169], v[202:205], v[10:13]
	s_barrier
	s_add_u32 s46, s18, 0x40000
	s_addc_u32 s47, s19, 0
	s_add_i32 s45, s37, s25
	v_lshl_add_u64 v[142:143], s[46:47], 0, v[132:133]
	s_mov_b32 m0, s45
	s_nop 0
	global_load_lds_dwordx4 v[142:143], off
	v_lshl_add_u64 v[142:143], s[46:47], 0, v[136:137]
	s_add_i32 m0, s45, 0x2000
	s_nop 0
	global_load_lds_dwordx4 v[142:143], off
	s_waitcnt vmcnt(6)
	s_barrier
	v_mfma_f32_16x16x32_bf16 v[54:57], v[206:209], v[170:173], v[54:57]
	v_mfma_f32_16x16x32_bf16 v[46:49], v[214:217], v[170:173], v[46:49]
	v_mfma_f32_16x16x32_bf16 v[38:41], v[206:209], v[182:185], v[38:41]
	v_mfma_f32_16x16x32_bf16 v[30:33], v[214:217], v[182:185], v[30:33]
	v_mfma_f32_16x16x32_bf16 v[22:25], v[206:209], v[190:193], v[22:25]
	v_mfma_f32_16x16x32_bf16 v[14:17], v[214:217], v[190:193], v[14:17]
	v_mfma_f32_16x16x32_bf16 v[6:9], v[206:209], v[198:201], v[6:9]
	v_mfma_f32_16x16x32_bf16 v[2:5], v[214:217], v[198:201], v[2:5]
	v_mfma_f32_16x16x32_bf16 v[54:57], v[210:213], v[174:177], v[54:57]
	v_mfma_f32_16x16x32_bf16 v[46:49], v[218:221], v[174:177], v[46:49]
	v_mfma_f32_16x16x32_bf16 v[38:41], v[210:213], v[186:189], v[38:41]
	v_mfma_f32_16x16x32_bf16 v[30:33], v[218:221], v[186:189], v[30:33]
	v_mfma_f32_16x16x32_bf16 v[22:25], v[210:213], v[194:197], v[22:25]
	v_mfma_f32_16x16x32_bf16 v[14:17], v[218:221], v[194:197], v[14:17]
	v_mfma_f32_16x16x32_bf16 v[6:9], v[210:213], v[202:205], v[6:9]
	v_mfma_f32_16x16x32_bf16 v[2:5], v[218:221], v[202:205], v[2:5]
	s_add_i32 s45, 0, 0x18000
	v_add_u32_e32 v166, s45, v153
	s_barrier
	ds_read_b128 v[142:145], v166
	ds_read_b128 v[158:161], v166 offset:1024
	ds_read_b128 v[162:165], v166 offset:2048
	ds_read_b128 v[166:169], v166 offset:3072
	s_add_u32 s20, s20, 0x40000
	s_addc_u32 s21, s21, 0
	s_mov_b32 m0, s29
	v_lshl_add_u64 v[206:207], s[20:21], 0, v[130:131]
	ds_read_b128 v[170:173], v156 offset:32768
	ds_read_b128 v[174:177], v156 offset:33792
	ds_read_b128 v[182:185], v156 offset:34816
	ds_read_b128 v[186:189], v156 offset:35840
	ds_read_b128 v[190:193], v156 offset:36864
	ds_read_b128 v[194:197], v156 offset:37888
	ds_read_b128 v[198:201], v156 offset:38912
	ds_read_b128 v[202:205], v156 offset:39936
	global_load_lds_dwordx4 v[206:207], off
	v_lshl_add_u64 v[206:207], s[20:21], 0, v[134:135]
	s_mov_b32 m0, s30
	s_nop 0
	global_load_lds_dwordx4 v[206:207], off
	s_waitcnt lgkmcnt(8)
	s_barrier
	s_waitcnt lgkmcnt(0)
	s_waitcnt lgkmcnt(0)
	v_mfma_f32_16x16x32_bf16 v[126:129], v[142:145], v[170:173], v[126:129]
	v_mfma_f32_16x16x32_bf16 v[122:125], v[162:165], v[170:173], v[122:125]
	v_mfma_f32_16x16x32_bf16 v[114:117], v[142:145], v[182:185], v[114:117]
	v_mfma_f32_16x16x32_bf16 v[106:109], v[162:165], v[182:185], v[106:109]
	v_mfma_f32_16x16x32_bf16 v[98:101], v[142:145], v[190:193], v[98:101]
	v_mfma_f32_16x16x32_bf16 v[90:93], v[162:165], v[190:193], v[90:93]
	v_mfma_f32_16x16x32_bf16 v[82:85], v[142:145], v[198:201], v[82:85]
	v_mfma_f32_16x16x32_bf16 v[74:77], v[162:165], v[198:201], v[74:77]
	v_mfma_f32_16x16x32_bf16 v[126:129], v[158:161], v[174:177], v[126:129]
	v_mfma_f32_16x16x32_bf16 v[122:125], v[166:169], v[174:177], v[122:125]
	v_mfma_f32_16x16x32_bf16 v[114:117], v[158:161], v[186:189], v[114:117]
	v_mfma_f32_16x16x32_bf16 v[106:109], v[166:169], v[186:189], v[106:109]
	v_mfma_f32_16x16x32_bf16 v[98:101], v[158:161], v[194:197], v[98:101]
	v_mfma_f32_16x16x32_bf16 v[90:93], v[166:169], v[194:197], v[90:93]
	v_mfma_f32_16x16x32_bf16 v[82:85], v[158:161], v[202:205], v[82:85]
	v_mfma_f32_16x16x32_bf16 v[74:77], v[166:169], v[202:205], v[74:77]
	s_barrier
	s_add_i32 s20, 0, 0x1c000
	s_add_i32 s21, s45, s25
	v_add_u32_e32 v181, s20, v153
	v_lshl_add_u64 v[222:223], v[222:223], 0, s[2:3]
	s_mov_b32 m0, s21
	ds_read_b128 v[206:209], v181
	ds_read_b128 v[210:213], v181 offset:1024
	ds_read_b128 v[214:217], v181 offset:2048
	ds_read_b128 v[218:221], v181 offset:3072
	global_load_lds_dwordx4 v[222:223], off
	v_lshl_add_u64 v[222:223], v[224:225], 0, s[2:3]
	s_add_i32 m0, s21, 0x2000
	s_nop 0
	global_load_lds_dwordx4 v[222:223], off
	s_barrier
	s_waitcnt lgkmcnt(0)
	s_waitcnt lgkmcnt(0)
	v_mfma_f32_16x16x32_bf16 v[118:121], v[206:209], v[170:173], v[118:121]
	v_mfma_f32_16x16x32_bf16 v[110:113], v[214:217], v[170:173], v[110:113]
	v_mfma_f32_16x16x32_bf16 v[102:105], v[206:209], v[182:185], v[102:105]
	v_mfma_f32_16x16x32_bf16 v[94:97], v[214:217], v[182:185], v[94:97]
	v_mfma_f32_16x16x32_bf16 v[86:89], v[206:209], v[190:193], v[86:89]
	v_mfma_f32_16x16x32_bf16 v[78:81], v[214:217], v[190:193], v[78:81]
	v_mfma_f32_16x16x32_bf16 v[70:73], v[206:209], v[198:201], v[70:73]
	v_mfma_f32_16x16x32_bf16 v[66:69], v[214:217], v[198:201], v[66:69]
	v_mfma_f32_16x16x32_bf16 v[118:121], v[210:213], v[174:177], v[118:121]
	v_mfma_f32_16x16x32_bf16 v[110:113], v[218:221], v[174:177], v[110:113]
	v_mfma_f32_16x16x32_bf16 v[102:105], v[210:213], v[186:189], v[102:105]
	v_mfma_f32_16x16x32_bf16 v[94:97], v[218:221], v[186:189], v[94:97]
	v_mfma_f32_16x16x32_bf16 v[86:89], v[210:213], v[194:197], v[86:89]
	v_mfma_f32_16x16x32_bf16 v[78:81], v[218:221], v[194:197], v[78:81]
	v_mfma_f32_16x16x32_bf16 v[70:73], v[210:213], v[202:205], v[70:73]
	v_mfma_f32_16x16x32_bf16 v[66:69], v[218:221], v[202:205], v[66:69]
	s_mov_b32 m0, s31
	v_lshl_add_u64 v[222:223], v[228:229], 0, s[2:3]
	s_barrier
	ds_read_b128 v[170:173], v156 offset:49152
	ds_read_b128 v[174:177], v156 offset:50176
	ds_read_b128 v[182:185], v156 offset:51200
	ds_read_b128 v[186:189], v156 offset:52224
	ds_read_b128 v[190:193], v156 offset:53248
	ds_read_b128 v[194:197], v156 offset:54272
	ds_read_b128 v[198:201], v156 offset:55296
	ds_read_b128 v[202:205], v156 offset:56320
	global_load_lds_dwordx4 v[222:223], off
	v_lshl_add_u64 v[222:223], v[230:231], 0, s[2:3]
	s_mov_b32 m0, s33
	s_nop 0
	global_load_lds_dwordx4 v[222:223], off
	s_barrier
	s_waitcnt lgkmcnt(0)
	s_waitcnt lgkmcnt(0)
	v_mfma_f32_16x16x32_bf16 v[62:65], v[142:145], v[170:173], v[62:65]
	v_mfma_f32_16x16x32_bf16 v[58:61], v[162:165], v[170:173], v[58:61]
	v_mfma_f32_16x16x32_bf16 v[50:53], v[142:145], v[182:185], v[50:53]
	v_mfma_f32_16x16x32_bf16 v[42:45], v[162:165], v[182:185], v[42:45]
	v_mfma_f32_16x16x32_bf16 v[34:37], v[142:145], v[190:193], v[34:37]
	v_mfma_f32_16x16x32_bf16 v[26:29], v[162:165], v[190:193], v[26:29]
	v_mfma_f32_16x16x32_bf16 v[18:21], v[142:145], v[198:201], v[18:21]
	v_mfma_f32_16x16x32_bf16 v[10:13], v[162:165], v[198:201], v[10:13]
	v_mfma_f32_16x16x32_bf16 v[62:65], v[158:161], v[174:177], v[62:65]
	v_mfma_f32_16x16x32_bf16 v[58:61], v[166:169], v[174:177], v[58:61]
	v_mfma_f32_16x16x32_bf16 v[50:53], v[158:161], v[186:189], v[50:53]
	v_mfma_f32_16x16x32_bf16 v[42:45], v[166:169], v[186:189], v[42:45]
	v_mfma_f32_16x16x32_bf16 v[34:37], v[158:161], v[194:197], v[34:37]
	v_mfma_f32_16x16x32_bf16 v[26:29], v[166:169], v[194:197], v[26:29]
	v_mfma_f32_16x16x32_bf16 v[18:21], v[158:161], v[202:205], v[18:21]
	v_mfma_f32_16x16x32_bf16 v[10:13], v[166:169], v[202:205], v[10:13]
	s_barrier
	s_add_u32 s18, s18, 0x40080
	s_addc_u32 s19, s19, 0
	s_add_i32 s20, s20, s25
	v_lshl_add_u64 v[142:143], s[18:19], 0, v[132:133]
	s_mov_b32 m0, s20
	s_nop 0
	global_load_lds_dwordx4 v[142:143], off
	v_lshl_add_u64 v[142:143], s[18:19], 0, v[136:137]
	s_add_i32 m0, s20, 0x2000
	s_nop 0
	global_load_lds_dwordx4 v[142:143], off
	s_waitcnt vmcnt(6)
	s_barrier
	v_mfma_f32_16x16x32_bf16 v[54:57], v[206:209], v[170:173], v[54:57]
	v_mfma_f32_16x16x32_bf16 v[46:49], v[214:217], v[170:173], v[46:49]
	v_mfma_f32_16x16x32_bf16 v[38:41], v[206:209], v[182:185], v[38:41]
	v_mfma_f32_16x16x32_bf16 v[30:33], v[214:217], v[182:185], v[30:33]
	v_mfma_f32_16x16x32_bf16 v[22:25], v[206:209], v[190:193], v[22:25]
	v_mfma_f32_16x16x32_bf16 v[14:17], v[214:217], v[190:193], v[14:17]
	v_mfma_f32_16x16x32_bf16 v[6:9], v[206:209], v[198:201], v[6:9]
	v_mfma_f32_16x16x32_bf16 v[2:5], v[214:217], v[198:201], v[2:5]
	v_mfma_f32_16x16x32_bf16 v[54:57], v[210:213], v[174:177], v[54:57]
	v_mfma_f32_16x16x32_bf16 v[46:49], v[218:221], v[174:177], v[46:49]
	v_mfma_f32_16x16x32_bf16 v[38:41], v[210:213], v[186:189], v[38:41]
	v_mfma_f32_16x16x32_bf16 v[30:33], v[218:221], v[186:189], v[30:33]
	v_mfma_f32_16x16x32_bf16 v[22:25], v[210:213], v[194:197], v[22:25]
	v_mfma_f32_16x16x32_bf16 v[14:17], v[218:221], v[194:197], v[14:17]
	v_mfma_f32_16x16x32_bf16 v[6:9], v[210:213], v[202:205], v[6:9]
	v_mfma_f32_16x16x32_bf16 v[2:5], v[218:221], v[202:205], v[2:5]
	s_add_i32 s44, s44, 2
	s_add_u32 s16, s16, 0x100
	s_addc_u32 s17, s17, 0
	s_add_u32 s42, s42, 0x100
	s_addc_u32 s43, s43, 0
	s_cmp_gt_u32 s44, 13
	s_barrier
	s_cbranch_scc0 .LBB0_3964
	v_lshl_add_u32 v144, s14, 8, v152
	v_lshl_or_b32 v142, s15, 8, v154
	v_cmp_gt_i32_e32 vcc, s38, v144
	v_ashrrev_i32_e32 v143, 31, v142
	s_and_saveexec_b64 s[14:15], vcc
	s_cbranch_execz .LBB0_3967
	s_load_dwordx16 s[40:55], s[78:79], 0x1e0
	v_ashrrev_i32_e32 v145, 31, v144
	v_lshlrev_b64 v[158:159], 9, v[144:145]
	v_cvt_pk_bf16_f32 v126, v126, v127
	v_cvt_pk_bf16_f32 v127, v128, v129
	v_cvt_pk_bf16_f32 v128, v122, v123
	s_waitcnt lgkmcnt(0)
	v_lshl_add_u64 v[122:123], s[44:45], 0, v[158:159]
	v_lshl_add_u64 v[122:123], v[142:143], 1, v[122:123]
	v_cvt_pk_bf16_f32 v129, v124, v125
	global_store_dwordx4 v[122:123], v[126:129], off
	v_cvt_pk_bf16_f32 v118, v118, v119
	v_cvt_pk_bf16_f32 v119, v120, v121
	v_cvt_pk_bf16_f32 v120, v110, v111
	v_cvt_pk_bf16_f32 v121, v112, v113
	global_store_dwordx4 v[122:123], v[118:121], off offset:256

.LBB0_4001:
	s_ashr_i32 s13, s12, 31
	v_cmp_lt_i64_e64 s[24:25], s[14:15], 16
	s_lshl_b64 s[14:15], s[12:13], 19
	s_add_u32 s14, s29, s14
	s_addc_u32 s15, s30, s15
	s_and_b64 s[16:17], s[24:25], exec
	s_cselect_b32 s13, s15, s21
	s_cselect_b32 s45, s14, s20
	s_ashr_i32 s11, s10, 31
	s_lshl_b64 s[16:17], s[10:11], 19
	s_add_u32 s16, s2, s16
	s_addc_u32 s17, s3, s17
	s_and_b64 s[24:25], s[24:25], exec
	s_cselect_b32 s11, s17, s23
	s_cselect_b32 s46, s16, s22
	s_add_u32 s20, s20, 0x40080
	s_addc_u32 s21, s21, 0
	s_add_u32 s47, s22, 0x100
	v_mov_b32_e32 v2, 0
	s_addc_u32 s48, s23, 0
	s_mov_b32 s49, -2
	v_mov_b32_e32 v3, v2
	v_mov_b32_e32 v4, v2
	v_mov_b32_e32 v5, v2
	v_mov_b32_e32 v6, v2
	v_mov_b32_e32 v7, v2
	v_mov_b32_e32 v8, v2
	v_mov_b32_e32 v9, v2
	v_mov_b32_e32 v14, v2
	v_mov_b32_e32 v15, v2
	v_mov_b32_e32 v16, v2
	v_mov_b32_e32 v17, v2
	v_mov_b32_e32 v22, v2
	v_mov_b32_e32 v23, v2
	v_mov_b32_e32 v24, v2
	v_mov_b32_e32 v25, v2
	v_mov_b32_e32 v30, v2
	v_mov_b32_e32 v31, v2
	v_mov_b32_e32 v32, v2
	v_mov_b32_e32 v33, v2
	v_mov_b32_e32 v38, v2
	v_mov_b32_e32 v39, v2
	v_mov_b32_e32 v40, v2
	v_mov_b32_e32 v41, v2
	v_mov_b32_e32 v46, v2
	v_mov_b32_e32 v47, v2
	v_mov_b32_e32 v48, v2
	v_mov_b32_e32 v49, v2
	v_mov_b32_e32 v54, v2
	v_mov_b32_e32 v55, v2
	v_mov_b32_e32 v56, v2
	v_mov_b32_e32 v57, v2
	v_mov_b32_e32 v10, v2
	v_mov_b32_e32 v11, v2
	v_mov_b32_e32 v12, v2
	v_mov_b32_e32 v13, v2
	v_mov_b32_e32 v18, v2
	v_mov_b32_e32 v19, v2
	v_mov_b32_e32 v20, v2
	v_mov_b32_e32 v21, v2
	v_mov_b32_e32 v26, v2
	v_mov_b32_e32 v27, v2
	v_mov_b32_e32 v28, v2
	v_mov_b32_e32 v29, v2
	v_mov_b32_e32 v34, v2
	v_mov_b32_e32 v35, v2
	v_mov_b32_e32 v36, v2
	v_mov_b32_e32 v37, v2
	v_mov_b32_e32 v42, v2
	v_mov_b32_e32 v43, v2
	v_mov_b32_e32 v44, v2
	v_mov_b32_e32 v45, v2
	v_mov_b32_e32 v50, v2
	v_mov_b32_e32 v51, v2
	v_mov_b32_e32 v52, v2
	v_mov_b32_e32 v53, v2
	v_mov_b32_e32 v58, v2
	v_mov_b32_e32 v59, v2
	v_mov_b32_e32 v60, v2
	v_mov_b32_e32 v61, v2
	v_mov_b32_e32 v62, v2
	v_mov_b32_e32 v63, v2
	v_mov_b32_e32 v64, v2
	v_mov_b32_e32 v65, v2
	v_mov_b32_e32 v66, v2
	v_mov_b32_e32 v67, v2
	v_mov_b32_e32 v68, v2
	v_mov_b32_e32 v69, v2
	v_mov_b32_e32 v70, v2
	v_mov_b32_e32 v71, v2
	v_mov_b32_e32 v72, v2
	v_mov_b32_e32 v73, v2
	v_mov_b32_e32 v78, v2
	v_mov_b32_e32 v79, v2
	v_mov_b32_e32 v80, v2
	v_mov_b32_e32 v81, v2
	v_mov_b32_e32 v86, v2
	v_mov_b32_e32 v87, v2
	v_mov_b32_e32 v88, v2
	v_mov_b32_e32 v89, v2
	v_mov_b32_e32 v94, v2
	v_mov_b32_e32 v95, v2
	v_mov_b32_e32 v96, v2
	v_mov_b32_e32 v97, v2
	v_mov_b32_e32 v102, v2
	v_mov_b32_e32 v103, v2
	v_mov_b32_e32 v104, v2
	v_mov_b32_e32 v105, v2
	v_mov_b32_e32 v110, v2
	v_mov_b32_e32 v111, v2
	v_mov_b32_e32 v112, v2
	v_mov_b32_e32 v113, v2
	v_mov_b32_e32 v118, v2
	v_mov_b32_e32 v119, v2
	v_mov_b32_e32 v120, v2
	v_mov_b32_e32 v121, v2
	v_mov_b32_e32 v74, v2
	v_mov_b32_e32 v75, v2
	v_mov_b32_e32 v76, v2
	v_mov_b32_e32 v77, v2
	v_mov_b32_e32 v82, v2
	v_mov_b32_e32 v83, v2
	v_mov_b32_e32 v84, v2
	v_mov_b32_e32 v85, v2
	v_mov_b32_e32 v90, v2
	v_mov_b32_e32 v91, v2
	v_mov_b32_e32 v92, v2
	v_mov_b32_e32 v93, v2
	v_mov_b32_e32 v98, v2
	v_mov_b32_e32 v99, v2
	v_mov_b32_e32 v100, v2
	v_mov_b32_e32 v101, v2
	v_mov_b32_e32 v106, v2
	v_mov_b32_e32 v107, v2
	v_mov_b32_e32 v108, v2
	v_mov_b32_e32 v109, v2
	v_mov_b32_e32 v114, v2
	v_mov_b32_e32 v115, v2
	v_mov_b32_e32 v116, v2
	v_mov_b32_e32 v117, v2
	v_mov_b32_e32 v122, v2
	v_mov_b32_e32 v123, v2
	v_mov_b32_e32 v124, v2
	v_mov_b32_e32 v125, v2
	v_mov_b32_e32 v126, v2
	v_mov_b32_e32 v127, v2
	v_mov_b32_e32 v128, v2
	v_mov_b32_e32 v129, v2
	v_readfirstlane_b32 s98, v248
	s_cmpk_lt_u32 s98, 0x100
	s_cbranch_scc0 .Lmy_lprio7
	s_setprio 1
.Lmy_lprio7:
.LBB0_4002:
	ds_read_b128 v[142:145], v1
	ds_read_b128 v[154:157], v1 offset:1024
	ds_read_b128 v[160:163], v1 offset:2048
	ds_read_b128 v[164:167], v1 offset:3072
	s_add_u32 s22, s20, 0xfffc0080
	s_addc_u32 s23, s21, -1
	s_cmp_eq_u32 s49, 12
	s_cselect_b32 s25, s13, s23
	s_cselect_b32 s24, s45, s22
	s_cselect_b32 s23, s11, s48
	s_cselect_b32 s22, s46, s47
	v_lshl_add_u64 v[176:177], s[20:21], 0, v[138:139]
	s_add_i32 m0, s33, 0xc000
	ds_read_b128 v[168:171], v146
	ds_read_b128 v[172:175], v146 offset:1024
	ds_read_b128 v[182:185], v146 offset:2048
	ds_read_b128 v[186:189], v146 offset:3072
	ds_read_b128 v[190:193], v146 offset:4096
	ds_read_b128 v[194:197], v146 offset:5120
	ds_read_b128 v[198:201], v146 offset:6144
	ds_read_b128 v[202:205], v146 offset:7168
	global_load_lds_dwordx4 v[176:177], off
	v_lshl_add_u64 v[176:177], s[20:21], 0, v[140:141]
	s_add_i32 m0, s33, 0xe000
	s_nop 0
	global_load_lds_dwordx4 v[176:177], off
	s_waitcnt lgkmcnt(8)
	s_barrier
	s_waitcnt lgkmcnt(0)
	s_waitcnt lgkmcnt(0)
	v_mfma_f32_16x16x32_bf16 v[126:129], v[142:145], v[168:171], v[126:129]
	v_mfma_f32_16x16x32_bf16 v[122:125], v[160:163], v[168:171], v[122:125]
	v_mfma_f32_16x16x32_bf16 v[114:117], v[142:145], v[182:185], v[114:117]
	v_mfma_f32_16x16x32_bf16 v[106:109], v[160:163], v[182:185], v[106:109]
	v_mfma_f32_16x16x32_bf16 v[98:101], v[142:145], v[190:193], v[98:101]
	v_mfma_f32_16x16x32_bf16 v[90:93], v[160:163], v[190:193], v[90:93]
	v_mfma_f32_16x16x32_bf16 v[82:85], v[142:145], v[198:201], v[82:85]
	v_mfma_f32_16x16x32_bf16 v[74:77], v[160:163], v[198:201], v[74:77]
	v_mfma_f32_16x16x32_bf16 v[126:129], v[154:157], v[172:175], v[126:129]
	v_mfma_f32_16x16x32_bf16 v[122:125], v[164:167], v[172:175], v[122:125]
	v_mfma_f32_16x16x32_bf16 v[114:117], v[154:157], v[186:189], v[114:117]
	v_mfma_f32_16x16x32_bf16 v[106:109], v[164:167], v[186:189], v[106:109]
	v_mfma_f32_16x16x32_bf16 v[98:101], v[154:157], v[194:197], v[98:101]
	v_mfma_f32_16x16x32_bf16 v[90:93], v[164:167], v[194:197], v[90:93]
	v_mfma_f32_16x16x32_bf16 v[82:85], v[154:157], v[202:205], v[82:85]
	v_mfma_f32_16x16x32_bf16 v[74:77], v[164:167], v[202:205], v[74:77]
	s_barrier
	s_add_i32 s50, s41, s31
	v_lshl_add_u64 v[176:177], s[22:23], 0, v[132:133]
	s_mov_b32 m0, s50
	ds_read_b128 v[206:209], v147
	ds_read_b128 v[210:213], v147 offset:1024
	ds_read_b128 v[214:217], v147 offset:2048
	ds_read_b128 v[218:221], v147 offset:3072
	global_load_lds_dwordx4 v[176:177], off
	v_lshl_add_u64 v[222:223], s[22:23], 0, v[136:137]
	s_add_i32 m0, s50, 0x2000
	s_nop 0
	global_load_lds_dwordx4 v[222:223], off
	s_barrier
	s_waitcnt lgkmcnt(0)
	s_waitcnt lgkmcnt(0)
	v_mfma_f32_16x16x32_bf16 v[118:121], v[206:209], v[168:171], v[118:121]
	v_mfma_f32_16x16x32_bf16 v[110:113], v[214:217], v[168:171], v[110:113]
	v_mfma_f32_16x16x32_bf16 v[102:105], v[206:209], v[182:185], v[102:105]
	v_mfma_f32_16x16x32_bf16 v[94:97], v[214:217], v[182:185], v[94:97]
	v_mfma_f32_16x16x32_bf16 v[86:89], v[206:209], v[190:193], v[86:89]
	v_mfma_f32_16x16x32_bf16 v[78:81], v[214:217], v[190:193], v[78:81]
	v_mfma_f32_16x16x32_bf16 v[70:73], v[206:209], v[198:201], v[70:73]
	v_mfma_f32_16x16x32_bf16 v[66:69], v[214:217], v[198:201], v[66:69]
	v_mfma_f32_16x16x32_bf16 v[118:121], v[210:213], v[172:175], v[118:121]
	v_mfma_f32_16x16x32_bf16 v[110:113], v[218:221], v[172:175], v[110:113]
	v_mfma_f32_16x16x32_bf16 v[102:105], v[210:213], v[186:189], v[102:105]
	v_mfma_f32_16x16x32_bf16 v[94:97], v[218:221], v[186:189], v[94:97]
	v_mfma_f32_16x16x32_bf16 v[86:89], v[210:213], v[194:197], v[86:89]
	v_mfma_f32_16x16x32_bf16 v[78:81], v[218:221], v[194:197], v[78:81]
	v_mfma_f32_16x16x32_bf16 v[70:73], v[210:213], v[202:205], v[70:73]
	v_mfma_f32_16x16x32_bf16 v[66:69], v[218:221], v[202:205], v[66:69]
	s_mov_b32 m0, s33
	v_lshl_add_u64 v[224:225], s[24:25], 0, v[130:131]
	s_barrier
	ds_read_b128 v[168:171], v146 offset:16384
	ds_read_b128 v[172:175], v146 offset:17408
	ds_read_b128 v[182:185], v146 offset:18432
	ds_read_b128 v[186:189], v146 offset:19456
	ds_read_b128 v[190:193], v146 offset:20480
	ds_read_b128 v[194:197], v146 offset:21504
	ds_read_b128 v[198:201], v146 offset:22528
	ds_read_b128 v[202:205], v146 offset:23552
	global_load_lds_dwordx4 v[224:225], off
	v_lshl_add_u64 v[228:229], s[24:25], 0, v[134:135]
	s_mov_b32 m0, s34
	s_nop 0
	global_load_lds_dwordx4 v[228:229], off
	s_barrier
	s_waitcnt lgkmcnt(0)
	s_waitcnt lgkmcnt(0)
	v_mfma_f32_16x16x32_bf16 v[62:65], v[142:145], v[168:171], v[62:65]
	v_mfma_f32_16x16x32_bf16 v[58:61], v[160:163], v[168:171], v[58:61]
	v_mfma_f32_16x16x32_bf16 v[50:53], v[142:145], v[182:185], v[50:53]
	v_mfma_f32_16x16x32_bf16 v[42:45], v[160:163], v[182:185], v[42:45]
	v_mfma_f32_16x16x32_bf16 v[34:37], v[142:145], v[190:193], v[34:37]
	v_mfma_f32_16x16x32_bf16 v[26:29], v[160:163], v[190:193], v[26:29]
	v_mfma_f32_16x16x32_bf16 v[18:21], v[142:145], v[198:201], v[18:21]
	v_mfma_f32_16x16x32_bf16 v[10:13], v[160:163], v[198:201], v[10:13]
	v_mfma_f32_16x16x32_bf16 v[62:65], v[154:157], v[172:175], v[62:65]
	v_mfma_f32_16x16x32_bf16 v[58:61], v[164:167], v[172:175], v[58:61]
	v_mfma_f32_16x16x32_bf16 v[50:53], v[154:157], v[186:189], v[50:53]
	v_mfma_f32_16x16x32_bf16 v[42:45], v[164:167], v[186:189], v[42:45]
	v_mfma_f32_16x16x32_bf16 v[34:37], v[154:157], v[194:197], v[34:37]
	v_mfma_f32_16x16x32_bf16 v[26:29], v[164:167], v[194:197], v[26:29]
	v_mfma_f32_16x16x32_bf16 v[18:21], v[154:157], v[202:205], v[18:21]
	v_mfma_f32_16x16x32_bf16 v[10:13], v[164:167], v[202:205], v[10:13]
	s_barrier
	s_add_u32 s50, s22, 0x40000
	s_addc_u32 s51, s23, 0
	s_add_i32 s52, s42, s31
	v_lshl_add_u64 v[142:143], s[50:51], 0, v[132:133]
	s_mov_b32 m0, s52
	s_nop 0
	global_load_lds_dwordx4 v[142:143], off
	v_lshl_add_u64 v[142:143], s[50:51], 0, v[136:137]
	s_add_i32 m0, s52, 0x2000
	s_nop 0
	global_load_lds_dwordx4 v[142:143], off
	s_waitcnt vmcnt(6)
	s_barrier
	v_mfma_f32_16x16x32_bf16 v[54:57], v[206:209], v[168:171], v[54:57]
	v_mfma_f32_16x16x32_bf16 v[46:49], v[214:217], v[168:171], v[46:49]
	v_mfma_f32_16x16x32_bf16 v[38:41], v[206:209], v[182:185], v[38:41]
	v_mfma_f32_16x16x32_bf16 v[30:33], v[214:217], v[182:185], v[30:33]
	v_mfma_f32_16x16x32_bf16 v[22:25], v[206:209], v[190:193], v[22:25]
	v_mfma_f32_16x16x32_bf16 v[14:17], v[214:217], v[190:193], v[14:17]
	v_mfma_f32_16x16x32_bf16 v[6:9], v[206:209], v[198:201], v[6:9]
	v_mfma_f32_16x16x32_bf16 v[2:5], v[214:217], v[198:201], v[2:5]
	v_mfma_f32_16x16x32_bf16 v[54:57], v[210:213], v[172:175], v[54:57]
	v_mfma_f32_16x16x32_bf16 v[46:49], v[218:221], v[172:175], v[46:49]
	v_mfma_f32_16x16x32_bf16 v[38:41], v[210:213], v[186:189], v[38:41]
	v_mfma_f32_16x16x32_bf16 v[30:33], v[218:221], v[186:189], v[30:33]
	v_mfma_f32_16x16x32_bf16 v[22:25], v[210:213], v[194:197], v[22:25]
	v_mfma_f32_16x16x32_bf16 v[14:17], v[218:221], v[194:197], v[14:17]
	v_mfma_f32_16x16x32_bf16 v[6:9], v[210:213], v[202:205], v[6:9]
	v_mfma_f32_16x16x32_bf16 v[2:5], v[218:221], v[202:205], v[2:5]
	s_add_i32 s50, 0, 0x18000
	v_add_u32_e32 v148, s50, v150
	s_barrier
	ds_read_b128 v[142:145], v148
	ds_read_b128 v[154:157], v148 offset:1024
	ds_read_b128 v[160:163], v148 offset:2048
	ds_read_b128 v[164:167], v148 offset:3072
	s_add_u32 s24, s24, 0x40000
	s_addc_u32 s25, s25, 0
	s_mov_b32 m0, s35
	v_lshl_add_u64 v[206:207], s[24:25], 0, v[130:131]
	ds_read_b128 v[168:171], v146 offset:32768
	ds_read_b128 v[172:175], v146 offset:33792
	ds_read_b128 v[182:185], v146 offset:34816
	ds_read_b128 v[186:189], v146 offset:35840
	ds_read_b128 v[190:193], v146 offset:36864
	ds_read_b128 v[194:197], v146 offset:37888
	ds_read_b128 v[198:201], v146 offset:38912
	ds_read_b128 v[202:205], v146 offset:39936
	global_load_lds_dwordx4 v[206:207], off
	v_lshl_add_u64 v[206:207], s[24:25], 0, v[134:135]
	s_mov_b32 m0, s36
	s_nop 0
	global_load_lds_dwordx4 v[206:207], off
	s_waitcnt lgkmcnt(8)
	s_barrier
	s_waitcnt lgkmcnt(0)
	s_waitcnt lgkmcnt(0)
	v_mfma_f32_16x16x32_bf16 v[126:129], v[142:145], v[168:171], v[126:129]
	v_mfma_f32_16x16x32_bf16 v[122:125], v[160:163], v[168:171], v[122:125]
	v_mfma_f32_16x16x32_bf16 v[114:117], v[142:145], v[182:185], v[114:117]
	v_mfma_f32_16x16x32_bf16 v[106:109], v[160:163], v[182:185], v[106:109]
	v_mfma_f32_16x16x32_bf16 v[98:101], v[142:145], v[190:193], v[98:101]
	v_mfma_f32_16x16x32_bf16 v[90:93], v[160:163], v[190:193], v[90:93]
	v_mfma_f32_16x16x32_bf16 v[82:85], v[142:145], v[198:201], v[82:85]
	v_mfma_f32_16x16x32_bf16 v[74:77], v[160:163], v[198:201], v[74:77]
	v_mfma_f32_16x16x32_bf16 v[126:129], v[154:157], v[172:175], v[126:129]
	v_mfma_f32_16x16x32_bf16 v[122:125], v[164:167], v[172:175], v[122:125]
	v_mfma_f32_16x16x32_bf16 v[114:117], v[154:157], v[186:189], v[114:117]
	v_mfma_f32_16x16x32_bf16 v[106:109], v[164:167], v[186:189], v[106:109]
	v_mfma_f32_16x16x32_bf16 v[98:101], v[154:157], v[194:197], v[98:101]
	v_mfma_f32_16x16x32_bf16 v[90:93], v[164:167], v[194:197], v[90:93]
	v_mfma_f32_16x16x32_bf16 v[82:85], v[154:157], v[202:205], v[82:85]
	v_mfma_f32_16x16x32_bf16 v[74:77], v[164:167], v[202:205], v[74:77]
	s_barrier
	s_add_i32 s24, 0, 0x1c000
	s_add_i32 s25, s50, s31
	v_add_u32_e32 v148, s24, v150
	v_lshl_add_u64 v[176:177], v[176:177], 0, s[6:7]
	s_mov_b32 m0, s25
	ds_read_b128 v[206:209], v148
	ds_read_b128 v[210:213], v148 offset:1024
	ds_read_b128 v[214:217], v148 offset:2048
	ds_read_b128 v[218:221], v148 offset:3072
	global_load_lds_dwordx4 v[176:177], off
	v_lshl_add_u64 v[176:177], v[222:223], 0, s[6:7]
	s_add_i32 m0, s25, 0x2000
	s_nop 0
	global_load_lds_dwordx4 v[176:177], off
	s_barrier
	s_waitcnt lgkmcnt(0)
	s_waitcnt lgkmcnt(0)
	v_mfma_f32_16x16x32_bf16 v[118:121], v[206:209], v[168:171], v[118:121]
	v_mfma_f32_16x16x32_bf16 v[110:113], v[214:217], v[168:171], v[110:113]
	v_mfma_f32_16x16x32_bf16 v[102:105], v[206:209], v[182:185], v[102:105]
	v_mfma_f32_16x16x32_bf16 v[94:97], v[214:217], v[182:185], v[94:97]
	v_mfma_f32_16x16x32_bf16 v[86:89], v[206:209], v[190:193], v[86:89]
	v_mfma_f32_16x16x32_bf16 v[78:81], v[214:217], v[190:193], v[78:81]
	v_mfma_f32_16x16x32_bf16 v[70:73], v[206:209], v[198:201], v[70:73]
	v_mfma_f32_16x16x32_bf16 v[66:69], v[214:217], v[198:201], v[66:69]
	v_mfma_f32_16x16x32_bf16 v[118:121], v[210:213], v[172:175], v[118:121]
	v_mfma_f32_16x16x32_bf16 v[110:113], v[218:221], v[172:175], v[110:113]
	v_mfma_f32_16x16x32_bf16 v[102:105], v[210:213], v[186:189], v[102:105]
	v_mfma_f32_16x16x32_bf16 v[94:97], v[218:221], v[186:189], v[94:97]
	v_mfma_f32_16x16x32_bf16 v[86:89], v[210:213], v[194:197], v[86:89]
	v_mfma_f32_16x16x32_bf16 v[78:81], v[218:221], v[194:197], v[78:81]
	v_mfma_f32_16x16x32_bf16 v[70:73], v[210:213], v[202:205], v[70:73]
	v_mfma_f32_16x16x32_bf16 v[66:69], v[218:221], v[202:205], v[66:69]
	s_mov_b32 m0, s37
	v_lshl_add_u64 v[176:177], v[224:225], 0, s[6:7]
	s_barrier
	ds_read_b128 v[168:171], v146 offset:49152
	ds_read_b128 v[172:175], v146 offset:50176
	ds_read_b128 v[182:185], v146 offset:51200
	ds_read_b128 v[186:189], v146 offset:52224
	ds_read_b128 v[190:193], v146 offset:53248
	ds_read_b128 v[194:197], v146 offset:54272
	ds_read_b128 v[198:201], v146 offset:55296
	ds_read_b128 v[202:205], v146 offset:56320
	global_load_lds_dwordx4 v[176:177], off
	v_lshl_add_u64 v[176:177], v[228:229], 0, s[6:7]
	s_mov_b32 m0, s38
	s_nop 0
	global_load_lds_dwordx4 v[176:177], off
	s_barrier
	s_waitcnt lgkmcnt(0)
	s_waitcnt lgkmcnt(0)
	v_mfma_f32_16x16x32_bf16 v[62:65], v[142:145], v[168:171], v[62:65]
	v_mfma_f32_16x16x32_bf16 v[58:61], v[160:163], v[168:171], v[58:61]
	v_mfma_f32_16x16x32_bf16 v[50:53], v[142:145], v[182:185], v[50:53]
	v_mfma_f32_16x16x32_bf16 v[42:45], v[160:163], v[182:185], v[42:45]
	v_mfma_f32_16x16x32_bf16 v[34:37], v[142:145], v[190:193], v[34:37]
	v_mfma_f32_16x16x32_bf16 v[26:29], v[160:163], v[190:193], v[26:29]
	v_mfma_f32_16x16x32_bf16 v[18:21], v[142:145], v[198:201], v[18:21]
	v_mfma_f32_16x16x32_bf16 v[10:13], v[160:163], v[198:201], v[10:13]
	v_mfma_f32_16x16x32_bf16 v[62:65], v[154:157], v[172:175], v[62:65]
	v_mfma_f32_16x16x32_bf16 v[58:61], v[164:167], v[172:175], v[58:61]
	v_mfma_f32_16x16x32_bf16 v[50:53], v[154:157], v[186:189], v[50:53]
	v_mfma_f32_16x16x32_bf16 v[42:45], v[164:167], v[186:189], v[42:45]
	v_mfma_f32_16x16x32_bf16 v[34:37], v[154:157], v[194:197], v[34:37]
	v_mfma_f32_16x16x32_bf16 v[26:29], v[164:167], v[194:197], v[26:29]
	v_mfma_f32_16x16x32_bf16 v[18:21], v[154:157], v[202:205], v[18:21]
	v_mfma_f32_16x16x32_bf16 v[10:13], v[164:167], v[202:205], v[10:13]
	s_barrier
	s_add_u32 s22, s22, 0x40080
	s_addc_u32 s23, s23, 0
	s_add_i32 s24, s24, s31
	v_lshl_add_u64 v[142:143], s[22:23], 0, v[132:133]
	s_mov_b32 m0, s24
	s_nop 0
	global_load_lds_dwordx4 v[142:143], off
	v_lshl_add_u64 v[142:143], s[22:23], 0, v[136:137]
	s_add_i32 m0, s24, 0x2000
	s_nop 0
	global_load_lds_dwordx4 v[142:143], off
	s_waitcnt vmcnt(6)
	s_barrier
	v_mfma_f32_16x16x32_bf16 v[54:57], v[206:209], v[168:171], v[54:57]
	v_mfma_f32_16x16x32_bf16 v[46:49], v[214:217], v[168:171], v[46:49]
	v_mfma_f32_16x16x32_bf16 v[38:41], v[206:209], v[182:185], v[38:41]
	v_mfma_f32_16x16x32_bf16 v[30:33], v[214:217], v[182:185], v[30:33]
	v_mfma_f32_16x16x32_bf16 v[22:25], v[206:209], v[190:193], v[22:25]
	v_mfma_f32_16x16x32_bf16 v[14:17], v[214:217], v[190:193], v[14:17]
	v_mfma_f32_16x16x32_bf16 v[6:9], v[206:209], v[198:201], v[6:9]
	v_mfma_f32_16x16x32_bf16 v[2:5], v[214:217], v[198:201], v[2:5]
	v_mfma_f32_16x16x32_bf16 v[54:57], v[210:213], v[172:175], v[54:57]
	v_mfma_f32_16x16x32_bf16 v[46:49], v[218:221], v[172:175], v[46:49]
	v_mfma_f32_16x16x32_bf16 v[38:41], v[210:213], v[186:189], v[38:41]
	v_mfma_f32_16x16x32_bf16 v[30:33], v[218:221], v[186:189], v[30:33]
	v_mfma_f32_16x16x32_bf16 v[22:25], v[210:213], v[194:197], v[22:25]
	v_mfma_f32_16x16x32_bf16 v[14:17], v[218:221], v[194:197], v[14:17]
	v_mfma_f32_16x16x32_bf16 v[6:9], v[210:213], v[202:205], v[6:9]
	v_mfma_f32_16x16x32_bf16 v[2:5], v[218:221], v[202:205], v[2:5]
	s_add_i32 s49, s49, 2
	s_add_u32 s20, s20, 0x100
	s_addc_u32 s21, s21, 0
	s_add_u32 s47, s47, 0x100
	s_addc_u32 s48, s48, 0
	s_cmp_gt_u32 s49, 13
	s_barrier
	s_cbranch_scc0 .LBB0_4002
	v_lshl_add_u32 v144, s18, 8, v152
	v_lshl_or_b32 v142, s19, 8, v149
	v_cmp_gt_i32_e32 vcc, s43, v144
	v_ashrrev_i32_e32 v143, 31, v142
	s_and_saveexec_b64 s[18:19], vcc
	s_cbranch_execz .LBB0_4005
	v_ashrrev_i32_e32 v145, 31, v144
	v_lshlrev_b64 v[154:155], 9, v[144:145]
	v_cvt_pk_bf16_f32 v126, v126, v127
	v_cvt_pk_bf16_f32 v127, v128, v129
	v_cvt_pk_bf16_f32 v128, v122, v123
	v_lshl_add_u64 v[122:123], s[4:5], 0, v[154:155]
	v_lshl_add_u64 v[122:123], v[142:143], 1, v[122:123]
	v_cvt_pk_bf16_f32 v129, v124, v125
	global_store_dwordx4 v[122:123], v[126:129], off
	v_cvt_pk_bf16_f32 v118, v118, v119
	v_cvt_pk_bf16_f32 v119, v120, v121
	v_cvt_pk_bf16_f32 v120, v110, v111
	v_cvt_pk_bf16_f32 v121, v112, v113
	global_store_dwordx4 v[122:123], v[118:121], off offset:256

.LBB0_4567:
	s_load_dwordx16 s[52:67], s[78:79], 0x268
	s_add_u32 s47, s24, 0x100
	s_addc_u32 s48, s25, 0
	s_ashr_i32 s19, s18, 31
	s_lshl_b64 s[20:21], s[18:19], 19
	s_waitcnt lgkmcnt(0)
	s_add_u32 s22, s64, s20
	s_addc_u32 s23, s65, s21
	s_and_b64 s[20:21], s[6:7], exec
	v_readlane_b32 s52, v253, 27
	s_cselect_b32 s19, s23, s1
	s_cselect_b32 s49, s22, s0
	s_ashr_i32 s17, s16, 31
	v_readlane_b32 s60, v253, 35
	v_readlane_b32 s61, v253, 36
	v_readlane_b32 s64, v253, 39
	v_readlane_b32 s65, v253, 40
	s_lshl_b64 s[20:21], s[16:17], 19
	s_mov_b64 s[60:61], s[64:65]
	s_add_u32 s20, s60, s20
	s_addc_u32 s21, s61, s21
	s_and_b64 s[26:27], s[6:7], exec
	s_cselect_b32 s17, s21, s25
	s_cselect_b32 s50, s20, s24
	v_lshl_add_u64 v[142:143], s[0:1], 0, v[134:135]
	v_lshl_add_u64 v[144:145], s[0:1], 0, v[136:137]
	s_mov_b32 s51, -2
	s_mov_b64 s[24:25], 0
	v_readlane_b32 s53, v253, 28
	v_readlane_b32 s54, v253, 29
	v_readlane_b32 s55, v253, 30
	v_readlane_b32 s56, v253, 31
	v_readlane_b32 s57, v253, 32
	v_readlane_b32 s58, v253, 33
	v_readlane_b32 s59, v253, 34
	v_readlane_b32 s62, v253, 37
	v_readlane_b32 s63, v253, 38
	v_readlane_b32 s66, v253, 41
	v_readlane_b32 s67, v253, 42
	v_readfirstlane_b32 s98, v248
	s_cmpk_lt_u32 s98, 0x100
	s_cbranch_scc0 .Lmy_lprio8
	s_setprio 1
.Lmy_lprio8:
.LBB0_4568:
	v_add_u32_e32 v149, s44, v147
	s_add_u32 s26, s0, s24
	ds_read_b128 v[150:153], v149
	ds_read_b128 v[154:157], v149 offset:1024
	ds_read_b128 v[158:161], v149 offset:2048
	ds_read_b128 v[162:165], v149 offset:3072
	s_addc_u32 s27, s1, s25
	s_add_u32 s26, s26, 0x100
	s_addc_u32 s27, s27, 0
	s_add_u32 s52, s47, s24
	s_addc_u32 s53, s48, s25
	s_cmpk_eq_i32 s24, 0x700
	s_cselect_b32 s29, s19, s27
	s_cselect_b32 s28, s49, s26
	s_cselect_b32 s27, s17, s53
	s_cselect_b32 s26, s50, s52
	v_lshl_add_u64 v[202:203], v[142:143], 0, s[24:25]
	s_add_i32 m0, s36, 0xc000
	ds_read_b128 v[166:169], v148
	ds_read_b128 v[170:173], v148 offset:1024
	ds_read_b128 v[174:177], v148 offset:2048
	ds_read_b128 v[182:185], v148 offset:3072
	ds_read_b128 v[186:189], v148 offset:4096
	ds_read_b128 v[190:193], v148 offset:5120
	ds_read_b128 v[194:197], v148 offset:6144
	ds_read_b128 v[198:201], v148 offset:7168
	global_load_lds_dwordx4 v[202:203], off
	v_lshl_add_u64 v[202:203], v[144:145], 0, s[24:25]
	s_add_i32 m0, s36, 0xe000
	s_nop 0
	global_load_lds_dwordx4 v[202:203], off
	s_waitcnt lgkmcnt(8)
	s_barrier
	s_waitcnt lgkmcnt(0)
	s_waitcnt lgkmcnt(0)
	v_mfma_f32_16x16x32_bf16 v[126:129], v[150:153], v[166:169], v[126:129]
	v_mfma_f32_16x16x32_bf16 v[122:125], v[158:161], v[166:169], v[122:125]
	v_mfma_f32_16x16x32_bf16 v[110:113], v[150:153], v[174:177], v[110:113]
	v_mfma_f32_16x16x32_bf16 v[106:109], v[158:161], v[174:177], v[106:109]
	v_mfma_f32_16x16x32_bf16 v[94:97], v[150:153], v[186:189], v[94:97]
	v_mfma_f32_16x16x32_bf16 v[90:93], v[158:161], v[186:189], v[90:93]
	v_mfma_f32_16x16x32_bf16 v[78:81], v[150:153], v[194:197], v[78:81]
	v_mfma_f32_16x16x32_bf16 v[74:77], v[158:161], v[194:197], v[74:77]
	v_mfma_f32_16x16x32_bf16 v[126:129], v[154:157], v[170:173], v[126:129]
	v_mfma_f32_16x16x32_bf16 v[122:125], v[162:165], v[170:173], v[122:125]
	v_mfma_f32_16x16x32_bf16 v[110:113], v[154:157], v[182:185], v[110:113]
	v_mfma_f32_16x16x32_bf16 v[106:109], v[162:165], v[182:185], v[106:109]
	v_mfma_f32_16x16x32_bf16 v[94:97], v[154:157], v[190:193], v[94:97]
	v_mfma_f32_16x16x32_bf16 v[90:93], v[162:165], v[190:193], v[90:93]
	v_mfma_f32_16x16x32_bf16 v[78:81], v[154:157], v[198:201], v[78:81]
	v_mfma_f32_16x16x32_bf16 v[74:77], v[162:165], v[198:201], v[74:77]
	s_barrier
	s_add_i32 s52, s44, s35
	v_add_u32_e32 v149, s45, v147
	v_lshl_add_u64 v[218:219], s[26:27], 0, v[130:131]
	s_mov_b32 m0, s52
	ds_read_b128 v[202:205], v149
	ds_read_b128 v[206:209], v149 offset:1024
	ds_read_b128 v[210:213], v149 offset:2048
	ds_read_b128 v[214:217], v149 offset:3072
	global_load_lds_dwordx4 v[218:219], off
	v_lshl_add_u64 v[220:221], s[26:27], 0, v[132:133]
	s_add_i32 m0, s52, 0x2000
	s_nop 0
	global_load_lds_dwordx4 v[220:221], off
	s_barrier
	s_waitcnt lgkmcnt(0)
	s_waitcnt lgkmcnt(0)
	v_mfma_f32_16x16x32_bf16 v[118:121], v[202:205], v[166:169], v[118:121]
	v_mfma_f32_16x16x32_bf16 v[114:117], v[210:213], v[166:169], v[114:117]
	v_mfma_f32_16x16x32_bf16 v[102:105], v[202:205], v[174:177], v[102:105]
	v_mfma_f32_16x16x32_bf16 v[98:101], v[210:213], v[174:177], v[98:101]
	v_mfma_f32_16x16x32_bf16 v[86:89], v[202:205], v[186:189], v[86:89]
	v_mfma_f32_16x16x32_bf16 v[82:85], v[210:213], v[186:189], v[82:85]
	v_mfma_f32_16x16x32_bf16 v[70:73], v[202:205], v[194:197], v[70:73]
	v_mfma_f32_16x16x32_bf16 v[66:69], v[210:213], v[194:197], v[66:69]
	v_mfma_f32_16x16x32_bf16 v[118:121], v[206:209], v[170:173], v[118:121]
	v_mfma_f32_16x16x32_bf16 v[114:117], v[214:217], v[170:173], v[114:117]
	v_mfma_f32_16x16x32_bf16 v[102:105], v[206:209], v[182:185], v[102:105]
	v_mfma_f32_16x16x32_bf16 v[98:101], v[214:217], v[182:185], v[98:101]
	v_mfma_f32_16x16x32_bf16 v[86:89], v[206:209], v[190:193], v[86:89]
	v_mfma_f32_16x16x32_bf16 v[82:85], v[214:217], v[190:193], v[82:85]
	v_mfma_f32_16x16x32_bf16 v[70:73], v[206:209], v[198:201], v[70:73]
	v_mfma_f32_16x16x32_bf16 v[66:69], v[214:217], v[198:201], v[66:69]
	s_mov_b32 m0, s36
	v_lshl_add_u64 v[222:223], s[28:29], 0, v[130:131]
	s_barrier
	ds_read_b128 v[166:169], v148 offset:16384
	ds_read_b128 v[170:173], v148 offset:17408
	ds_read_b128 v[174:177], v148 offset:18432
	ds_read_b128 v[182:185], v148 offset:19456
	ds_read_b128 v[186:189], v148 offset:20480
	ds_read_b128 v[190:193], v148 offset:21504
	ds_read_b128 v[194:197], v148 offset:22528
	ds_read_b128 v[198:201], v148 offset:23552
	global_load_lds_dwordx4 v[222:223], off
	v_lshl_add_u64 v[224:225], s[28:29], 0, v[132:133]
	s_mov_b32 m0, s37
	s_nop 0
	global_load_lds_dwordx4 v[224:225], off
	s_barrier
	s_waitcnt lgkmcnt(0)
	s_waitcnt lgkmcnt(0)
	v_mfma_f32_16x16x32_bf16 v[62:65], v[150:153], v[166:169], v[62:65]
	v_mfma_f32_16x16x32_bf16 v[58:61], v[158:161], v[166:169], v[58:61]
	v_mfma_f32_16x16x32_bf16 v[46:49], v[150:153], v[174:177], v[46:49]
	v_mfma_f32_16x16x32_bf16 v[42:45], v[158:161], v[174:177], v[42:45]
	v_mfma_f32_16x16x32_bf16 v[30:33], v[150:153], v[186:189], v[30:33]
	v_mfma_f32_16x16x32_bf16 v[26:29], v[158:161], v[186:189], v[26:29]
	v_mfma_f32_16x16x32_bf16 v[14:17], v[150:153], v[194:197], v[14:17]
	v_mfma_f32_16x16x32_bf16 v[10:13], v[158:161], v[194:197], v[10:13]
	v_mfma_f32_16x16x32_bf16 v[62:65], v[154:157], v[170:173], v[62:65]
	v_mfma_f32_16x16x32_bf16 v[58:61], v[162:165], v[170:173], v[58:61]
	v_mfma_f32_16x16x32_bf16 v[46:49], v[154:157], v[182:185], v[46:49]
	v_mfma_f32_16x16x32_bf16 v[42:45], v[162:165], v[182:185], v[42:45]
	v_mfma_f32_16x16x32_bf16 v[30:33], v[154:157], v[190:193], v[30:33]
	v_mfma_f32_16x16x32_bf16 v[26:29], v[162:165], v[190:193], v[26:29]
	v_mfma_f32_16x16x32_bf16 v[14:17], v[154:157], v[198:201], v[14:17]
	v_mfma_f32_16x16x32_bf16 v[10:13], v[162:165], v[198:201], v[10:13]
	s_barrier
	s_add_u32 s52, s26, 0x40000
	s_addc_u32 s53, s27, 0
	s_add_i32 s54, s45, s35
	v_lshl_add_u64 v[150:151], s[52:53], 0, v[130:131]
	s_mov_b32 m0, s54
	s_nop 0
	global_load_lds_dwordx4 v[150:151], off
	v_lshl_add_u64 v[150:151], s[52:53], 0, v[132:133]
	s_add_i32 m0, s54, 0x2000
	s_nop 0
	global_load_lds_dwordx4 v[150:151], off
	s_waitcnt vmcnt(6)
	s_barrier
	v_mfma_f32_16x16x32_bf16 v[54:57], v[202:205], v[166:169], v[54:57]
	v_mfma_f32_16x16x32_bf16 v[50:53], v[210:213], v[166:169], v[50:53]
	v_mfma_f32_16x16x32_bf16 v[38:41], v[202:205], v[174:177], v[38:41]
	v_mfma_f32_16x16x32_bf16 v[34:37], v[210:213], v[174:177], v[34:37]
	v_mfma_f32_16x16x32_bf16 v[22:25], v[202:205], v[186:189], v[22:25]
	v_mfma_f32_16x16x32_bf16 v[18:21], v[210:213], v[186:189], v[18:21]
	v_mfma_f32_16x16x32_bf16 v[6:9], v[202:205], v[194:197], v[6:9]
	v_mfma_f32_16x16x32_bf16 v[2:5], v[210:213], v[194:197], v[2:5]
	v_mfma_f32_16x16x32_bf16 v[54:57], v[206:209], v[170:173], v[54:57]
	v_mfma_f32_16x16x32_bf16 v[50:53], v[214:217], v[170:173], v[50:53]
	v_mfma_f32_16x16x32_bf16 v[38:41], v[206:209], v[182:185], v[38:41]
	v_mfma_f32_16x16x32_bf16 v[34:37], v[214:217], v[182:185], v[34:37]
	v_mfma_f32_16x16x32_bf16 v[22:25], v[206:209], v[190:193], v[22:25]
	v_mfma_f32_16x16x32_bf16 v[18:21], v[214:217], v[190:193], v[18:21]
	v_mfma_f32_16x16x32_bf16 v[6:9], v[206:209], v[198:201], v[6:9]
	v_mfma_f32_16x16x32_bf16 v[2:5], v[214:217], v[198:201], v[2:5]
	s_add_i32 s52, 0, 0x18000
	v_add_u32_e32 v149, s52, v147
	s_barrier
	ds_read_b128 v[150:153], v149
	ds_read_b128 v[154:157], v149 offset:1024
	ds_read_b128 v[158:161], v149 offset:2048
	ds_read_b128 v[162:165], v149 offset:3072
	s_add_u32 s28, s28, 0x40000
	s_addc_u32 s29, s29, 0
	s_mov_b32 m0, s38
	v_lshl_add_u64 v[202:203], s[28:29], 0, v[130:131]
	ds_read_b128 v[166:169], v148 offset:32768
	ds_read_b128 v[170:173], v148 offset:33792
	ds_read_b128 v[174:177], v148 offset:34816
	ds_read_b128 v[182:185], v148 offset:35840
	ds_read_b128 v[186:189], v148 offset:36864
	ds_read_b128 v[190:193], v148 offset:37888
	ds_read_b128 v[194:197], v148 offset:38912
	ds_read_b128 v[198:201], v148 offset:39936
	global_load_lds_dwordx4 v[202:203], off
	v_lshl_add_u64 v[202:203], s[28:29], 0, v[132:133]
	s_mov_b32 m0, s39
	s_nop 0
	global_load_lds_dwordx4 v[202:203], off
	s_waitcnt lgkmcnt(8)
	s_barrier
	s_waitcnt lgkmcnt(0)
	s_waitcnt lgkmcnt(0)
	v_mfma_f32_16x16x32_bf16 v[126:129], v[150:153], v[166:169], v[126:129]
	v_mfma_f32_16x16x32_bf16 v[122:125], v[158:161], v[166:169], v[122:125]
	v_mfma_f32_16x16x32_bf16 v[110:113], v[150:153], v[174:177], v[110:113]
	v_mfma_f32_16x16x32_bf16 v[106:109], v[158:161], v[174:177], v[106:109]
	v_mfma_f32_16x16x32_bf16 v[94:97], v[150:153], v[186:189], v[94:97]
	v_mfma_f32_16x16x32_bf16 v[90:93], v[158:161], v[186:189], v[90:93]
	v_mfma_f32_16x16x32_bf16 v[78:81], v[150:153], v[194:197], v[78:81]
	v_mfma_f32_16x16x32_bf16 v[74:77], v[158:161], v[194:197], v[74:77]
	v_mfma_f32_16x16x32_bf16 v[126:129], v[154:157], v[170:173], v[126:129]
	v_mfma_f32_16x16x32_bf16 v[122:125], v[162:165], v[170:173], v[122:125]
	v_mfma_f32_16x16x32_bf16 v[110:113], v[154:157], v[182:185], v[110:113]
	v_mfma_f32_16x16x32_bf16 v[106:109], v[162:165], v[182:185], v[106:109]
	v_mfma_f32_16x16x32_bf16 v[94:97], v[154:157], v[190:193], v[94:97]
	v_mfma_f32_16x16x32_bf16 v[90:93], v[162:165], v[190:193], v[90:93]
	v_mfma_f32_16x16x32_bf16 v[78:81], v[154:157], v[198:201], v[78:81]
	v_mfma_f32_16x16x32_bf16 v[74:77], v[162:165], v[198:201], v[74:77]
	s_barrier
	s_add_i32 s28, 0, 0x1c000
	s_add_i32 s29, s52, s35
	v_add_u32_e32 v149, s28, v147
	v_lshl_add_u64 v[218:219], v[218:219], 0, s[14:15]
	s_mov_b32 m0, s29
	ds_read_b128 v[202:205], v149
	ds_read_b128 v[206:209], v149 offset:1024
	ds_read_b128 v[210:213], v149 offset:2048
	ds_read_b128 v[214:217], v149 offset:3072
	global_load_lds_dwordx4 v[218:219], off
	v_lshl_add_u64 v[218:219], v[220:221], 0, s[14:15]
	s_add_i32 m0, s29, 0x2000
	s_nop 0
	global_load_lds_dwordx4 v[218:219], off
	s_barrier
	s_waitcnt lgkmcnt(0)
	s_waitcnt lgkmcnt(0)
	v_mfma_f32_16x16x32_bf16 v[118:121], v[202:205], v[166:169], v[118:121]
	v_mfma_f32_16x16x32_bf16 v[114:117], v[210:213], v[166:169], v[114:117]
	v_mfma_f32_16x16x32_bf16 v[102:105], v[202:205], v[174:177], v[102:105]
	v_mfma_f32_16x16x32_bf16 v[98:101], v[210:213], v[174:177], v[98:101]
	v_mfma_f32_16x16x32_bf16 v[86:89], v[202:205], v[186:189], v[86:89]
	v_mfma_f32_16x16x32_bf16 v[82:85], v[210:213], v[186:189], v[82:85]
	v_mfma_f32_16x16x32_bf16 v[70:73], v[202:205], v[194:197], v[70:73]
	v_mfma_f32_16x16x32_bf16 v[66:69], v[210:213], v[194:197], v[66:69]
	v_mfma_f32_16x16x32_bf16 v[118:121], v[206:209], v[170:173], v[118:121]
	v_mfma_f32_16x16x32_bf16 v[114:117], v[214:217], v[170:173], v[114:117]
	v_mfma_f32_16x16x32_bf16 v[102:105], v[206:209], v[182:185], v[102:105]
	v_mfma_f32_16x16x32_bf16 v[98:101], v[214:217], v[182:185], v[98:101]
	v_mfma_f32_16x16x32_bf16 v[86:89], v[206:209], v[190:193], v[86:89]
	v_mfma_f32_16x16x32_bf16 v[82:85], v[214:217], v[190:193], v[82:85]
	v_mfma_f32_16x16x32_bf16 v[70:73], v[206:209], v[198:201], v[70:73]
	v_mfma_f32_16x16x32_bf16 v[66:69], v[214:217], v[198:201], v[66:69]
	s_mov_b32 m0, s42
	v_lshl_add_u64 v[218:219], v[222:223], 0, s[14:15]
	s_barrier
	ds_read_b128 v[166:169], v148 offset:49152
	ds_read_b128 v[170:173], v148 offset:50176
	ds_read_b128 v[174:177], v148 offset:51200
	ds_read_b128 v[182:185], v148 offset:52224
	ds_read_b128 v[186:189], v148 offset:53248
	ds_read_b128 v[190:193], v148 offset:54272
	ds_read_b128 v[194:197], v148 offset:55296
	ds_read_b128 v[198:201], v148 offset:56320
	global_load_lds_dwordx4 v[218:219], off
	v_lshl_add_u64 v[218:219], v[224:225], 0, s[14:15]
	s_mov_b32 m0, s43
	s_nop 0
	global_load_lds_dwordx4 v[218:219], off
	s_barrier
	s_waitcnt lgkmcnt(0)
	s_waitcnt lgkmcnt(0)
	v_mfma_f32_16x16x32_bf16 v[62:65], v[150:153], v[166:169], v[62:65]
	v_mfma_f32_16x16x32_bf16 v[58:61], v[158:161], v[166:169], v[58:61]
	v_mfma_f32_16x16x32_bf16 v[46:49], v[150:153], v[174:177], v[46:49]
	v_mfma_f32_16x16x32_bf16 v[42:45], v[158:161], v[174:177], v[42:45]
	v_mfma_f32_16x16x32_bf16 v[30:33], v[150:153], v[186:189], v[30:33]
	v_mfma_f32_16x16x32_bf16 v[26:29], v[158:161], v[186:189], v[26:29]
	v_mfma_f32_16x16x32_bf16 v[14:17], v[150:153], v[194:197], v[14:17]
	v_mfma_f32_16x16x32_bf16 v[10:13], v[158:161], v[194:197], v[10:13]
	v_mfma_f32_16x16x32_bf16 v[62:65], v[154:157], v[170:173], v[62:65]
	v_mfma_f32_16x16x32_bf16 v[58:61], v[162:165], v[170:173], v[58:61]
	v_mfma_f32_16x16x32_bf16 v[46:49], v[154:157], v[182:185], v[46:49]
	v_mfma_f32_16x16x32_bf16 v[42:45], v[162:165], v[182:185], v[42:45]
	v_mfma_f32_16x16x32_bf16 v[30:33], v[154:157], v[190:193], v[30:33]
	v_mfma_f32_16x16x32_bf16 v[26:29], v[162:165], v[190:193], v[26:29]
	v_mfma_f32_16x16x32_bf16 v[14:17], v[154:157], v[198:201], v[14:17]
	v_mfma_f32_16x16x32_bf16 v[10:13], v[162:165], v[198:201], v[10:13]
	s_barrier
	s_add_u32 s26, s26, 0x40080
	s_addc_u32 s27, s27, 0
	s_add_i32 s28, s28, s35
	v_lshl_add_u64 v[150:151], s[26:27], 0, v[130:131]
	s_mov_b32 m0, s28
	s_nop 0
	global_load_lds_dwordx4 v[150:151], off
	v_lshl_add_u64 v[150:151], s[26:27], 0, v[132:133]
	s_add_i32 m0, s28, 0x2000
	s_nop 0
	global_load_lds_dwordx4 v[150:151], off
	s_waitcnt vmcnt(6)
	s_barrier
	v_mfma_f32_16x16x32_bf16 v[54:57], v[202:205], v[166:169], v[54:57]
	v_mfma_f32_16x16x32_bf16 v[50:53], v[210:213], v[166:169], v[50:53]
	v_mfma_f32_16x16x32_bf16 v[38:41], v[202:205], v[174:177], v[38:41]
	v_mfma_f32_16x16x32_bf16 v[34:37], v[210:213], v[174:177], v[34:37]
	v_mfma_f32_16x16x32_bf16 v[22:25], v[202:205], v[186:189], v[22:25]
	v_mfma_f32_16x16x32_bf16 v[18:21], v[210:213], v[186:189], v[18:21]
	v_mfma_f32_16x16x32_bf16 v[6:9], v[202:205], v[194:197], v[6:9]
	v_mfma_f32_16x16x32_bf16 v[2:5], v[210:213], v[194:197], v[2:5]
	v_mfma_f32_16x16x32_bf16 v[54:57], v[206:209], v[170:173], v[54:57]
	v_mfma_f32_16x16x32_bf16 v[50:53], v[214:217], v[170:173], v[50:53]
	v_mfma_f32_16x16x32_bf16 v[38:41], v[206:209], v[182:185], v[38:41]
	v_mfma_f32_16x16x32_bf16 v[34:37], v[214:217], v[182:185], v[34:37]
	v_mfma_f32_16x16x32_bf16 v[22:25], v[206:209], v[190:193], v[22:25]
	v_mfma_f32_16x16x32_bf16 v[18:21], v[214:217], v[190:193], v[18:21]
	v_mfma_f32_16x16x32_bf16 v[6:9], v[206:209], v[198:201], v[6:9]
	v_mfma_f32_16x16x32_bf16 v[2:5], v[214:217], v[198:201], v[2:5]
	s_add_i32 s51, s51, 2
	s_add_u32 s24, s24, 0x100
	s_addc_u32 s25, s25, 0
	s_cmp_gt_u32 s51, 13
	s_barrier
	s_cbranch_scc0 .LBB0_4568
	s_add_u32 s24, s47, 0xffffff00
	s_addc_u32 s25, s48, -1
	s_andn2_b64 vcc, exec, s[6:7]
	s_cbranch_vccnz .LBB0_4559
	v_mov_b32_e32 v2, 0
	s_mov_b32 s2, s16
	s_mov_b32 s12, s18
	s_mov_b64 s[0:1], s[22:23]
	s_mov_b32 s41, s46
	v_mov_b32_e32 v3, v2
	v_mov_b32_e32 v4, v2
	v_mov_b32_e32 v5, v2
	v_mov_b32_e32 v6, v2
	v_mov_b32_e32 v7, v2
	v_mov_b32_e32 v8, v2
	v_mov_b32_e32 v9, v2
	v_mov_b32_e32 v18, v2
	v_mov_b32_e32 v19, v2
	v_mov_b32_e32 v20, v2
	v_mov_b32_e32 v21, v2
	v_mov_b32_e32 v22, v2
	v_mov_b32_e32 v23, v2
	v_mov_b32_e32 v24, v2
	v_mov_b32_e32 v25, v2
	v_mov_b32_e32 v34, v2
	v_mov_b32_e32 v35, v2
	v_mov_b32_e32 v36, v2
	v_mov_b32_e32 v37, v2
	v_mov_b32_e32 v38, v2
	v_mov_b32_e32 v39, v2
	v_mov_b32_e32 v40, v2
	v_mov_b32_e32 v41, v2
	v_mov_b32_e32 v50, v2
	v_mov_b32_e32 v51, v2
	v_mov_b32_e32 v52, v2
	v_mov_b32_e32 v53, v2
	v_mov_b32_e32 v54, v2
	v_mov_b32_e32 v55, v2
	v_mov_b32_e32 v56, v2
	v_mov_b32_e32 v57, v2
	v_mov_b32_e32 v10, v2
	v_mov_b32_e32 v11, v2
	v_mov_b32_e32 v12, v2
	v_mov_b32_e32 v13, v2
	v_mov_b32_e32 v14, v2
	v_mov_b32_e32 v15, v2
	v_mov_b32_e32 v16, v2
	v_mov_b32_e32 v17, v2
	v_mov_b32_e32 v26, v2
	v_mov_b32_e32 v27, v2
	v_mov_b32_e32 v28, v2
	v_mov_b32_e32 v29, v2
	v_mov_b32_e32 v30, v2
	v_mov_b32_e32 v31, v2
	v_mov_b32_e32 v32, v2
	v_mov_b32_e32 v33, v2
	v_mov_b32_e32 v42, v2
	v_mov_b32_e32 v43, v2
	v_mov_b32_e32 v44, v2
	v_mov_b32_e32 v45, v2
	v_mov_b32_e32 v46, v2
	v_mov_b32_e32 v47, v2
	v_mov_b32_e32 v48, v2
	v_mov_b32_e32 v49, v2
	v_mov_b32_e32 v58, v2
	v_mov_b32_e32 v59, v2
	v_mov_b32_e32 v60, v2
	v_mov_b32_e32 v61, v2
	v_mov_b32_e32 v62, v2
	v_mov_b32_e32 v63, v2
	v_mov_b32_e32 v64, v2
	v_mov_b32_e32 v65, v2
	v_mov_b32_e32 v66, v2
	v_mov_b32_e32 v67, v2
	v_mov_b32_e32 v68, v2
	v_mov_b32_e32 v69, v2
	v_mov_b32_e32 v70, v2
	v_mov_b32_e32 v71, v2
	v_mov_b32_e32 v72, v2
	v_mov_b32_e32 v73, v2
	v_mov_b32_e32 v82, v2
	v_mov_b32_e32 v83, v2
	v_mov_b32_e32 v84, v2
	v_mov_b32_e32 v85, v2
	v_mov_b32_e32 v86, v2
	v_mov_b32_e32 v87, v2
	v_mov_b32_e32 v88, v2
	v_mov_b32_e32 v89, v2
	v_mov_b32_e32 v98, v2
	v_mov_b32_e32 v99, v2
	v_mov_b32_e32 v100, v2
	v_mov_b32_e32 v101, v2
	v_mov_b32_e32 v102, v2
	v_mov_b32_e32 v103, v2
	v_mov_b32_e32 v104, v2
	v_mov_b32_e32 v105, v2
	v_mov_b32_e32 v114, v2
	v_mov_b32_e32 v115, v2
	v_mov_b32_e32 v116, v2
	v_mov_b32_e32 v117, v2
	v_mov_b32_e32 v118, v2
	v_mov_b32_e32 v119, v2
	v_mov_b32_e32 v120, v2
	v_mov_b32_e32 v121, v2
	v_mov_b32_e32 v74, v2
	v_mov_b32_e32 v75, v2
	v_mov_b32_e32 v76, v2
	v_mov_b32_e32 v77, v2
	v_mov_b32_e32 v78, v2
	v_mov_b32_e32 v79, v2
	v_mov_b32_e32 v80, v2
	v_mov_b32_e32 v81, v2
	v_mov_b32_e32 v90, v2
	v_mov_b32_e32 v91, v2
	v_mov_b32_e32 v92, v2
	v_mov_b32_e32 v93, v2
	v_mov_b32_e32 v94, v2
	v_mov_b32_e32 v95, v2
	v_mov_b32_e32 v96, v2
	v_mov_b32_e32 v97, v2
	v_mov_b32_e32 v106, v2
	v_mov_b32_e32 v107, v2
	v_mov_b32_e32 v108, v2
	v_mov_b32_e32 v109, v2
	v_mov_b32_e32 v110, v2
	v_mov_b32_e32 v111, v2
	v_mov_b32_e32 v112, v2
	v_mov_b32_e32 v113, v2
	v_mov_b32_e32 v122, v2
	v_mov_b32_e32 v123, v2
	v_mov_b32_e32 v124, v2
	v_mov_b32_e32 v125, v2
	v_mov_b32_e32 v126, v2
	v_mov_b32_e32 v127, v2
	v_mov_b32_e32 v128, v2
	v_mov_b32_e32 v129, v2
	s_andn2_b64 vcc, exec, s[4:5]
	s_cbranch_vccnz .LBB0_4560

.LBB0_4742:
	s_load_dwordx16 s[36:51], s[78:79], 0x1e0
	v_readlane_b32 s4, v255, 2
	v_readlane_b32 s5, v255, 3
	s_mov_b32 s10, s4
	s_ashr_i32 s11, s4, 31
	v_cmp_lt_i64_e32 vcc, s[20:21], v[200:201]
	v_writelane_b32 v255, s4, 2
	s_lshl_b64 s[20:21], s[10:11], 19
	s_waitcnt lgkmcnt(0)
	s_mov_b64 s[28:29], s[48:49]
	v_writelane_b32 v255, s5, 3
	s_add_u32 s4, s28, s20
	s_addc_u32 s5, s29, s21
	s_and_b64 s[20:21], vcc, exec
	s_cselect_b32 s13, s5, s17
	v_writelane_b32 v254, s4, 11
	s_cselect_b32 s15, s4, s16
	v_mov_b32_e32 v2, 0
	v_writelane_b32 v254, s5, 12
	v_readlane_b32 s4, v252, 58
	v_readlane_b32 s5, v252, 59
	s_mov_b32 s10, s4
	s_ashr_i32 s11, s4, 31
	v_writelane_b32 v252, s4, 58
	s_lshl_b64 s[20:21], s[10:11], 19
	s_mov_b32 s26, -2
	v_writelane_b32 v252, s5, 59
	v_readlane_b32 s4, v254, 58
	s_add_u32 s10, s4, s20
	v_readlane_b32 s4, v255, 12
	s_addc_u32 s11, s4, s21
	s_and_b64 s[20:21], vcc, exec
	s_cselect_b32 s22, s11, s19
	v_writelane_b32 v255, s10, 10
	s_cselect_b32 s23, s10, s18
	s_add_u32 s16, s16, 0x40080
	s_addc_u32 s17, s17, 0
	s_add_u32 s24, s18, 0x100
	v_writelane_b32 v255, s11, 11
	s_addc_u32 s25, s19, 0
	v_mov_b32_e32 v3, v2
	v_mov_b32_e32 v4, v2
	v_mov_b32_e32 v5, v2
	v_mov_b32_e32 v66, v2
	v_mov_b32_e32 v67, v2
	v_mov_b32_e32 v68, v2
	v_mov_b32_e32 v69, v2
	s_waitcnt vmcnt(0)
	v_mov_b32_e32 v10, v2
	v_mov_b32_e32 v11, v2
	v_mov_b32_e32 v12, v2
	v_mov_b32_e32 v13, v2
	v_mov_b32_e32 v74, v2
	v_mov_b32_e32 v75, v2
	v_mov_b32_e32 v76, v2
	v_mov_b32_e32 v77, v2
	v_mov_b32_e32 v18, v2
	v_mov_b32_e32 v19, v2
	v_mov_b32_e32 v20, v2
	v_mov_b32_e32 v21, v2
	v_mov_b32_e32 v82, v2
	v_mov_b32_e32 v83, v2
	v_mov_b32_e32 v84, v2
	v_mov_b32_e32 v85, v2
	v_mov_b32_e32 v26, v2
	v_mov_b32_e32 v27, v2
	v_mov_b32_e32 v28, v2
	v_mov_b32_e32 v29, v2
	v_mov_b32_e32 v90, v2
	v_mov_b32_e32 v91, v2
	v_mov_b32_e32 v92, v2
	v_mov_b32_e32 v93, v2
	v_mov_b32_e32 v6, v2
	v_mov_b32_e32 v7, v2
	v_mov_b32_e32 v8, v2
	v_mov_b32_e32 v9, v2
	v_mov_b32_e32 v70, v2
	v_mov_b32_e32 v71, v2
	v_mov_b32_e32 v72, v2
	v_mov_b32_e32 v73, v2
	v_mov_b32_e32 v14, v2
	v_mov_b32_e32 v15, v2
	v_mov_b32_e32 v16, v2
	v_mov_b32_e32 v17, v2
	v_mov_b32_e32 v78, v2
	v_mov_b32_e32 v79, v2
	v_mov_b32_e32 v80, v2
	v_mov_b32_e32 v81, v2
	v_mov_b32_e32 v22, v2
	v_mov_b32_e32 v23, v2
	v_mov_b32_e32 v24, v2
	v_mov_b32_e32 v25, v2
	v_mov_b32_e32 v86, v2
	v_mov_b32_e32 v87, v2
	v_mov_b32_e32 v88, v2
	v_mov_b32_e32 v89, v2
	v_mov_b32_e32 v30, v2
	v_mov_b32_e32 v31, v2
	v_mov_b32_e32 v32, v2
	v_mov_b32_e32 v33, v2
	v_mov_b32_e32 v94, v2
	v_mov_b32_e32 v95, v2
	v_mov_b32_e32 v96, v2
	v_mov_b32_e32 v97, v2
	v_mov_b32_e32 v34, v2
	v_mov_b32_e32 v35, v2
	v_mov_b32_e32 v36, v2
	v_mov_b32_e32 v37, v2
	v_mov_b32_e32 v98, v2
	v_mov_b32_e32 v99, v2
	v_mov_b32_e32 v100, v2
	v_mov_b32_e32 v101, v2
	v_mov_b32_e32 v42, v2
	v_mov_b32_e32 v43, v2
	v_mov_b32_e32 v44, v2
	v_mov_b32_e32 v45, v2
	v_mov_b32_e32 v106, v2
	v_mov_b32_e32 v107, v2
	v_mov_b32_e32 v108, v2
	v_mov_b32_e32 v109, v2
	v_mov_b32_e32 v50, v2
	v_mov_b32_e32 v51, v2
	v_mov_b32_e32 v52, v2
	v_mov_b32_e32 v53, v2
	v_mov_b32_e32 v114, v2
	v_mov_b32_e32 v115, v2
	v_mov_b32_e32 v116, v2
	v_mov_b32_e32 v117, v2
	v_mov_b32_e32 v58, v2
	v_mov_b32_e32 v59, v2
	v_mov_b32_e32 v60, v2
	v_mov_b32_e32 v61, v2
	v_mov_b32_e32 v122, v2
	v_mov_b32_e32 v123, v2
	v_mov_b32_e32 v124, v2
	v_mov_b32_e32 v125, v2
	v_mov_b32_e32 v38, v2
	v_mov_b32_e32 v39, v2
	v_mov_b32_e32 v40, v2
	v_mov_b32_e32 v41, v2
	v_mov_b32_e32 v102, v2
	v_mov_b32_e32 v103, v2
	v_mov_b32_e32 v104, v2
	v_mov_b32_e32 v105, v2
	v_mov_b32_e32 v46, v2
	v_mov_b32_e32 v47, v2
	v_mov_b32_e32 v48, v2
	v_mov_b32_e32 v49, v2
	v_mov_b32_e32 v110, v2
	v_mov_b32_e32 v111, v2
	v_mov_b32_e32 v112, v2
	v_mov_b32_e32 v113, v2
	v_mov_b32_e32 v54, v2
	v_mov_b32_e32 v55, v2
	v_mov_b32_e32 v56, v2
	v_mov_b32_e32 v57, v2
	v_mov_b32_e32 v118, v2
	v_mov_b32_e32 v119, v2
	v_mov_b32_e32 v120, v2
	v_mov_b32_e32 v121, v2
	v_mov_b32_e32 v62, v2
	v_mov_b32_e32 v63, v2
	v_mov_b32_e32 v64, v2
	v_mov_b32_e32 v65, v2
	v_mov_b32_e32 v126, v2
	v_mov_b32_e32 v127, v2
	v_mov_b32_e32 v128, v2
	v_mov_b32_e32 v129, v2
	v_readfirstlane_b32 s98, v248
	s_cmpk_lt_u32 s98, 0x100
	s_cbranch_scc0 .Lmy_lprio9
	s_setprio 1
.Lmy_lprio9:
.LBB0_4743:
	ds_read_b128 v[130:133], v228
	ds_read_b128 v[134:137], v228 offset:1024
	ds_read_b128 v[138:141], v228 offset:2048
	ds_read_b128 v[142:145], v228 offset:3072
	s_add_u32 s18, s16, 0xfffc0080
	s_addc_u32 s19, s17, -1
	s_cmp_eq_u32 s26, 12
	s_cselect_b32 s21, s13, s19
	s_cselect_b32 s20, s15, s18
	s_cselect_b32 s19, s22, s25
	s_cselect_b32 s18, s23, s24
	v_lshl_add_u64 v[204:205], s[16:17], 0, v[196:197]
	s_add_i32 m0, s62, 0xc000
	ds_read_b128 v[146:149], v229
	ds_read_b128 v[150:153], v229 offset:1024
	ds_read_b128 v[154:157], v229 offset:2048
	ds_read_b128 v[158:161], v229 offset:3072
	ds_read_b128 v[162:165], v229 offset:4096
	ds_read_b128 v[166:169], v229 offset:5120
	ds_read_b128 v[170:173], v229 offset:6144
	ds_read_b128 v[174:177], v229 offset:7168
	global_load_lds_dwordx4 v[204:205], off
	v_lshl_add_u64 v[204:205], s[16:17], 0, v[198:199]
	s_add_i32 m0, s62, 0xe000
	s_nop 0
	global_load_lds_dwordx4 v[204:205], off
	s_waitcnt lgkmcnt(8)
	s_barrier
	s_waitcnt lgkmcnt(0)
	s_waitcnt lgkmcnt(0)
	v_mfma_f32_16x16x32_bf16 v[126:129], v[130:133], v[146:149], v[126:129]
	v_mfma_f32_16x16x32_bf16 v[62:65], v[138:141], v[146:149], v[62:65]
	v_mfma_f32_16x16x32_bf16 v[118:121], v[130:133], v[154:157], v[118:121]
	v_mfma_f32_16x16x32_bf16 v[54:57], v[138:141], v[154:157], v[54:57]
	v_mfma_f32_16x16x32_bf16 v[110:113], v[130:133], v[162:165], v[110:113]
	v_mfma_f32_16x16x32_bf16 v[46:49], v[138:141], v[162:165], v[46:49]
	v_mfma_f32_16x16x32_bf16 v[102:105], v[130:133], v[170:173], v[102:105]
	v_mfma_f32_16x16x32_bf16 v[38:41], v[138:141], v[170:173], v[38:41]
	v_mfma_f32_16x16x32_bf16 v[126:129], v[134:137], v[150:153], v[126:129]
	v_mfma_f32_16x16x32_bf16 v[62:65], v[142:145], v[150:153], v[62:65]
	v_mfma_f32_16x16x32_bf16 v[118:121], v[134:137], v[158:161], v[118:121]
	v_mfma_f32_16x16x32_bf16 v[54:57], v[142:145], v[158:161], v[54:57]
	v_mfma_f32_16x16x32_bf16 v[110:113], v[134:137], v[166:169], v[110:113]
	v_mfma_f32_16x16x32_bf16 v[46:49], v[142:145], v[166:169], v[46:49]
	v_mfma_f32_16x16x32_bf16 v[102:105], v[134:137], v[174:177], v[102:105]
	v_mfma_f32_16x16x32_bf16 v[38:41], v[142:145], v[174:177], v[38:41]
	s_barrier
	s_add_i32 s27, s33, s1
	v_lshl_add_u64 v[220:221], s[18:19], 0, v[184:185]
	s_mov_b32 m0, s27
	ds_read_b128 v[204:207], v230
	ds_read_b128 v[208:211], v230 offset:1024
	ds_read_b128 v[212:215], v230 offset:2048
	ds_read_b128 v[216:219], v230 offset:3072
	global_load_lds_dwordx4 v[220:221], off
	v_lshl_add_u64 v[222:223], s[18:19], 0, v[188:189]
	s_add_i32 m0, s27, 0x2000
	s_nop 0
	global_load_lds_dwordx4 v[222:223], off
	s_barrier
	s_waitcnt lgkmcnt(0)
	s_waitcnt lgkmcnt(0)
	v_mfma_f32_16x16x32_bf16 v[122:125], v[204:207], v[146:149], v[122:125]
	v_mfma_f32_16x16x32_bf16 v[58:61], v[212:215], v[146:149], v[58:61]
	v_mfma_f32_16x16x32_bf16 v[114:117], v[204:207], v[154:157], v[114:117]
	v_mfma_f32_16x16x32_bf16 v[50:53], v[212:215], v[154:157], v[50:53]
	v_mfma_f32_16x16x32_bf16 v[106:109], v[204:207], v[162:165], v[106:109]
	v_mfma_f32_16x16x32_bf16 v[42:45], v[212:215], v[162:165], v[42:45]
	v_mfma_f32_16x16x32_bf16 v[98:101], v[204:207], v[170:173], v[98:101]
	v_mfma_f32_16x16x32_bf16 v[34:37], v[212:215], v[170:173], v[34:37]
	v_mfma_f32_16x16x32_bf16 v[122:125], v[208:211], v[150:153], v[122:125]
	v_mfma_f32_16x16x32_bf16 v[58:61], v[216:219], v[150:153], v[58:61]
	v_mfma_f32_16x16x32_bf16 v[114:117], v[208:211], v[158:161], v[114:117]
	v_mfma_f32_16x16x32_bf16 v[50:53], v[216:219], v[158:161], v[50:53]
	v_mfma_f32_16x16x32_bf16 v[106:109], v[208:211], v[166:169], v[106:109]
	v_mfma_f32_16x16x32_bf16 v[42:45], v[216:219], v[166:169], v[42:45]
	v_mfma_f32_16x16x32_bf16 v[98:101], v[208:211], v[174:177], v[98:101]
	v_mfma_f32_16x16x32_bf16 v[34:37], v[216:219], v[174:177], v[34:37]
	s_mov_b32 m0, s62
	v_lshl_add_u64 v[224:225], s[20:21], 0, v[182:183]
	s_barrier
	ds_read_b128 v[146:149], v229 offset:16384
	ds_read_b128 v[150:153], v229 offset:17408
	ds_read_b128 v[154:157], v229 offset:18432
	ds_read_b128 v[158:161], v229 offset:19456
	ds_read_b128 v[162:165], v229 offset:20480
	ds_read_b128 v[166:169], v229 offset:21504
	ds_read_b128 v[170:173], v229 offset:22528
	ds_read_b128 v[174:177], v229 offset:23552
	global_load_lds_dwordx4 v[224:225], off
	v_lshl_add_u64 v[232:233], s[20:21], 0, v[186:187]
	s_mov_b32 m0, s63
	s_nop 0
	global_load_lds_dwordx4 v[232:233], off
	s_barrier
	s_waitcnt lgkmcnt(0)
	s_waitcnt lgkmcnt(0)
	v_mfma_f32_16x16x32_bf16 v[94:97], v[130:133], v[146:149], v[94:97]
	v_mfma_f32_16x16x32_bf16 v[30:33], v[138:141], v[146:149], v[30:33]
	v_mfma_f32_16x16x32_bf16 v[86:89], v[130:133], v[154:157], v[86:89]
	v_mfma_f32_16x16x32_bf16 v[22:25], v[138:141], v[154:157], v[22:25]
	v_mfma_f32_16x16x32_bf16 v[78:81], v[130:133], v[162:165], v[78:81]
	v_mfma_f32_16x16x32_bf16 v[14:17], v[138:141], v[162:165], v[14:17]
	v_mfma_f32_16x16x32_bf16 v[70:73], v[130:133], v[170:173], v[70:73]
	v_mfma_f32_16x16x32_bf16 v[6:9], v[138:141], v[170:173], v[6:9]
	v_mfma_f32_16x16x32_bf16 v[94:97], v[134:137], v[150:153], v[94:97]
	v_mfma_f32_16x16x32_bf16 v[30:33], v[142:145], v[150:153], v[30:33]
	v_mfma_f32_16x16x32_bf16 v[86:89], v[134:137], v[158:161], v[86:89]
	v_mfma_f32_16x16x32_bf16 v[22:25], v[142:145], v[158:161], v[22:25]
	v_mfma_f32_16x16x32_bf16 v[78:81], v[134:137], v[166:169], v[78:81]
	v_mfma_f32_16x16x32_bf16 v[14:17], v[142:145], v[166:169], v[14:17]
	v_mfma_f32_16x16x32_bf16 v[70:73], v[134:137], v[174:177], v[70:73]
	v_mfma_f32_16x16x32_bf16 v[6:9], v[142:145], v[174:177], v[6:9]
	s_barrier
	s_add_u32 s28, s18, 0x40000
	s_addc_u32 s29, s19, 0
	s_add_i32 s27, s83, s1
	v_lshl_add_u64 v[130:131], s[28:29], 0, v[184:185]
	s_mov_b32 m0, s27
	s_nop 0
	global_load_lds_dwordx4 v[130:131], off
	v_lshl_add_u64 v[130:131], s[28:29], 0, v[188:189]
	s_add_i32 m0, s27, 0x2000
	s_nop 0
	global_load_lds_dwordx4 v[130:131], off
	s_waitcnt vmcnt(6)
	s_barrier
	v_mfma_f32_16x16x32_bf16 v[90:93], v[204:207], v[146:149], v[90:93]
	v_mfma_f32_16x16x32_bf16 v[26:29], v[212:215], v[146:149], v[26:29]
	v_mfma_f32_16x16x32_bf16 v[82:85], v[204:207], v[154:157], v[82:85]
	v_mfma_f32_16x16x32_bf16 v[18:21], v[212:215], v[154:157], v[18:21]
	v_mfma_f32_16x16x32_bf16 v[74:77], v[204:207], v[162:165], v[74:77]
	v_mfma_f32_16x16x32_bf16 v[10:13], v[212:215], v[162:165], v[10:13]
	v_mfma_f32_16x16x32_bf16 v[66:69], v[204:207], v[170:173], v[66:69]
	v_mfma_f32_16x16x32_bf16 v[2:5], v[212:215], v[170:173], v[2:5]
	v_mfma_f32_16x16x32_bf16 v[90:93], v[208:211], v[150:153], v[90:93]
	v_mfma_f32_16x16x32_bf16 v[26:29], v[216:219], v[150:153], v[26:29]
	v_mfma_f32_16x16x32_bf16 v[82:85], v[208:211], v[158:161], v[82:85]
	v_mfma_f32_16x16x32_bf16 v[18:21], v[216:219], v[158:161], v[18:21]
	v_mfma_f32_16x16x32_bf16 v[74:77], v[208:211], v[166:169], v[74:77]
	v_mfma_f32_16x16x32_bf16 v[10:13], v[216:219], v[166:169], v[10:13]
	v_mfma_f32_16x16x32_bf16 v[66:69], v[208:211], v[174:177], v[66:69]
	v_mfma_f32_16x16x32_bf16 v[2:5], v[216:219], v[174:177], v[2:5]
	s_add_i32 s27, 0, 0x18000
	v_add_u32_e32 v142, s27, v1
	s_barrier
	ds_read_b128 v[130:133], v142
	ds_read_b128 v[134:137], v142 offset:1024
	ds_read_b128 v[138:141], v142 offset:2048
	ds_read_b128 v[142:145], v142 offset:3072
	s_add_u32 s20, s20, 0x40000
	s_addc_u32 s21, s21, 0
	s_mov_b32 m0, s6
	v_lshl_add_u64 v[204:205], s[20:21], 0, v[182:183]
	ds_read_b128 v[146:149], v229 offset:32768
	ds_read_b128 v[150:153], v229 offset:33792
	ds_read_b128 v[154:157], v229 offset:34816
	ds_read_b128 v[158:161], v229 offset:35840
	ds_read_b128 v[162:165], v229 offset:36864
	ds_read_b128 v[166:169], v229 offset:37888
	ds_read_b128 v[170:173], v229 offset:38912
	ds_read_b128 v[174:177], v229 offset:39936
	global_load_lds_dwordx4 v[204:205], off
	v_lshl_add_u64 v[204:205], s[20:21], 0, v[186:187]
	s_mov_b32 m0, s7
	s_nop 0
	global_load_lds_dwordx4 v[204:205], off
	s_waitcnt lgkmcnt(8)
	s_barrier
	s_waitcnt lgkmcnt(0)
	s_waitcnt lgkmcnt(0)
	v_mfma_f32_16x16x32_bf16 v[126:129], v[130:133], v[146:149], v[126:129]
	v_mfma_f32_16x16x32_bf16 v[62:65], v[138:141], v[146:149], v[62:65]
	v_mfma_f32_16x16x32_bf16 v[118:121], v[130:133], v[154:157], v[118:121]
	v_mfma_f32_16x16x32_bf16 v[54:57], v[138:141], v[154:157], v[54:57]
	v_mfma_f32_16x16x32_bf16 v[110:113], v[130:133], v[162:165], v[110:113]
	v_mfma_f32_16x16x32_bf16 v[46:49], v[138:141], v[162:165], v[46:49]
	v_mfma_f32_16x16x32_bf16 v[102:105], v[130:133], v[170:173], v[102:105]
	v_mfma_f32_16x16x32_bf16 v[38:41], v[138:141], v[170:173], v[38:41]
	v_mfma_f32_16x16x32_bf16 v[126:129], v[134:137], v[150:153], v[126:129]
	v_mfma_f32_16x16x32_bf16 v[62:65], v[142:145], v[150:153], v[62:65]
	v_mfma_f32_16x16x32_bf16 v[118:121], v[134:137], v[158:161], v[118:121]
	v_mfma_f32_16x16x32_bf16 v[54:57], v[142:145], v[158:161], v[54:57]
	v_mfma_f32_16x16x32_bf16 v[110:113], v[134:137], v[166:169], v[110:113]
	v_mfma_f32_16x16x32_bf16 v[46:49], v[142:145], v[166:169], v[46:49]
	v_mfma_f32_16x16x32_bf16 v[102:105], v[134:137], v[174:177], v[102:105]
	v_mfma_f32_16x16x32_bf16 v[38:41], v[142:145], v[174:177], v[38:41]
	s_barrier
	s_add_i32 s20, 0, 0x1c000
	s_add_i32 s21, s27, s1
	v_add_u32_e32 v190, s20, v1
	v_lshl_add_u64 v[220:221], v[220:221], 0, s[2:3]
	s_mov_b32 m0, s21
	ds_read_b128 v[204:207], v190
	ds_read_b128 v[208:211], v190 offset:1024
	ds_read_b128 v[212:215], v190 offset:2048
	ds_read_b128 v[216:219], v190 offset:3072
	global_load_lds_dwordx4 v[220:221], off
	v_lshl_add_u64 v[220:221], v[222:223], 0, s[2:3]
	s_add_i32 m0, s21, 0x2000
	s_nop 0
	global_load_lds_dwordx4 v[220:221], off
	s_barrier
	s_waitcnt lgkmcnt(0)
	s_waitcnt lgkmcnt(0)
	v_mfma_f32_16x16x32_bf16 v[122:125], v[204:207], v[146:149], v[122:125]
	v_mfma_f32_16x16x32_bf16 v[58:61], v[212:215], v[146:149], v[58:61]
	v_mfma_f32_16x16x32_bf16 v[114:117], v[204:207], v[154:157], v[114:117]
	v_mfma_f32_16x16x32_bf16 v[50:53], v[212:215], v[154:157], v[50:53]
	v_mfma_f32_16x16x32_bf16 v[106:109], v[204:207], v[162:165], v[106:109]
	v_mfma_f32_16x16x32_bf16 v[42:45], v[212:215], v[162:165], v[42:45]
	v_mfma_f32_16x16x32_bf16 v[98:101], v[204:207], v[170:173], v[98:101]
	v_mfma_f32_16x16x32_bf16 v[34:37], v[212:215], v[170:173], v[34:37]
	v_mfma_f32_16x16x32_bf16 v[122:125], v[208:211], v[150:153], v[122:125]
	v_mfma_f32_16x16x32_bf16 v[58:61], v[216:219], v[150:153], v[58:61]
	v_mfma_f32_16x16x32_bf16 v[114:117], v[208:211], v[158:161], v[114:117]
	v_mfma_f32_16x16x32_bf16 v[50:53], v[216:219], v[158:161], v[50:53]
	v_mfma_f32_16x16x32_bf16 v[106:109], v[208:211], v[166:169], v[106:109]
	v_mfma_f32_16x16x32_bf16 v[42:45], v[216:219], v[166:169], v[42:45]
	v_mfma_f32_16x16x32_bf16 v[98:101], v[208:211], v[174:177], v[98:101]
	v_mfma_f32_16x16x32_bf16 v[34:37], v[216:219], v[174:177], v[34:37]
	s_mov_b32 m0, s80
	v_lshl_add_u64 v[220:221], v[224:225], 0, s[2:3]
	s_barrier
	ds_read_b128 v[146:149], v229 offset:49152
	ds_read_b128 v[150:153], v229 offset:50176
	ds_read_b128 v[154:157], v229 offset:51200
	ds_read_b128 v[158:161], v229 offset:52224
	ds_read_b128 v[162:165], v229 offset:53248
	ds_read_b128 v[166:169], v229 offset:54272
	ds_read_b128 v[170:173], v229 offset:55296
	ds_read_b128 v[174:177], v229 offset:56320
	global_load_lds_dwordx4 v[220:221], off
	v_lshl_add_u64 v[220:221], v[232:233], 0, s[2:3]
	s_mov_b32 m0, s81
	s_nop 0
	global_load_lds_dwordx4 v[220:221], off
	s_barrier
	s_waitcnt lgkmcnt(0)
	s_waitcnt lgkmcnt(0)
	v_mfma_f32_16x16x32_bf16 v[94:97], v[130:133], v[146:149], v[94:97]
	v_mfma_f32_16x16x32_bf16 v[30:33], v[138:141], v[146:149], v[30:33]
	v_mfma_f32_16x16x32_bf16 v[86:89], v[130:133], v[154:157], v[86:89]
	v_mfma_f32_16x16x32_bf16 v[22:25], v[138:141], v[154:157], v[22:25]
	v_mfma_f32_16x16x32_bf16 v[78:81], v[130:133], v[162:165], v[78:81]
	v_mfma_f32_16x16x32_bf16 v[14:17], v[138:141], v[162:165], v[14:17]
	v_mfma_f32_16x16x32_bf16 v[70:73], v[130:133], v[170:173], v[70:73]
	v_mfma_f32_16x16x32_bf16 v[6:9], v[138:141], v[170:173], v[6:9]
	v_mfma_f32_16x16x32_bf16 v[94:97], v[134:137], v[150:153], v[94:97]
	v_mfma_f32_16x16x32_bf16 v[30:33], v[142:145], v[150:153], v[30:33]
	v_mfma_f32_16x16x32_bf16 v[86:89], v[134:137], v[158:161], v[86:89]
	v_mfma_f32_16x16x32_bf16 v[22:25], v[142:145], v[158:161], v[22:25]
	v_mfma_f32_16x16x32_bf16 v[78:81], v[134:137], v[166:169], v[78:81]
	v_mfma_f32_16x16x32_bf16 v[14:17], v[142:145], v[166:169], v[14:17]
	v_mfma_f32_16x16x32_bf16 v[70:73], v[134:137], v[174:177], v[70:73]
	v_mfma_f32_16x16x32_bf16 v[6:9], v[142:145], v[174:177], v[6:9]
	s_barrier
	s_add_u32 s18, s18, 0x40080
	s_addc_u32 s19, s19, 0
	s_add_i32 s20, s20, s1
	v_lshl_add_u64 v[130:131], s[18:19], 0, v[184:185]
	s_mov_b32 m0, s20
	s_nop 0
	global_load_lds_dwordx4 v[130:131], off
	v_lshl_add_u64 v[130:131], s[18:19], 0, v[188:189]
	s_add_i32 m0, s20, 0x2000
	s_nop 0
	global_load_lds_dwordx4 v[130:131], off
	s_waitcnt vmcnt(6)
	s_barrier
	v_mfma_f32_16x16x32_bf16 v[90:93], v[204:207], v[146:149], v[90:93]
	v_mfma_f32_16x16x32_bf16 v[26:29], v[212:215], v[146:149], v[26:29]
	v_mfma_f32_16x16x32_bf16 v[82:85], v[204:207], v[154:157], v[82:85]
	v_mfma_f32_16x16x32_bf16 v[18:21], v[212:215], v[154:157], v[18:21]
	v_mfma_f32_16x16x32_bf16 v[74:77], v[204:207], v[162:165], v[74:77]
	v_mfma_f32_16x16x32_bf16 v[10:13], v[212:215], v[162:165], v[10:13]
	v_mfma_f32_16x16x32_bf16 v[66:69], v[204:207], v[170:173], v[66:69]
	v_mfma_f32_16x16x32_bf16 v[2:5], v[212:215], v[170:173], v[2:5]
	v_mfma_f32_16x16x32_bf16 v[90:93], v[208:211], v[150:153], v[90:93]
	v_mfma_f32_16x16x32_bf16 v[26:29], v[216:219], v[150:153], v[26:29]
	v_mfma_f32_16x16x32_bf16 v[82:85], v[208:211], v[158:161], v[82:85]
	v_mfma_f32_16x16x32_bf16 v[18:21], v[216:219], v[158:161], v[18:21]
	v_mfma_f32_16x16x32_bf16 v[74:77], v[208:211], v[166:169], v[74:77]
	v_mfma_f32_16x16x32_bf16 v[10:13], v[216:219], v[166:169], v[10:13]
	v_mfma_f32_16x16x32_bf16 v[66:69], v[208:211], v[174:177], v[66:69]
	v_mfma_f32_16x16x32_bf16 v[2:5], v[216:219], v[174:177], v[2:5]
	s_add_i32 s26, s26, 2
	s_add_u32 s16, s16, 0x100
	s_addc_u32 s17, s17, 0
	s_add_u32 s24, s24, 0x100
	s_addc_u32 s25, s25, 0
	s_cmp_gt_u32 s26, 13
	s_barrier
	s_cbranch_scc0 .LBB0_4743
	s_mov_b64 s[16:17], -1
	s_cmp_lt_i32 s12, 64
	v_lshl_or_b32 v204, s14, 7, v181
	s_cbranch_scc0 .Lmy_ffnB_sample
	s_load_dwordx2 s[36:37], s[78:79], 0x268
	s_load_dwordx2 s[38:39], s[78:79], 0x2a0
	s_load_dwordx4 s[40:43], s[78:79], 0x70
	s_load_dwordx2 s[44:45], s[78:79], 0x120
	v_and_b32_e32 v204, 15, v248
	v_bfe_u32 v205, v248, 8, 1
	v_bfe_u32 v206, v248, 6, 2
	v_bfe_u32 v207, v248, 4, 2
	v_lshlrev_b32_e32 v206, 5, v206
	v_lshl_or_b32 v206, v207, 3, v206
	s_lshl_b32 s13, s14, 7
	v_add_u32_e32 v206, s13, v206
	s_lshl_b32 s13, s12, 8
	v_lshl_add_u32 v207, v205, 6, v204
	v_add_u32_e32 v207, s13, v207
	v_mul_u32_u24_e32 v231, 0x1600, v207
	v_lshl_add_u32 v231, v206, 1, v231
	v_lshlrev_b32_e32 v232, 2, v206
	s_lshl_b32 s13, s12, 4
	v_lshl_add_u32 v233, v205, 2, s13
	v_add_u32_e32 v208, -12, v204
	v_cmp_gt_u32_e32 vcc, 2, v204
	s_nop 1
	v_cndmask_b32_e32 v208, v208, v204, vcc
	v_add_u32_e32 v233, v233, v208
	v_mul_u32_u24_e32 v233, 0x2c00, v233
	v_lshl_add_u32 v233, v206, 1, v233
	s_lshr_b32 s13, s12, 3
	s_lshl_b32 s13, s13, 1
	s_add_i32 s13, s13, 2
	v_add_u32_e32 v234, s13, v204
	v_mul_u32_u24_e32 v234, 0x5800, v234
	v_lshl_add_u32 v234, v206, 2, v234
	v_readfirstlane_b32 s4, v248
	s_lshr_b32 s4, s4, 8
	s_and_b32 s5, s12, 7
	s_cmp_eq_u32 s5, 7
	s_cselect_b32 s5, 1, 0
	s_and_b32 s5, s5, s4
	s_waitcnt lgkmcnt(0)
	s_add_u32 s40, s40, 0x10800
	s_addc_u32 s41, s41, 0
	s_add_u32 s42, s42, 0x5800
	s_addc_u32 s43, s43, 0
	global_load_dwordx4 v[130:133], v232, s[40:41]
	v_add_u32_e32 v213, 0x5800, v232
	global_load_dwordx4 v[134:137], v213, s[40:41]
	v_add_u32_e32 v214, 0xb000, v232
	global_load_dwordx4 v[138:141], v214, s[40:41]
	global_load_dwordx4 v[142:145], v232, s[42:43]
	v_add_u32_e32 v215, 0x2c00, v232
	global_load_dwordx4 v[146:149], v215, s[40:41]
	v_add_u32_e32 v216, 0x8400, v232
	global_load_dwordx4 v[150:153], v216, s[40:41]
	v_add_u32_e32 v217, 0xdc00, v232
	global_load_dwordx4 v[154:157], v217, s[40:41]
	v_add_u32_e32 v218, 0x2c00, v232
	global_load_dwordx4 v[158:161], v218, s[42:43]
	s_mov_b32 exec_lo, 0x30003
	s_mov_b32 exec_hi, 0x30003
	v_cvt_pk_bf16_f32 v162, v126, v127
	v_cvt_pk_bf16_f32 v163, v128, v129
	global_store_dwordx2 v233, v[162:163], s[38:39]
	v_cvt_pk_bf16_f32 v164, v122, v123
	v_cvt_pk_bf16_f32 v165, v124, v125
	v_add_u32_e32 v220, 0x1600, v233
	global_store_dwordx2 v220, v[164:165], s[38:39]
	v_cvt_pk_bf16_f32 v166, v94, v95
	v_cvt_pk_bf16_f32 v167, v96, v97
	v_add_u32_e32 v221, 0x16000, v233
	global_store_dwordx2 v221, v[166:167], s[38:39]
	v_cvt_pk_bf16_f32 v168, v90, v91
	v_cvt_pk_bf16_f32 v169, v92, v93
	v_add_u32_e32 v222, 0x17600, v233
	global_store_dwordx2 v222, v[168:169], s[38:39]
	v_cvt_pk_bf16_f32 v170, v62, v63
	v_cvt_pk_bf16_f32 v171, v64, v65
	v_add_u32_e32 v223, 0x8, v233
	global_store_dwordx2 v223, v[170:171], s[38:39]
	v_cvt_pk_bf16_f32 v172, v58, v59
	v_cvt_pk_bf16_f32 v173, v60, v61
	v_add_u32_e32 v224, 0x1608, v233
	global_store_dwordx2 v224, v[172:173], s[38:39]
	v_cvt_pk_bf16_f32 v174, v30, v31
	v_cvt_pk_bf16_f32 v175, v32, v33
	v_add_u32_e32 v225, 0x16008, v233
	global_store_dwordx2 v225, v[174:175], s[38:39]
	v_cvt_pk_bf16_f32 v176, v26, v27
	v_cvt_pk_bf16_f32 v177, v28, v29
	v_add_u32_e32 v226, 0x17608, v233
	global_store_dwordx2 v226, v[176:177], s[38:39]
	s_mov_b32 exec_lo, 0xc000c000
	s_mov_b32 exec_hi, 0xc000c000
	v_cvt_pk_bf16_f32 v162, v102, v103
	v_cvt_pk_bf16_f32 v163, v104, v105
	global_store_dwordx2 v233, v[162:163], s[38:39]
	v_cvt_pk_bf16_f32 v164, v98, v99
	v_cvt_pk_bf16_f32 v165, v100, v101
	v_add_u32_e32 v220, 0x1600, v233
	global_store_dwordx2 v220, v[164:165], s[38:39]
	v_cvt_pk_bf16_f32 v166, v70, v71
	v_cvt_pk_bf16_f32 v167, v72, v73
	v_add_u32_e32 v221, 0x16000, v233
	global_store_dwordx2 v221, v[166:167], s[38:39]
	v_cvt_pk_bf16_f32 v168, v66, v67
	v_cvt_pk_bf16_f32 v169, v68, v69
	v_add_u32_e32 v222, 0x17600, v233
	global_store_dwordx2 v222, v[168:169], s[38:39]
	v_cvt_pk_bf16_f32 v170, v38, v39
	v_cvt_pk_bf16_f32 v171, v40, v41
	v_add_u32_e32 v223, 0x8, v233
	global_store_dwordx2 v223, v[170:171], s[38:39]
	v_cvt_pk_bf16_f32 v172, v34, v35
	v_cvt_pk_bf16_f32 v173, v36, v37
	v_add_u32_e32 v224, 0x1608, v233
	global_store_dwordx2 v224, v[172:173], s[38:39]
	v_cvt_pk_bf16_f32 v174, v6, v7
	v_cvt_pk_bf16_f32 v175, v8, v9
	v_add_u32_e32 v225, 0x16008, v233
	global_store_dwordx2 v225, v[174:175], s[38:39]
	v_cvt_pk_bf16_f32 v176, v2, v3
	v_cvt_pk_bf16_f32 v177, v4, v5
	v_add_u32_e32 v226, 0x17608, v233
	global_store_dwordx2 v226, v[176:177], s[38:39]
	s_cmp_lg_u32 s5, 0
	s_cbranch_scc0 .Lmy_ffnB_ncp
	global_store_dwordx4 v234, v[70:73], s[44:45]
	v_add_u32_e32 v220, 0x2c00, v234
	global_store_dwordx4 v220, v[66:69], s[44:45]
	v_add_u32_e32 v221, 0x10, v234
	global_store_dwordx4 v221, v[6:9], s[44:45]
	v_add_u32_e32 v222, 0x2c10, v234
	global_store_dwordx4 v222, v[2:5], s[44:45]

.LBB0_5226:
	s_add_u32 s43, s14, 0x100
	s_addc_u32 s44, s15, 0
	v_lshl_add_u64 v[142:143], s[8:9], 0, v[134:135]
	v_lshl_add_u64 v[144:145], s[8:9], 0, v[136:137]
	s_mov_b32 s45, -2
	s_mov_b64 s[14:15], 0
	v_readfirstlane_b32 s98, v248
	s_cmpk_lt_u32 s98, 0x100
	s_cbranch_scc0 .Lmy_lprio10
	s_setprio 1
.Lmy_lprio10:
.LBB0_5227:
	v_add_u32_e32 v0, s38, v147
	s_add_u32 s16, s8, s14
	ds_read_b128 v[150:153], v0
	ds_read_b128 v[154:157], v0 offset:1024
	ds_read_b128 v[158:161], v0 offset:2048
	ds_read_b128 v[162:165], v0 offset:3072
	s_addc_u32 s17, s9, s15
	s_add_u32 s16, s16, 0x100
	s_addc_u32 s17, s17, 0
	s_add_u32 s46, s43, s14
	s_addc_u32 s47, s44, s15
	s_cmpk_eq_i32 s14, 0x1500
	s_cselect_b32 s19, s13, s17
	s_cselect_b32 s18, s12, s16
	s_cselect_b32 s17, s3, s47
	s_cselect_b32 s16, s2, s46
	v_lshl_add_u64 v[202:203], v[142:143], 0, s[14:15]
	s_add_i32 m0, s29, 0xc000
	ds_read_b128 v[166:169], v148
	ds_read_b128 v[170:173], v148 offset:1024
	ds_read_b128 v[174:177], v148 offset:2048
	ds_read_b128 v[182:185], v148 offset:3072
	ds_read_b128 v[186:189], v148 offset:4096
	ds_read_b128 v[190:193], v148 offset:5120
	ds_read_b128 v[194:197], v148 offset:6144
	ds_read_b128 v[198:201], v148 offset:7168
	global_load_lds_dwordx4 v[202:203], off
	v_lshl_add_u64 v[202:203], v[144:145], 0, s[14:15]
	s_add_i32 m0, s29, 0xe000
	s_nop 0
	global_load_lds_dwordx4 v[202:203], off
	s_waitcnt lgkmcnt(8)
	s_barrier
	s_waitcnt lgkmcnt(0)
	s_waitcnt lgkmcnt(0)
	v_mfma_f32_16x16x32_bf16 v[126:129], v[150:153], v[166:169], v[126:129]
	v_mfma_f32_16x16x32_bf16 v[122:125], v[158:161], v[166:169], v[122:125]
	v_mfma_f32_16x16x32_bf16 v[110:113], v[150:153], v[174:177], v[110:113]
	v_mfma_f32_16x16x32_bf16 v[106:109], v[158:161], v[174:177], v[106:109]
	v_mfma_f32_16x16x32_bf16 v[94:97], v[150:153], v[186:189], v[94:97]
	v_mfma_f32_16x16x32_bf16 v[90:93], v[158:161], v[186:189], v[90:93]
	v_mfma_f32_16x16x32_bf16 v[78:81], v[150:153], v[194:197], v[78:81]
	v_mfma_f32_16x16x32_bf16 v[74:77], v[158:161], v[194:197], v[74:77]
	v_mfma_f32_16x16x32_bf16 v[126:129], v[154:157], v[170:173], v[126:129]
	v_mfma_f32_16x16x32_bf16 v[122:125], v[162:165], v[170:173], v[122:125]
	v_mfma_f32_16x16x32_bf16 v[110:113], v[154:157], v[182:185], v[110:113]
	v_mfma_f32_16x16x32_bf16 v[106:109], v[162:165], v[182:185], v[106:109]
	v_mfma_f32_16x16x32_bf16 v[94:97], v[154:157], v[190:193], v[94:97]
	v_mfma_f32_16x16x32_bf16 v[90:93], v[162:165], v[190:193], v[90:93]
	v_mfma_f32_16x16x32_bf16 v[78:81], v[154:157], v[198:201], v[78:81]
	v_mfma_f32_16x16x32_bf16 v[74:77], v[162:165], v[198:201], v[74:77]
	s_barrier
	s_add_i32 s46, s38, s28
	v_add_u32_e32 v0, s39, v147
	v_lshl_add_u64 v[218:219], s[16:17], 0, v[130:131]
	s_mov_b32 m0, s46
	ds_read_b128 v[202:205], v0
	ds_read_b128 v[206:209], v0 offset:1024
	ds_read_b128 v[210:213], v0 offset:2048
	ds_read_b128 v[214:217], v0 offset:3072
	global_load_lds_dwordx4 v[218:219], off
	v_lshl_add_u64 v[220:221], s[16:17], 0, v[132:133]
	s_add_i32 m0, s46, 0x2000
	s_nop 0
	global_load_lds_dwordx4 v[220:221], off
	s_barrier
	s_waitcnt lgkmcnt(0)
	s_waitcnt lgkmcnt(0)
	v_mfma_f32_16x16x32_bf16 v[118:121], v[202:205], v[166:169], v[118:121]
	v_mfma_f32_16x16x32_bf16 v[114:117], v[210:213], v[166:169], v[114:117]
	v_mfma_f32_16x16x32_bf16 v[102:105], v[202:205], v[174:177], v[102:105]
	v_mfma_f32_16x16x32_bf16 v[98:101], v[210:213], v[174:177], v[98:101]
	v_mfma_f32_16x16x32_bf16 v[86:89], v[202:205], v[186:189], v[86:89]
	v_mfma_f32_16x16x32_bf16 v[82:85], v[210:213], v[186:189], v[82:85]
	v_mfma_f32_16x16x32_bf16 v[70:73], v[202:205], v[194:197], v[70:73]
	v_mfma_f32_16x16x32_bf16 v[66:69], v[210:213], v[194:197], v[66:69]
	v_mfma_f32_16x16x32_bf16 v[118:121], v[206:209], v[170:173], v[118:121]
	v_mfma_f32_16x16x32_bf16 v[114:117], v[214:217], v[170:173], v[114:117]
	v_mfma_f32_16x16x32_bf16 v[102:105], v[206:209], v[182:185], v[102:105]
	v_mfma_f32_16x16x32_bf16 v[98:101], v[214:217], v[182:185], v[98:101]
	v_mfma_f32_16x16x32_bf16 v[86:89], v[206:209], v[190:193], v[86:89]
	v_mfma_f32_16x16x32_bf16 v[82:85], v[214:217], v[190:193], v[82:85]
	v_mfma_f32_16x16x32_bf16 v[70:73], v[206:209], v[198:201], v[70:73]
	v_mfma_f32_16x16x32_bf16 v[66:69], v[214:217], v[198:201], v[66:69]
	s_mov_b32 m0, s29
	v_lshl_add_u64 v[222:223], s[18:19], 0, v[130:131]
	s_barrier
	ds_read_b128 v[166:169], v148 offset:16384
	ds_read_b128 v[170:173], v148 offset:17408
	ds_read_b128 v[174:177], v148 offset:18432
	ds_read_b128 v[182:185], v148 offset:19456
	ds_read_b128 v[186:189], v148 offset:20480
	ds_read_b128 v[190:193], v148 offset:21504
	ds_read_b128 v[194:197], v148 offset:22528
	ds_read_b128 v[198:201], v148 offset:23552
	global_load_lds_dwordx4 v[222:223], off
	v_lshl_add_u64 v[224:225], s[18:19], 0, v[132:133]
	s_mov_b32 m0, s30
	s_nop 0
	global_load_lds_dwordx4 v[224:225], off
	s_barrier
	s_waitcnt lgkmcnt(0)
	s_waitcnt lgkmcnt(0)
	v_mfma_f32_16x16x32_bf16 v[62:65], v[150:153], v[166:169], v[62:65]
	v_mfma_f32_16x16x32_bf16 v[58:61], v[158:161], v[166:169], v[58:61]
	v_mfma_f32_16x16x32_bf16 v[46:49], v[150:153], v[174:177], v[46:49]
	v_mfma_f32_16x16x32_bf16 v[42:45], v[158:161], v[174:177], v[42:45]
	v_mfma_f32_16x16x32_bf16 v[30:33], v[150:153], v[186:189], v[30:33]
	v_mfma_f32_16x16x32_bf16 v[26:29], v[158:161], v[186:189], v[26:29]
	v_mfma_f32_16x16x32_bf16 v[14:17], v[150:153], v[194:197], v[14:17]
	v_mfma_f32_16x16x32_bf16 v[10:13], v[158:161], v[194:197], v[10:13]
	v_mfma_f32_16x16x32_bf16 v[62:65], v[154:157], v[170:173], v[62:65]
	v_mfma_f32_16x16x32_bf16 v[58:61], v[162:165], v[170:173], v[58:61]
	v_mfma_f32_16x16x32_bf16 v[46:49], v[154:157], v[182:185], v[46:49]
	v_mfma_f32_16x16x32_bf16 v[42:45], v[162:165], v[182:185], v[42:45]
	v_mfma_f32_16x16x32_bf16 v[30:33], v[154:157], v[190:193], v[30:33]
	v_mfma_f32_16x16x32_bf16 v[26:29], v[162:165], v[190:193], v[26:29]
	v_mfma_f32_16x16x32_bf16 v[14:17], v[154:157], v[198:201], v[14:17]
	v_mfma_f32_16x16x32_bf16 v[10:13], v[162:165], v[198:201], v[10:13]
	s_barrier
	s_add_u32 s46, s16, 0xb0000
	s_addc_u32 s47, s17, 0
	s_add_i32 s48, s39, s28
	v_lshl_add_u64 v[150:151], s[46:47], 0, v[130:131]
	s_mov_b32 m0, s48
	s_nop 0
	global_load_lds_dwordx4 v[150:151], off
	v_lshl_add_u64 v[150:151], s[46:47], 0, v[132:133]
	s_add_i32 m0, s48, 0x2000
	s_nop 0
	global_load_lds_dwordx4 v[150:151], off
	s_waitcnt vmcnt(6)
	s_barrier
	v_mfma_f32_16x16x32_bf16 v[54:57], v[202:205], v[166:169], v[54:57]
	v_mfma_f32_16x16x32_bf16 v[50:53], v[210:213], v[166:169], v[50:53]
	v_mfma_f32_16x16x32_bf16 v[38:41], v[202:205], v[174:177], v[38:41]
	v_mfma_f32_16x16x32_bf16 v[34:37], v[210:213], v[174:177], v[34:37]
	v_mfma_f32_16x16x32_bf16 v[22:25], v[202:205], v[186:189], v[22:25]
	v_mfma_f32_16x16x32_bf16 v[18:21], v[210:213], v[186:189], v[18:21]
	v_mfma_f32_16x16x32_bf16 v[6:9], v[202:205], v[194:197], v[6:9]
	v_mfma_f32_16x16x32_bf16 v[2:5], v[210:213], v[194:197], v[2:5]
	v_mfma_f32_16x16x32_bf16 v[54:57], v[206:209], v[170:173], v[54:57]
	v_mfma_f32_16x16x32_bf16 v[50:53], v[214:217], v[170:173], v[50:53]
	v_mfma_f32_16x16x32_bf16 v[38:41], v[206:209], v[182:185], v[38:41]
	v_mfma_f32_16x16x32_bf16 v[34:37], v[214:217], v[182:185], v[34:37]
	v_mfma_f32_16x16x32_bf16 v[22:25], v[206:209], v[190:193], v[22:25]
	v_mfma_f32_16x16x32_bf16 v[18:21], v[214:217], v[190:193], v[18:21]
	v_mfma_f32_16x16x32_bf16 v[6:9], v[206:209], v[198:201], v[6:9]
	v_mfma_f32_16x16x32_bf16 v[2:5], v[214:217], v[198:201], v[2:5]
	s_add_i32 s46, 0, 0x18000
	v_add_u32_e32 v0, s46, v147
	s_barrier
	ds_read_b128 v[150:153], v0
	ds_read_b128 v[154:157], v0 offset:1024
	ds_read_b128 v[158:161], v0 offset:2048
	ds_read_b128 v[162:165], v0 offset:3072
	s_add_u32 s18, s18, 0xb0000
	s_addc_u32 s19, s19, 0
	s_mov_b32 m0, s31
	v_lshl_add_u64 v[202:203], s[18:19], 0, v[130:131]
	ds_read_b128 v[166:169], v148 offset:32768
	ds_read_b128 v[170:173], v148 offset:33792
	ds_read_b128 v[174:177], v148 offset:34816
	ds_read_b128 v[182:185], v148 offset:35840
	ds_read_b128 v[186:189], v148 offset:36864
	ds_read_b128 v[190:193], v148 offset:37888
	ds_read_b128 v[194:197], v148 offset:38912
	ds_read_b128 v[198:201], v148 offset:39936
	global_load_lds_dwordx4 v[202:203], off
	v_lshl_add_u64 v[202:203], s[18:19], 0, v[132:133]
	s_mov_b32 m0, s33
	s_nop 0
	global_load_lds_dwordx4 v[202:203], off
	s_waitcnt lgkmcnt(8)
	s_barrier
	s_waitcnt lgkmcnt(0)
	s_waitcnt lgkmcnt(0)
	v_mfma_f32_16x16x32_bf16 v[126:129], v[150:153], v[166:169], v[126:129]
	v_mfma_f32_16x16x32_bf16 v[122:125], v[158:161], v[166:169], v[122:125]
	v_mfma_f32_16x16x32_bf16 v[110:113], v[150:153], v[174:177], v[110:113]
	v_mfma_f32_16x16x32_bf16 v[106:109], v[158:161], v[174:177], v[106:109]
	v_mfma_f32_16x16x32_bf16 v[94:97], v[150:153], v[186:189], v[94:97]
	v_mfma_f32_16x16x32_bf16 v[90:93], v[158:161], v[186:189], v[90:93]
	v_mfma_f32_16x16x32_bf16 v[78:81], v[150:153], v[194:197], v[78:81]
	v_mfma_f32_16x16x32_bf16 v[74:77], v[158:161], v[194:197], v[74:77]
	v_mfma_f32_16x16x32_bf16 v[126:129], v[154:157], v[170:173], v[126:129]
	v_mfma_f32_16x16x32_bf16 v[122:125], v[162:165], v[170:173], v[122:125]
	v_mfma_f32_16x16x32_bf16 v[110:113], v[154:157], v[182:185], v[110:113]
	v_mfma_f32_16x16x32_bf16 v[106:109], v[162:165], v[182:185], v[106:109]
	v_mfma_f32_16x16x32_bf16 v[94:97], v[154:157], v[190:193], v[94:97]
	v_mfma_f32_16x16x32_bf16 v[90:93], v[162:165], v[190:193], v[90:93]
	v_mfma_f32_16x16x32_bf16 v[78:81], v[154:157], v[198:201], v[78:81]
	v_mfma_f32_16x16x32_bf16 v[74:77], v[162:165], v[198:201], v[74:77]
	s_barrier
	s_add_i32 s18, 0, 0x1c000
	s_add_i32 s19, s46, s28
	v_add_u32_e32 v0, s18, v147
	v_lshl_add_u64 v[218:219], v[218:219], 0, s[10:11]
	s_mov_b32 m0, s19
	ds_read_b128 v[202:205], v0
	ds_read_b128 v[206:209], v0 offset:1024
	ds_read_b128 v[210:213], v0 offset:2048
	ds_read_b128 v[214:217], v0 offset:3072
	global_load_lds_dwordx4 v[218:219], off
	v_lshl_add_u64 v[218:219], v[220:221], 0, s[10:11]
	s_add_i32 m0, s19, 0x2000
	s_nop 0
	global_load_lds_dwordx4 v[218:219], off
	s_barrier
	s_waitcnt lgkmcnt(0)
	s_waitcnt lgkmcnt(0)
	v_mfma_f32_16x16x32_bf16 v[118:121], v[202:205], v[166:169], v[118:121]
	v_mfma_f32_16x16x32_bf16 v[114:117], v[210:213], v[166:169], v[114:117]
	v_mfma_f32_16x16x32_bf16 v[102:105], v[202:205], v[174:177], v[102:105]
	v_mfma_f32_16x16x32_bf16 v[98:101], v[210:213], v[174:177], v[98:101]
	v_mfma_f32_16x16x32_bf16 v[86:89], v[202:205], v[186:189], v[86:89]
	v_mfma_f32_16x16x32_bf16 v[82:85], v[210:213], v[186:189], v[82:85]
	v_mfma_f32_16x16x32_bf16 v[70:73], v[202:205], v[194:197], v[70:73]
	v_mfma_f32_16x16x32_bf16 v[66:69], v[210:213], v[194:197], v[66:69]
	v_mfma_f32_16x16x32_bf16 v[118:121], v[206:209], v[170:173], v[118:121]
	v_mfma_f32_16x16x32_bf16 v[114:117], v[214:217], v[170:173], v[114:117]
	v_mfma_f32_16x16x32_bf16 v[102:105], v[206:209], v[182:185], v[102:105]
	v_mfma_f32_16x16x32_bf16 v[98:101], v[214:217], v[182:185], v[98:101]
	v_mfma_f32_16x16x32_bf16 v[86:89], v[206:209], v[190:193], v[86:89]
	v_mfma_f32_16x16x32_bf16 v[82:85], v[214:217], v[190:193], v[82:85]
	v_mfma_f32_16x16x32_bf16 v[70:73], v[206:209], v[198:201], v[70:73]
	v_mfma_f32_16x16x32_bf16 v[66:69], v[214:217], v[198:201], v[66:69]
	s_mov_b32 m0, s36
	v_lshl_add_u64 v[218:219], v[222:223], 0, s[10:11]
	s_barrier
	ds_read_b128 v[166:169], v148 offset:49152
	ds_read_b128 v[170:173], v148 offset:50176
	ds_read_b128 v[174:177], v148 offset:51200
	ds_read_b128 v[182:185], v148 offset:52224
	ds_read_b128 v[186:189], v148 offset:53248
	ds_read_b128 v[190:193], v148 offset:54272
	ds_read_b128 v[194:197], v148 offset:55296
	ds_read_b128 v[198:201], v148 offset:56320
	global_load_lds_dwordx4 v[218:219], off
	v_lshl_add_u64 v[218:219], v[224:225], 0, s[10:11]
	s_mov_b32 m0, s37
	s_nop 0
	global_load_lds_dwordx4 v[218:219], off
	s_barrier
	s_waitcnt lgkmcnt(0)
	s_waitcnt lgkmcnt(0)
	v_mfma_f32_16x16x32_bf16 v[62:65], v[150:153], v[166:169], v[62:65]
	v_mfma_f32_16x16x32_bf16 v[58:61], v[158:161], v[166:169], v[58:61]
	v_mfma_f32_16x16x32_bf16 v[46:49], v[150:153], v[174:177], v[46:49]
	v_mfma_f32_16x16x32_bf16 v[42:45], v[158:161], v[174:177], v[42:45]
	v_mfma_f32_16x16x32_bf16 v[30:33], v[150:153], v[186:189], v[30:33]
	v_mfma_f32_16x16x32_bf16 v[26:29], v[158:161], v[186:189], v[26:29]
	v_mfma_f32_16x16x32_bf16 v[14:17], v[150:153], v[194:197], v[14:17]
	v_mfma_f32_16x16x32_bf16 v[10:13], v[158:161], v[194:197], v[10:13]
	v_mfma_f32_16x16x32_bf16 v[62:65], v[154:157], v[170:173], v[62:65]
	v_mfma_f32_16x16x32_bf16 v[58:61], v[162:165], v[170:173], v[58:61]
	v_mfma_f32_16x16x32_bf16 v[46:49], v[154:157], v[182:185], v[46:49]
	v_mfma_f32_16x16x32_bf16 v[42:45], v[162:165], v[182:185], v[42:45]
	v_mfma_f32_16x16x32_bf16 v[30:33], v[154:157], v[190:193], v[30:33]
	v_mfma_f32_16x16x32_bf16 v[26:29], v[162:165], v[190:193], v[26:29]
	v_mfma_f32_16x16x32_bf16 v[14:17], v[154:157], v[198:201], v[14:17]
	v_mfma_f32_16x16x32_bf16 v[10:13], v[162:165], v[198:201], v[10:13]
	s_barrier
	s_add_u32 s16, s16, 0xb0080
	s_addc_u32 s17, s17, 0
	s_add_i32 s18, s18, s28
	v_lshl_add_u64 v[150:151], s[16:17], 0, v[130:131]
	s_mov_b32 m0, s18
	s_nop 0
	global_load_lds_dwordx4 v[150:151], off
	v_lshl_add_u64 v[150:151], s[16:17], 0, v[132:133]
	s_add_i32 m0, s18, 0x2000
	s_nop 0
	global_load_lds_dwordx4 v[150:151], off
	s_waitcnt vmcnt(6)
	s_barrier
	v_mfma_f32_16x16x32_bf16 v[54:57], v[202:205], v[166:169], v[54:57]
	v_mfma_f32_16x16x32_bf16 v[50:53], v[210:213], v[166:169], v[50:53]
	v_mfma_f32_16x16x32_bf16 v[38:41], v[202:205], v[174:177], v[38:41]
	v_mfma_f32_16x16x32_bf16 v[34:37], v[210:213], v[174:177], v[34:37]
	v_mfma_f32_16x16x32_bf16 v[22:25], v[202:205], v[186:189], v[22:25]
	v_mfma_f32_16x16x32_bf16 v[18:21], v[210:213], v[186:189], v[18:21]
	v_mfma_f32_16x16x32_bf16 v[6:9], v[202:205], v[194:197], v[6:9]
	v_mfma_f32_16x16x32_bf16 v[2:5], v[210:213], v[194:197], v[2:5]
	v_mfma_f32_16x16x32_bf16 v[54:57], v[206:209], v[170:173], v[54:57]
	v_mfma_f32_16x16x32_bf16 v[50:53], v[214:217], v[170:173], v[50:53]
	v_mfma_f32_16x16x32_bf16 v[38:41], v[206:209], v[182:185], v[38:41]
	v_mfma_f32_16x16x32_bf16 v[34:37], v[214:217], v[182:185], v[34:37]
	v_mfma_f32_16x16x32_bf16 v[22:25], v[206:209], v[190:193], v[22:25]
	v_mfma_f32_16x16x32_bf16 v[18:21], v[214:217], v[190:193], v[18:21]
	v_mfma_f32_16x16x32_bf16 v[6:9], v[206:209], v[198:201], v[6:9]
	v_mfma_f32_16x16x32_bf16 v[2:5], v[214:217], v[198:201], v[2:5]
	s_add_i32 s45, s45, 2
	s_add_u32 s14, s14, 0x100
	s_addc_u32 s15, s15, 0
	s_cmp_gt_u32 s45, 41
	s_barrier
	s_cbranch_scc0 .LBB0_5227
	s_add_u32 s14, s43, 0xffffff00
	s_addc_u32 s15, s44, -1
	s_and_b64 vcc, exec, s[4:5]
	s_cbranch_vccnz .LBB0_5214
	v_mov_b32_e32 v2, 0
	s_mov_b32 s6, s40
	s_mov_b32 s24, s41
	s_mov_b64 s[8:9], s[12:13]
	s_mov_b32 s35, s42
	v_mov_b32_e32 v3, v2
	v_mov_b32_e32 v4, v2
	v_mov_b32_e32 v5, v2
	v_mov_b32_e32 v6, v2
	v_mov_b32_e32 v7, v2
	v_mov_b32_e32 v8, v2
	v_mov_b32_e32 v9, v2
	v_mov_b32_e32 v18, v2
	v_mov_b32_e32 v19, v2
	v_mov_b32_e32 v20, v2
	v_mov_b32_e32 v21, v2
	v_mov_b32_e32 v22, v2
	v_mov_b32_e32 v23, v2
	v_mov_b32_e32 v24, v2
	v_mov_b32_e32 v25, v2
	v_mov_b32_e32 v34, v2
	v_mov_b32_e32 v35, v2
	v_mov_b32_e32 v36, v2
	v_mov_b32_e32 v37, v2
	v_mov_b32_e32 v38, v2
	v_mov_b32_e32 v39, v2
	v_mov_b32_e32 v40, v2
	v_mov_b32_e32 v41, v2
	v_mov_b32_e32 v50, v2
	v_mov_b32_e32 v51, v2
	v_mov_b32_e32 v52, v2
	v_mov_b32_e32 v53, v2
	v_mov_b32_e32 v54, v2
	v_mov_b32_e32 v55, v2
	v_mov_b32_e32 v56, v2
	v_mov_b32_e32 v57, v2
	v_mov_b32_e32 v10, v2
	v_mov_b32_e32 v11, v2
	v_mov_b32_e32 v12, v2
	v_mov_b32_e32 v13, v2
	v_mov_b32_e32 v14, v2
	v_mov_b32_e32 v15, v2
	v_mov_b32_e32 v16, v2
	v_mov_b32_e32 v17, v2
	v_mov_b32_e32 v26, v2
	v_mov_b32_e32 v27, v2
	v_mov_b32_e32 v28, v2
	v_mov_b32_e32 v29, v2
	v_mov_b32_e32 v30, v2
	v_mov_b32_e32 v31, v2
	v_mov_b32_e32 v32, v2
	v_mov_b32_e32 v33, v2
	v_mov_b32_e32 v42, v2
	v_mov_b32_e32 v43, v2
	v_mov_b32_e32 v44, v2
	v_mov_b32_e32 v45, v2
	v_mov_b32_e32 v46, v2
	v_mov_b32_e32 v47, v2
	v_mov_b32_e32 v48, v2
	v_mov_b32_e32 v49, v2
	v_mov_b32_e32 v58, v2
	v_mov_b32_e32 v59, v2
	v_mov_b32_e32 v60, v2
	v_mov_b32_e32 v61, v2
	v_mov_b32_e32 v62, v2
	v_mov_b32_e32 v63, v2
	v_mov_b32_e32 v64, v2
	v_mov_b32_e32 v65, v2
	v_mov_b32_e32 v66, v2
	v_mov_b32_e32 v67, v2
	v_mov_b32_e32 v68, v2
	v_mov_b32_e32 v69, v2
	v_mov_b32_e32 v70, v2
	v_mov_b32_e32 v71, v2
	v_mov_b32_e32 v72, v2
	v_mov_b32_e32 v73, v2
	v_mov_b32_e32 v82, v2
	v_mov_b32_e32 v83, v2
	v_mov_b32_e32 v84, v2
	v_mov_b32_e32 v85, v2
	v_mov_b32_e32 v86, v2
	v_mov_b32_e32 v87, v2
	v_mov_b32_e32 v88, v2
	v_mov_b32_e32 v89, v2
	v_mov_b32_e32 v98, v2
	v_mov_b32_e32 v99, v2
	v_mov_b32_e32 v100, v2
	v_mov_b32_e32 v101, v2
	v_mov_b32_e32 v102, v2
	v_mov_b32_e32 v103, v2
	v_mov_b32_e32 v104, v2
	v_mov_b32_e32 v105, v2
	v_mov_b32_e32 v114, v2
	v_mov_b32_e32 v115, v2
	v_mov_b32_e32 v116, v2
	v_mov_b32_e32 v117, v2
	v_mov_b32_e32 v118, v2
	v_mov_b32_e32 v119, v2
	v_mov_b32_e32 v120, v2
	v_mov_b32_e32 v121, v2
	v_mov_b32_e32 v74, v2
	v_mov_b32_e32 v75, v2
	v_mov_b32_e32 v76, v2
	v_mov_b32_e32 v77, v2
	v_mov_b32_e32 v78, v2
	v_mov_b32_e32 v79, v2
	v_mov_b32_e32 v80, v2
	v_mov_b32_e32 v81, v2
	v_mov_b32_e32 v90, v2
	v_mov_b32_e32 v91, v2
	v_mov_b32_e32 v92, v2
	v_mov_b32_e32 v93, v2
	v_mov_b32_e32 v94, v2
	v_mov_b32_e32 v95, v2
	v_mov_b32_e32 v96, v2
	v_mov_b32_e32 v97, v2
	v_mov_b32_e32 v106, v2
	v_mov_b32_e32 v107, v2
	v_mov_b32_e32 v108, v2
	v_mov_b32_e32 v109, v2
	v_mov_b32_e32 v110, v2
	v_mov_b32_e32 v111, v2
	v_mov_b32_e32 v112, v2
	v_mov_b32_e32 v113, v2
	v_mov_b32_e32 v122, v2
	v_mov_b32_e32 v123, v2
	v_mov_b32_e32 v124, v2
	v_mov_b32_e32 v125, v2
	v_mov_b32_e32 v126, v2
	v_mov_b32_e32 v127, v2
	v_mov_b32_e32 v128, v2
	v_mov_b32_e32 v129, v2
	s_andn2_b64 vcc, exec, s[0:1]
	s_cbranch_vccnz .LBB0_5215
